# P0 p0_mod GEMV k-loop de-serialised: 64 weight-row loads in flight per wave instead of 4, LDS reads double-buffered, same accumulation order; on top of the guarded final
# speedup vs baseline: 1.0072x; 1.0041x over previous
; __device__ __forceinline__ void p0_mod(const Args& a, LAS unsigned char* lds, int bid, int G, int tid) {
;     ...
;         float acc[16];
; #pragma unroll
;         for (int r = 0; r < 16; ++r) acc[r] = 0.f;
;         const float* wp = a.in[I_ADAW] + cb * 64 + lane;
; #pragma unroll 4
;         for (int k = wave * 128; k < wave * 128 + 128; ++k) {
;             const float wv = wp[(size_t)k * 6144];
.LBB0_14:
	s_or_b64 exec, exec, s[22:23]
	s_ashr_i32 s5, s4, 31
	v_mov_b32_e32 v14, 0
	v_lshl_add_u64 v[12:13], s[4:5], 2, v[8:9]
	s_mov_b64 s[22:23], 0
	v_mov_b32_e32 v10, v3
	v_mov_b32_e32 v15, v14
	v_mov_b32_e32 v16, v14
	v_mov_b32_e32 v17, v14
	v_mov_b32_e32 v18, v14
	v_mov_b32_e32 v19, v14
	v_mov_b32_e32 v20, v14
	v_mov_b32_e32 v21, v14
	v_mov_b32_e32 v22, v14
	v_mov_b32_e32 v23, v14
	v_mov_b32_e32 v24, v14
	v_mov_b32_e32 v25, v14
	v_mov_b32_e32 v26, v14
	v_mov_b32_e32 v27, v14
	v_mov_b32_e32 v28, v14
	v_mov_b32_e32 v29, v14
	s_waitcnt lgkmcnt(0)
	s_barrier
	s_mov_b64 s[60:61], 0x6000
	v_mov_b64_e32 v[230:231], v[12:13]
	global_load_dword v102, v[230:231], off
	v_lshl_add_u64 v[230:231], v[230:231], 0, s[60:61]
	global_load_dword v103, v[230:231], off
	v_lshl_add_u64 v[230:231], v[230:231], 0, s[60:61]
	global_load_dword v104, v[230:231], off
	v_lshl_add_u64 v[230:231], v[230:231], 0, s[60:61]
	global_load_dword v105, v[230:231], off
	v_lshl_add_u64 v[230:231], v[230:231], 0, s[60:61]
	global_load_dword v106, v[230:231], off
	v_lshl_add_u64 v[230:231], v[230:231], 0, s[60:61]
	global_load_dword v107, v[230:231], off
	v_lshl_add_u64 v[230:231], v[230:231], 0, s[60:61]
	global_load_dword v108, v[230:231], off
	v_lshl_add_u64 v[230:231], v[230:231], 0, s[60:61]
	global_load_dword v109, v[230:231], off
	v_lshl_add_u64 v[230:231], v[230:231], 0, s[60:61]
	global_load_dword v110, v[230:231], off
	v_lshl_add_u64 v[230:231], v[230:231], 0, s[60:61]
	global_load_dword v111, v[230:231], off
	v_lshl_add_u64 v[230:231], v[230:231], 0, s[60:61]
	global_load_dword v112, v[230:231], off
	v_lshl_add_u64 v[230:231], v[230:231], 0, s[60:61]
	global_load_dword v113, v[230:231], off
	v_lshl_add_u64 v[230:231], v[230:231], 0, s[60:61]
	global_load_dword v114, v[230:231], off
	v_lshl_add_u64 v[230:231], v[230:231], 0, s[60:61]
	global_load_dword v115, v[230:231], off
	v_lshl_add_u64 v[230:231], v[230:231], 0, s[60:61]
	global_load_dword v116, v[230:231], off
	v_lshl_add_u64 v[230:231], v[230:231], 0, s[60:61]
	global_load_dword v117, v[230:231], off
	v_lshl_add_u64 v[230:231], v[230:231], 0, s[60:61]
	global_load_dword v118, v[230:231], off
	v_lshl_add_u64 v[230:231], v[230:231], 0, s[60:61]
	global_load_dword v119, v[230:231], off
	v_lshl_add_u64 v[230:231], v[230:231], 0, s[60:61]
	global_load_dword v120, v[230:231], off
	v_lshl_add_u64 v[230:231], v[230:231], 0, s[60:61]
	global_load_dword v121, v[230:231], off
	v_lshl_add_u64 v[230:231], v[230:231], 0, s[60:61]
	global_load_dword v122, v[230:231], off
	v_lshl_add_u64 v[230:231], v[230:231], 0, s[60:61]
	global_load_dword v123, v[230:231], off
	v_lshl_add_u64 v[230:231], v[230:231], 0, s[60:61]
	global_load_dword v124, v[230:231], off
	v_lshl_add_u64 v[230:231], v[230:231], 0, s[60:61]
	global_load_dword v125, v[230:231], off
	v_lshl_add_u64 v[230:231], v[230:231], 0, s[60:61]
	global_load_dword v126, v[230:231], off
	v_lshl_add_u64 v[230:231], v[230:231], 0, s[60:61]
	global_load_dword v127, v[230:231], off
	v_lshl_add_u64 v[230:231], v[230:231], 0, s[60:61]
	global_load_dword v128, v[230:231], off
	v_lshl_add_u64 v[230:231], v[230:231], 0, s[60:61]
	global_load_dword v129, v[230:231], off
	v_lshl_add_u64 v[230:231], v[230:231], 0, s[60:61]
	global_load_dword v130, v[230:231], off
	v_lshl_add_u64 v[230:231], v[230:231], 0, s[60:61]
	global_load_dword v131, v[230:231], off
	v_lshl_add_u64 v[230:231], v[230:231], 0, s[60:61]
	global_load_dword v132, v[230:231], off
	v_lshl_add_u64 v[230:231], v[230:231], 0, s[60:61]
	global_load_dword v133, v[230:231], off
	v_lshl_add_u64 v[230:231], v[230:231], 0, s[60:61]
	global_load_dword v134, v[230:231], off
	v_lshl_add_u64 v[230:231], v[230:231], 0, s[60:61]
	global_load_dword v135, v[230:231], off
	v_lshl_add_u64 v[230:231], v[230:231], 0, s[60:61]
	global_load_dword v136, v[230:231], off
	v_lshl_add_u64 v[230:231], v[230:231], 0, s[60:61]
	global_load_dword v137, v[230:231], off
	v_lshl_add_u64 v[230:231], v[230:231], 0, s[60:61]
	global_load_dword v138, v[230:231], off
	v_lshl_add_u64 v[230:231], v[230:231], 0, s[60:61]
	global_load_dword v139, v[230:231], off
	v_lshl_add_u64 v[230:231], v[230:231], 0, s[60:61]
	global_load_dword v140, v[230:231], off
	v_lshl_add_u64 v[230:231], v[230:231], 0, s[60:61]
	global_load_dword v141, v[230:231], off
	v_lshl_add_u64 v[230:231], v[230:231], 0, s[60:61]
	global_load_dword v142, v[230:231], off
	v_lshl_add_u64 v[230:231], v[230:231], 0, s[60:61]
	global_load_dword v143, v[230:231], off
	v_lshl_add_u64 v[230:231], v[230:231], 0, s[60:61]
	global_load_dword v144, v[230:231], off
	v_lshl_add_u64 v[230:231], v[230:231], 0, s[60:61]
	global_load_dword v145, v[230:231], off
	v_lshl_add_u64 v[230:231], v[230:231], 0, s[60:61]
	global_load_dword v146, v[230:231], off
	v_lshl_add_u64 v[230:231], v[230:231], 0, s[60:61]
	global_load_dword v147, v[230:231], off
	v_lshl_add_u64 v[230:231], v[230:231], 0, s[60:61]
	global_load_dword v148, v[230:231], off
	v_lshl_add_u64 v[230:231], v[230:231], 0, s[60:61]
	global_load_dword v149, v[230:231], off
	v_lshl_add_u64 v[230:231], v[230:231], 0, s[60:61]
	global_load_dword v150, v[230:231], off
	v_lshl_add_u64 v[230:231], v[230:231], 0, s[60:61]
	global_load_dword v151, v[230:231], off
	v_lshl_add_u64 v[230:231], v[230:231], 0, s[60:61]
	global_load_dword v152, v[230:231], off
	v_lshl_add_u64 v[230:231], v[230:231], 0, s[60:61]
	global_load_dword v153, v[230:231], off
	v_lshl_add_u64 v[230:231], v[230:231], 0, s[60:61]
	global_load_dword v154, v[230:231], off
	v_lshl_add_u64 v[230:231], v[230:231], 0, s[60:61]
	global_load_dword v155, v[230:231], off
	v_lshl_add_u64 v[230:231], v[230:231], 0, s[60:61]
; #define LAS __attribute__((address_space(3)))
; __device__ __forceinline__ void p0_mod(const Args& a, LAS unsigned char* lds, int bid, int G, int tid) {
;     ...
;         for (int k = wave * 128; k < wave * 128 + 128; ++k) {
;             const float wv = wp[(size_t)k * 6144];
; #pragma unroll
;             for (int r4 = 0; r4 < 4; ++r4) { const f32x4 s = *(const LAS f32x4*)(S + k * 16 + r4 * 4);
;                 acc[r4 * 4 + 0] += s.x * wv; acc[r4 * 4 + 1] += s.y * wv; acc[r4 * 4 + 2] += s.z * wv; acc[r4 * 4 + 3] += s.w * wv; }
;         }
	global_load_dword v156, v[230:231], off
	v_lshl_add_u64 v[230:231], v[230:231], 0, s[60:61]
	global_load_dword v157, v[230:231], off
	v_lshl_add_u64 v[230:231], v[230:231], 0, s[60:61]
	global_load_dword v158, v[230:231], off
	v_lshl_add_u64 v[230:231], v[230:231], 0, s[60:61]
	global_load_dword v159, v[230:231], off
	v_lshl_add_u64 v[230:231], v[230:231], 0, s[60:61]
	global_load_dword v160, v[230:231], off
	v_lshl_add_u64 v[230:231], v[230:231], 0, s[60:61]
	global_load_dword v161, v[230:231], off
	v_lshl_add_u64 v[230:231], v[230:231], 0, s[60:61]
	global_load_dword v162, v[230:231], off
	v_lshl_add_u64 v[230:231], v[230:231], 0, s[60:61]
	global_load_dword v163, v[230:231], off
	v_lshl_add_u64 v[230:231], v[230:231], 0, s[60:61]
	global_load_dword v164, v[230:231], off
	v_lshl_add_u64 v[230:231], v[230:231], 0, s[60:61]
	global_load_dword v165, v[230:231], off
	v_lshl_add_u64 v[230:231], v[230:231], 0, s[60:61]
	ds_read_b128 v[166:169], v10 offset:0
	ds_read_b128 v[170:173], v10 offset:16
	ds_read_b128 v[174:177], v10 offset:32
	ds_read_b128 v[178:181], v10 offset:48
	ds_read_b128 v[182:185], v10 offset:64
	ds_read_b128 v[186:189], v10 offset:80
	ds_read_b128 v[190:193], v10 offset:96
	ds_read_b128 v[194:197], v10 offset:112
	ds_read_b128 v[198:201], v10 offset:128
	ds_read_b128 v[202:205], v10 offset:144
	ds_read_b128 v[206:209], v10 offset:160
	ds_read_b128 v[210:213], v10 offset:176
	ds_read_b128 v[214:217], v10 offset:192
	ds_read_b128 v[218:221], v10 offset:208
	ds_read_b128 v[222:225], v10 offset:224
	ds_read_b128 v[226:229], v10 offset:240
	s_waitcnt vmcnt(63) lgkmcnt(8)
	v_pk_fma_f32 v[16:17], v[102:103], v[166:167], v[16:17] op_sel_hi:[0,1,1]
	v_pk_fma_f32 v[18:19], v[102:103], v[168:169], v[18:19] op_sel_hi:[0,1,1]
	v_pk_fma_f32 v[20:21], v[102:103], v[170:171], v[20:21] op_sel_hi:[0,1,1]
	v_pk_fma_f32 v[22:23], v[102:103], v[172:173], v[22:23] op_sel_hi:[0,1,1]
	v_pk_fma_f32 v[24:25], v[102:103], v[174:175], v[24:25] op_sel_hi:[0,1,1]
	v_pk_fma_f32 v[26:27], v[102:103], v[176:177], v[26:27] op_sel_hi:[0,1,1]
	v_pk_fma_f32 v[28:29], v[102:103], v[178:179], v[28:29] op_sel_hi:[0,1,1]
	v_pk_fma_f32 v[14:15], v[102:103], v[180:181], v[14:15] op_sel_hi:[0,1,1]
	global_load_dword v102, v[230:231], off
	v_lshl_add_u64 v[230:231], v[230:231], 0, s[60:61]
	s_waitcnt vmcnt(63)
	v_pk_fma_f32 v[16:17], v[102:103], v[182:183], v[16:17] op_sel:[1,0,0] op_sel_hi:[1,1,1]
	v_pk_fma_f32 v[18:19], v[102:103], v[184:185], v[18:19] op_sel:[1,0,0] op_sel_hi:[1,1,1]
	v_pk_fma_f32 v[20:21], v[102:103], v[186:187], v[20:21] op_sel:[1,0,0] op_sel_hi:[1,1,1]
	v_pk_fma_f32 v[22:23], v[102:103], v[188:189], v[22:23] op_sel:[1,0,0] op_sel_hi:[1,1,1]
	v_pk_fma_f32 v[24:25], v[102:103], v[190:191], v[24:25] op_sel:[1,0,0] op_sel_hi:[1,1,1]
	v_pk_fma_f32 v[26:27], v[102:103], v[192:193], v[26:27] op_sel:[1,0,0] op_sel_hi:[1,1,1]
	v_pk_fma_f32 v[28:29], v[102:103], v[194:195], v[28:29] op_sel:[1,0,0] op_sel_hi:[1,1,1]
	v_pk_fma_f32 v[14:15], v[102:103], v[196:197], v[14:15] op_sel:[1,0,0] op_sel_hi:[1,1,1]
	global_load_dword v103, v[230:231], off
	v_lshl_add_u64 v[230:231], v[230:231], 0, s[60:61]
	ds_read_b128 v[166:169], v10 offset:256
	ds_read_b128 v[170:173], v10 offset:272
	ds_read_b128 v[174:177], v10 offset:288
	ds_read_b128 v[178:181], v10 offset:304
	ds_read_b128 v[182:185], v10 offset:320
	ds_read_b128 v[186:189], v10 offset:336
	ds_read_b128 v[190:193], v10 offset:352
	ds_read_b128 v[194:197], v10 offset:368
	s_waitcnt vmcnt(63) lgkmcnt(8)
	v_pk_fma_f32 v[16:17], v[104:105], v[198:199], v[16:17] op_sel_hi:[0,1,1]
	v_pk_fma_f32 v[18:19], v[104:105], v[200:201], v[18:19] op_sel_hi:[0,1,1]
	v_pk_fma_f32 v[20:21], v[104:105], v[202:203], v[20:21] op_sel_hi:[0,1,1]
	v_pk_fma_f32 v[22:23], v[104:105], v[204:205], v[22:23] op_sel_hi:[0,1,1]
	v_pk_fma_f32 v[24:25], v[104:105], v[206:207], v[24:25] op_sel_hi:[0,1,1]
	v_pk_fma_f32 v[26:27], v[104:105], v[208:209], v[26:27] op_sel_hi:[0,1,1]
	v_pk_fma_f32 v[28:29], v[104:105], v[210:211], v[28:29] op_sel_hi:[0,1,1]
	v_pk_fma_f32 v[14:15], v[104:105], v[212:213], v[14:15] op_sel_hi:[0,1,1]
	global_load_dword v104, v[230:231], off
	v_lshl_add_u64 v[230:231], v[230:231], 0, s[60:61]
	s_waitcnt vmcnt(63)
	v_pk_fma_f32 v[16:17], v[104:105], v[214:215], v[16:17] op_sel:[1,0,0] op_sel_hi:[1,1,1]
	v_pk_fma_f32 v[18:19], v[104:105], v[216:217], v[18:19] op_sel:[1,0,0] op_sel_hi:[1,1,1]
	v_pk_fma_f32 v[20:21], v[104:105], v[218:219], v[20:21] op_sel:[1,0,0] op_sel_hi:[1,1,1]
	v_pk_fma_f32 v[22:23], v[104:105], v[220:221], v[22:23] op_sel:[1,0,0] op_sel_hi:[1,1,1]
	v_pk_fma_f32 v[24:25], v[104:105], v[222:223], v[24:25] op_sel:[1,0,0] op_sel_hi:[1,1,1]
	v_pk_fma_f32 v[26:27], v[104:105], v[224:225], v[26:27] op_sel:[1,0,0] op_sel_hi:[1,1,1]
	v_pk_fma_f32 v[28:29], v[104:105], v[226:227], v[28:29] op_sel:[1,0,0] op_sel_hi:[1,1,1]
	v_pk_fma_f32 v[14:15], v[104:105], v[228:229], v[14:15] op_sel:[1,0,0] op_sel_hi:[1,1,1]
	global_load_dword v105, v[230:231], off
	v_lshl_add_u64 v[230:231], v[230:231], 0, s[60:61]
	ds_read_b128 v[198:201], v10 offset:384
	ds_read_b128 v[202:205], v10 offset:400
	ds_read_b128 v[206:209], v10 offset:416
	ds_read_b128 v[210:213], v10 offset:432
	ds_read_b128 v[214:217], v10 offset:448
	ds_read_b128 v[218:221], v10 offset:464
	ds_read_b128 v[222:225], v10 offset:480
	ds_read_b128 v[226:229], v10 offset:496
	s_waitcnt vmcnt(63) lgkmcnt(8)
; #define LAS __attribute__((address_space(3)))
; __device__ __forceinline__ void p0_mod(const Args& a, LAS unsigned char* lds, int bid, int G, int tid) {
;     ...
;         for (int k = wave * 128; k < wave * 128 + 128; ++k) {
;             const float wv = wp[(size_t)k * 6144];
; #pragma unroll
;             for (int r4 = 0; r4 < 4; ++r4) { const f32x4 s = *(const LAS f32x4*)(S + k * 16 + r4 * 4);
;                 acc[r4 * 4 + 0] += s.x * wv; acc[r4 * 4 + 1] += s.y * wv; acc[r4 * 4 + 2] += s.z * wv; acc[r4 * 4 + 3] += s.w * wv; }
;         }
	v_pk_fma_f32 v[16:17], v[106:107], v[166:167], v[16:17] op_sel_hi:[0,1,1]
	v_pk_fma_f32 v[18:19], v[106:107], v[168:169], v[18:19] op_sel_hi:[0,1,1]
	v_pk_fma_f32 v[20:21], v[106:107], v[170:171], v[20:21] op_sel_hi:[0,1,1]
	v_pk_fma_f32 v[22:23], v[106:107], v[172:173], v[22:23] op_sel_hi:[0,1,1]
	v_pk_fma_f32 v[24:25], v[106:107], v[174:175], v[24:25] op_sel_hi:[0,1,1]
	v_pk_fma_f32 v[26:27], v[106:107], v[176:177], v[26:27] op_sel_hi:[0,1,1]
	v_pk_fma_f32 v[28:29], v[106:107], v[178:179], v[28:29] op_sel_hi:[0,1,1]
	v_pk_fma_f32 v[14:15], v[106:107], v[180:181], v[14:15] op_sel_hi:[0,1,1]
	global_load_dword v106, v[230:231], off
	v_lshl_add_u64 v[230:231], v[230:231], 0, s[60:61]
	s_waitcnt vmcnt(63)
	v_pk_fma_f32 v[16:17], v[106:107], v[182:183], v[16:17] op_sel:[1,0,0] op_sel_hi:[1,1,1]
	v_pk_fma_f32 v[18:19], v[106:107], v[184:185], v[18:19] op_sel:[1,0,0] op_sel_hi:[1,1,1]
	v_pk_fma_f32 v[20:21], v[106:107], v[186:187], v[20:21] op_sel:[1,0,0] op_sel_hi:[1,1,1]
	v_pk_fma_f32 v[22:23], v[106:107], v[188:189], v[22:23] op_sel:[1,0,0] op_sel_hi:[1,1,1]
	v_pk_fma_f32 v[24:25], v[106:107], v[190:191], v[24:25] op_sel:[1,0,0] op_sel_hi:[1,1,1]
	v_pk_fma_f32 v[26:27], v[106:107], v[192:193], v[26:27] op_sel:[1,0,0] op_sel_hi:[1,1,1]
	v_pk_fma_f32 v[28:29], v[106:107], v[194:195], v[28:29] op_sel:[1,0,0] op_sel_hi:[1,1,1]
	v_pk_fma_f32 v[14:15], v[106:107], v[196:197], v[14:15] op_sel:[1,0,0] op_sel_hi:[1,1,1]
	global_load_dword v107, v[230:231], off
	v_lshl_add_u64 v[230:231], v[230:231], 0, s[60:61]
	ds_read_b128 v[166:169], v10 offset:512
	ds_read_b128 v[170:173], v10 offset:528
	ds_read_b128 v[174:177], v10 offset:544
	ds_read_b128 v[178:181], v10 offset:560
	ds_read_b128 v[182:185], v10 offset:576
	ds_read_b128 v[186:189], v10 offset:592
	ds_read_b128 v[190:193], v10 offset:608
	ds_read_b128 v[194:197], v10 offset:624
	s_waitcnt vmcnt(63) lgkmcnt(8)
	v_pk_fma_f32 v[16:17], v[108:109], v[198:199], v[16:17] op_sel_hi:[0,1,1]
	v_pk_fma_f32 v[18:19], v[108:109], v[200:201], v[18:19] op_sel_hi:[0,1,1]
	v_pk_fma_f32 v[20:21], v[108:109], v[202:203], v[20:21] op_sel_hi:[0,1,1]
	v_pk_fma_f32 v[22:23], v[108:109], v[204:205], v[22:23] op_sel_hi:[0,1,1]
	v_pk_fma_f32 v[24:25], v[108:109], v[206:207], v[24:25] op_sel_hi:[0,1,1]
	v_pk_fma_f32 v[26:27], v[108:109], v[208:209], v[26:27] op_sel_hi:[0,1,1]
	v_pk_fma_f32 v[28:29], v[108:109], v[210:211], v[28:29] op_sel_hi:[0,1,1]
	v_pk_fma_f32 v[14:15], v[108:109], v[212:213], v[14:15] op_sel_hi:[0,1,1]
	global_load_dword v108, v[230:231], off
	v_lshl_add_u64 v[230:231], v[230:231], 0, s[60:61]
	s_waitcnt vmcnt(63)
	v_pk_fma_f32 v[16:17], v[108:109], v[214:215], v[16:17] op_sel:[1,0,0] op_sel_hi:[1,1,1]
	v_pk_fma_f32 v[18:19], v[108:109], v[216:217], v[18:19] op_sel:[1,0,0] op_sel_hi:[1,1,1]
	v_pk_fma_f32 v[20:21], v[108:109], v[218:219], v[20:21] op_sel:[1,0,0] op_sel_hi:[1,1,1]
	v_pk_fma_f32 v[22:23], v[108:109], v[220:221], v[22:23] op_sel:[1,0,0] op_sel_hi:[1,1,1]
	v_pk_fma_f32 v[24:25], v[108:109], v[222:223], v[24:25] op_sel:[1,0,0] op_sel_hi:[1,1,1]
	v_pk_fma_f32 v[26:27], v[108:109], v[224:225], v[26:27] op_sel:[1,0,0] op_sel_hi:[1,1,1]
	v_pk_fma_f32 v[28:29], v[108:109], v[226:227], v[28:29] op_sel:[1,0,0] op_sel_hi:[1,1,1]
	v_pk_fma_f32 v[14:15], v[108:109], v[228:229], v[14:15] op_sel:[1,0,0] op_sel_hi:[1,1,1]
	global_load_dword v109, v[230:231], off
	v_lshl_add_u64 v[230:231], v[230:231], 0, s[60:61]
	ds_read_b128 v[198:201], v10 offset:640
	ds_read_b128 v[202:205], v10 offset:656
	ds_read_b128 v[206:209], v10 offset:672
	ds_read_b128 v[210:213], v10 offset:688
	ds_read_b128 v[214:217], v10 offset:704
	ds_read_b128 v[218:221], v10 offset:720
	ds_read_b128 v[222:225], v10 offset:736
	ds_read_b128 v[226:229], v10 offset:752
	s_waitcnt vmcnt(63) lgkmcnt(8)
	v_pk_fma_f32 v[16:17], v[110:111], v[166:167], v[16:17] op_sel_hi:[0,1,1]
	v_pk_fma_f32 v[18:19], v[110:111], v[168:169], v[18:19] op_sel_hi:[0,1,1]
	v_pk_fma_f32 v[20:21], v[110:111], v[170:171], v[20:21] op_sel_hi:[0,1,1]
	v_pk_fma_f32 v[22:23], v[110:111], v[172:173], v[22:23] op_sel_hi:[0,1,1]
	v_pk_fma_f32 v[24:25], v[110:111], v[174:175], v[24:25] op_sel_hi:[0,1,1]
	v_pk_fma_f32 v[26:27], v[110:111], v[176:177], v[26:27] op_sel_hi:[0,1,1]
	v_pk_fma_f32 v[28:29], v[110:111], v[178:179], v[28:29] op_sel_hi:[0,1,1]
	v_pk_fma_f32 v[14:15], v[110:111], v[180:181], v[14:15] op_sel_hi:[0,1,1]
	global_load_dword v110, v[230:231], off
	v_lshl_add_u64 v[230:231], v[230:231], 0, s[60:61]
	s_waitcnt vmcnt(63)
	v_pk_fma_f32 v[16:17], v[110:111], v[182:183], v[16:17] op_sel:[1,0,0] op_sel_hi:[1,1,1]
	v_pk_fma_f32 v[18:19], v[110:111], v[184:185], v[18:19] op_sel:[1,0,0] op_sel_hi:[1,1,1]
	v_pk_fma_f32 v[20:21], v[110:111], v[186:187], v[20:21] op_sel:[1,0,0] op_sel_hi:[1,1,1]
	v_pk_fma_f32 v[22:23], v[110:111], v[188:189], v[22:23] op_sel:[1,0,0] op_sel_hi:[1,1,1]
	v_pk_fma_f32 v[24:25], v[110:111], v[190:191], v[24:25] op_sel:[1,0,0] op_sel_hi:[1,1,1]
	v_pk_fma_f32 v[26:27], v[110:111], v[192:193], v[26:27] op_sel:[1,0,0] op_sel_hi:[1,1,1]
	v_pk_fma_f32 v[28:29], v[110:111], v[194:195], v[28:29] op_sel:[1,0,0] op_sel_hi:[1,1,1]
	v_pk_fma_f32 v[14:15], v[110:111], v[196:197], v[14:15] op_sel:[1,0,0] op_sel_hi:[1,1,1]
	global_load_dword v111, v[230:231], off
	v_lshl_add_u64 v[230:231], v[230:231], 0, s[60:61]
	ds_read_b128 v[166:169], v10 offset:768
	ds_read_b128 v[170:173], v10 offset:784
	ds_read_b128 v[174:177], v10 offset:800
	ds_read_b128 v[178:181], v10 offset:816
	ds_read_b128 v[182:185], v10 offset:832
	ds_read_b128 v[186:189], v10 offset:848
	ds_read_b128 v[190:193], v10 offset:864
	ds_read_b128 v[194:197], v10 offset:880
	s_waitcnt vmcnt(63) lgkmcnt(8)
; #define LAS __attribute__((address_space(3)))
; __device__ __forceinline__ void p0_mod(const Args& a, LAS unsigned char* lds, int bid, int G, int tid) {
;     ...
;         for (int k = wave * 128; k < wave * 128 + 128; ++k) {
;             const float wv = wp[(size_t)k * 6144];
; #pragma unroll
;             for (int r4 = 0; r4 < 4; ++r4) { const f32x4 s = *(const LAS f32x4*)(S + k * 16 + r4 * 4);
;                 acc[r4 * 4 + 0] += s.x * wv; acc[r4 * 4 + 1] += s.y * wv; acc[r4 * 4 + 2] += s.z * wv; acc[r4 * 4 + 3] += s.w * wv; }
;         }
	v_pk_fma_f32 v[16:17], v[112:113], v[198:199], v[16:17] op_sel_hi:[0,1,1]
	v_pk_fma_f32 v[18:19], v[112:113], v[200:201], v[18:19] op_sel_hi:[0,1,1]
	v_pk_fma_f32 v[20:21], v[112:113], v[202:203], v[20:21] op_sel_hi:[0,1,1]
	v_pk_fma_f32 v[22:23], v[112:113], v[204:205], v[22:23] op_sel_hi:[0,1,1]
	v_pk_fma_f32 v[24:25], v[112:113], v[206:207], v[24:25] op_sel_hi:[0,1,1]
	v_pk_fma_f32 v[26:27], v[112:113], v[208:209], v[26:27] op_sel_hi:[0,1,1]
	v_pk_fma_f32 v[28:29], v[112:113], v[210:211], v[28:29] op_sel_hi:[0,1,1]
	v_pk_fma_f32 v[14:15], v[112:113], v[212:213], v[14:15] op_sel_hi:[0,1,1]
	global_load_dword v112, v[230:231], off
	v_lshl_add_u64 v[230:231], v[230:231], 0, s[60:61]
	s_waitcnt vmcnt(63)
	v_pk_fma_f32 v[16:17], v[112:113], v[214:215], v[16:17] op_sel:[1,0,0] op_sel_hi:[1,1,1]
	v_pk_fma_f32 v[18:19], v[112:113], v[216:217], v[18:19] op_sel:[1,0,0] op_sel_hi:[1,1,1]
	v_pk_fma_f32 v[20:21], v[112:113], v[218:219], v[20:21] op_sel:[1,0,0] op_sel_hi:[1,1,1]
	v_pk_fma_f32 v[22:23], v[112:113], v[220:221], v[22:23] op_sel:[1,0,0] op_sel_hi:[1,1,1]
	v_pk_fma_f32 v[24:25], v[112:113], v[222:223], v[24:25] op_sel:[1,0,0] op_sel_hi:[1,1,1]
	v_pk_fma_f32 v[26:27], v[112:113], v[224:225], v[26:27] op_sel:[1,0,0] op_sel_hi:[1,1,1]
	v_pk_fma_f32 v[28:29], v[112:113], v[226:227], v[28:29] op_sel:[1,0,0] op_sel_hi:[1,1,1]
	v_pk_fma_f32 v[14:15], v[112:113], v[228:229], v[14:15] op_sel:[1,0,0] op_sel_hi:[1,1,1]
	global_load_dword v113, v[230:231], off
	v_lshl_add_u64 v[230:231], v[230:231], 0, s[60:61]
	ds_read_b128 v[198:201], v10 offset:896
	ds_read_b128 v[202:205], v10 offset:912
	ds_read_b128 v[206:209], v10 offset:928
	ds_read_b128 v[210:213], v10 offset:944
	ds_read_b128 v[214:217], v10 offset:960
	ds_read_b128 v[218:221], v10 offset:976
	ds_read_b128 v[222:225], v10 offset:992
	ds_read_b128 v[226:229], v10 offset:1008
	s_waitcnt vmcnt(63) lgkmcnt(8)
	v_pk_fma_f32 v[16:17], v[114:115], v[166:167], v[16:17] op_sel_hi:[0,1,1]
	v_pk_fma_f32 v[18:19], v[114:115], v[168:169], v[18:19] op_sel_hi:[0,1,1]
	v_pk_fma_f32 v[20:21], v[114:115], v[170:171], v[20:21] op_sel_hi:[0,1,1]
	v_pk_fma_f32 v[22:23], v[114:115], v[172:173], v[22:23] op_sel_hi:[0,1,1]
	v_pk_fma_f32 v[24:25], v[114:115], v[174:175], v[24:25] op_sel_hi:[0,1,1]
	v_pk_fma_f32 v[26:27], v[114:115], v[176:177], v[26:27] op_sel_hi:[0,1,1]
	v_pk_fma_f32 v[28:29], v[114:115], v[178:179], v[28:29] op_sel_hi:[0,1,1]
	v_pk_fma_f32 v[14:15], v[114:115], v[180:181], v[14:15] op_sel_hi:[0,1,1]
	global_load_dword v114, v[230:231], off
	v_lshl_add_u64 v[230:231], v[230:231], 0, s[60:61]
	s_waitcnt vmcnt(63)
	v_pk_fma_f32 v[16:17], v[114:115], v[182:183], v[16:17] op_sel:[1,0,0] op_sel_hi:[1,1,1]
	v_pk_fma_f32 v[18:19], v[114:115], v[184:185], v[18:19] op_sel:[1,0,0] op_sel_hi:[1,1,1]
	v_pk_fma_f32 v[20:21], v[114:115], v[186:187], v[20:21] op_sel:[1,0,0] op_sel_hi:[1,1,1]
	v_pk_fma_f32 v[22:23], v[114:115], v[188:189], v[22:23] op_sel:[1,0,0] op_sel_hi:[1,1,1]
	v_pk_fma_f32 v[24:25], v[114:115], v[190:191], v[24:25] op_sel:[1,0,0] op_sel_hi:[1,1,1]
	v_pk_fma_f32 v[26:27], v[114:115], v[192:193], v[26:27] op_sel:[1,0,0] op_sel_hi:[1,1,1]
	v_pk_fma_f32 v[28:29], v[114:115], v[194:195], v[28:29] op_sel:[1,0,0] op_sel_hi:[1,1,1]
	v_pk_fma_f32 v[14:15], v[114:115], v[196:197], v[14:15] op_sel:[1,0,0] op_sel_hi:[1,1,1]
	global_load_dword v115, v[230:231], off
	v_lshl_add_u64 v[230:231], v[230:231], 0, s[60:61]
	ds_read_b128 v[166:169], v10 offset:1024
	ds_read_b128 v[170:173], v10 offset:1040
	ds_read_b128 v[174:177], v10 offset:1056
	ds_read_b128 v[178:181], v10 offset:1072
	ds_read_b128 v[182:185], v10 offset:1088
	ds_read_b128 v[186:189], v10 offset:1104
	ds_read_b128 v[190:193], v10 offset:1120
	ds_read_b128 v[194:197], v10 offset:1136
	s_waitcnt vmcnt(63) lgkmcnt(8)
	v_pk_fma_f32 v[16:17], v[116:117], v[198:199], v[16:17] op_sel_hi:[0,1,1]
	v_pk_fma_f32 v[18:19], v[116:117], v[200:201], v[18:19] op_sel_hi:[0,1,1]
	v_pk_fma_f32 v[20:21], v[116:117], v[202:203], v[20:21] op_sel_hi:[0,1,1]
	v_pk_fma_f32 v[22:23], v[116:117], v[204:205], v[22:23] op_sel_hi:[0,1,1]
	v_pk_fma_f32 v[24:25], v[116:117], v[206:207], v[24:25] op_sel_hi:[0,1,1]
	v_pk_fma_f32 v[26:27], v[116:117], v[208:209], v[26:27] op_sel_hi:[0,1,1]
	v_pk_fma_f32 v[28:29], v[116:117], v[210:211], v[28:29] op_sel_hi:[0,1,1]
	v_pk_fma_f32 v[14:15], v[116:117], v[212:213], v[14:15] op_sel_hi:[0,1,1]
	global_load_dword v116, v[230:231], off
	v_lshl_add_u64 v[230:231], v[230:231], 0, s[60:61]
	s_waitcnt vmcnt(63)
	v_pk_fma_f32 v[16:17], v[116:117], v[214:215], v[16:17] op_sel:[1,0,0] op_sel_hi:[1,1,1]
	v_pk_fma_f32 v[18:19], v[116:117], v[216:217], v[18:19] op_sel:[1,0,0] op_sel_hi:[1,1,1]
	v_pk_fma_f32 v[20:21], v[116:117], v[218:219], v[20:21] op_sel:[1,0,0] op_sel_hi:[1,1,1]
	v_pk_fma_f32 v[22:23], v[116:117], v[220:221], v[22:23] op_sel:[1,0,0] op_sel_hi:[1,1,1]
	v_pk_fma_f32 v[24:25], v[116:117], v[222:223], v[24:25] op_sel:[1,0,0] op_sel_hi:[1,1,1]
	v_pk_fma_f32 v[26:27], v[116:117], v[224:225], v[26:27] op_sel:[1,0,0] op_sel_hi:[1,1,1]
	v_pk_fma_f32 v[28:29], v[116:117], v[226:227], v[28:29] op_sel:[1,0,0] op_sel_hi:[1,1,1]
	v_pk_fma_f32 v[14:15], v[116:117], v[228:229], v[14:15] op_sel:[1,0,0] op_sel_hi:[1,1,1]
	global_load_dword v117, v[230:231], off
	v_lshl_add_u64 v[230:231], v[230:231], 0, s[60:61]
	ds_read_b128 v[198:201], v10 offset:1152
	ds_read_b128 v[202:205], v10 offset:1168
	ds_read_b128 v[206:209], v10 offset:1184
	ds_read_b128 v[210:213], v10 offset:1200
	ds_read_b128 v[214:217], v10 offset:1216
	ds_read_b128 v[218:221], v10 offset:1232
	ds_read_b128 v[222:225], v10 offset:1248
	ds_read_b128 v[226:229], v10 offset:1264
	s_waitcnt vmcnt(63) lgkmcnt(8)
; #define LAS __attribute__((address_space(3)))
; __device__ __forceinline__ void p0_mod(const Args& a, LAS unsigned char* lds, int bid, int G, int tid) {
;     ...
;         for (int k = wave * 128; k < wave * 128 + 128; ++k) {
;             const float wv = wp[(size_t)k * 6144];
; #pragma unroll
;             for (int r4 = 0; r4 < 4; ++r4) { const f32x4 s = *(const LAS f32x4*)(S + k * 16 + r4 * 4);
;                 acc[r4 * 4 + 0] += s.x * wv; acc[r4 * 4 + 1] += s.y * wv; acc[r4 * 4 + 2] += s.z * wv; acc[r4 * 4 + 3] += s.w * wv; }
;         }
	v_pk_fma_f32 v[16:17], v[118:119], v[166:167], v[16:17] op_sel_hi:[0,1,1]
	v_pk_fma_f32 v[18:19], v[118:119], v[168:169], v[18:19] op_sel_hi:[0,1,1]
	v_pk_fma_f32 v[20:21], v[118:119], v[170:171], v[20:21] op_sel_hi:[0,1,1]
	v_pk_fma_f32 v[22:23], v[118:119], v[172:173], v[22:23] op_sel_hi:[0,1,1]
	v_pk_fma_f32 v[24:25], v[118:119], v[174:175], v[24:25] op_sel_hi:[0,1,1]
	v_pk_fma_f32 v[26:27], v[118:119], v[176:177], v[26:27] op_sel_hi:[0,1,1]
	v_pk_fma_f32 v[28:29], v[118:119], v[178:179], v[28:29] op_sel_hi:[0,1,1]
	v_pk_fma_f32 v[14:15], v[118:119], v[180:181], v[14:15] op_sel_hi:[0,1,1]
	global_load_dword v118, v[230:231], off
	v_lshl_add_u64 v[230:231], v[230:231], 0, s[60:61]
	s_waitcnt vmcnt(63)
	v_pk_fma_f32 v[16:17], v[118:119], v[182:183], v[16:17] op_sel:[1,0,0] op_sel_hi:[1,1,1]
	v_pk_fma_f32 v[18:19], v[118:119], v[184:185], v[18:19] op_sel:[1,0,0] op_sel_hi:[1,1,1]
	v_pk_fma_f32 v[20:21], v[118:119], v[186:187], v[20:21] op_sel:[1,0,0] op_sel_hi:[1,1,1]
	v_pk_fma_f32 v[22:23], v[118:119], v[188:189], v[22:23] op_sel:[1,0,0] op_sel_hi:[1,1,1]
	v_pk_fma_f32 v[24:25], v[118:119], v[190:191], v[24:25] op_sel:[1,0,0] op_sel_hi:[1,1,1]
	v_pk_fma_f32 v[26:27], v[118:119], v[192:193], v[26:27] op_sel:[1,0,0] op_sel_hi:[1,1,1]
	v_pk_fma_f32 v[28:29], v[118:119], v[194:195], v[28:29] op_sel:[1,0,0] op_sel_hi:[1,1,1]
	v_pk_fma_f32 v[14:15], v[118:119], v[196:197], v[14:15] op_sel:[1,0,0] op_sel_hi:[1,1,1]
	global_load_dword v119, v[230:231], off
	v_lshl_add_u64 v[230:231], v[230:231], 0, s[60:61]
	ds_read_b128 v[166:169], v10 offset:1280
	ds_read_b128 v[170:173], v10 offset:1296
	ds_read_b128 v[174:177], v10 offset:1312
	ds_read_b128 v[178:181], v10 offset:1328
	ds_read_b128 v[182:185], v10 offset:1344
	ds_read_b128 v[186:189], v10 offset:1360
	ds_read_b128 v[190:193], v10 offset:1376
	ds_read_b128 v[194:197], v10 offset:1392
	s_waitcnt vmcnt(63) lgkmcnt(8)
	v_pk_fma_f32 v[16:17], v[120:121], v[198:199], v[16:17] op_sel_hi:[0,1,1]
	v_pk_fma_f32 v[18:19], v[120:121], v[200:201], v[18:19] op_sel_hi:[0,1,1]
	v_pk_fma_f32 v[20:21], v[120:121], v[202:203], v[20:21] op_sel_hi:[0,1,1]
	v_pk_fma_f32 v[22:23], v[120:121], v[204:205], v[22:23] op_sel_hi:[0,1,1]
	v_pk_fma_f32 v[24:25], v[120:121], v[206:207], v[24:25] op_sel_hi:[0,1,1]
	v_pk_fma_f32 v[26:27], v[120:121], v[208:209], v[26:27] op_sel_hi:[0,1,1]
	v_pk_fma_f32 v[28:29], v[120:121], v[210:211], v[28:29] op_sel_hi:[0,1,1]
	v_pk_fma_f32 v[14:15], v[120:121], v[212:213], v[14:15] op_sel_hi:[0,1,1]
	global_load_dword v120, v[230:231], off
	v_lshl_add_u64 v[230:231], v[230:231], 0, s[60:61]
	s_waitcnt vmcnt(63)
	v_pk_fma_f32 v[16:17], v[120:121], v[214:215], v[16:17] op_sel:[1,0,0] op_sel_hi:[1,1,1]
	v_pk_fma_f32 v[18:19], v[120:121], v[216:217], v[18:19] op_sel:[1,0,0] op_sel_hi:[1,1,1]
	v_pk_fma_f32 v[20:21], v[120:121], v[218:219], v[20:21] op_sel:[1,0,0] op_sel_hi:[1,1,1]
	v_pk_fma_f32 v[22:23], v[120:121], v[220:221], v[22:23] op_sel:[1,0,0] op_sel_hi:[1,1,1]
	v_pk_fma_f32 v[24:25], v[120:121], v[222:223], v[24:25] op_sel:[1,0,0] op_sel_hi:[1,1,1]
	v_pk_fma_f32 v[26:27], v[120:121], v[224:225], v[26:27] op_sel:[1,0,0] op_sel_hi:[1,1,1]
	v_pk_fma_f32 v[28:29], v[120:121], v[226:227], v[28:29] op_sel:[1,0,0] op_sel_hi:[1,1,1]
	v_pk_fma_f32 v[14:15], v[120:121], v[228:229], v[14:15] op_sel:[1,0,0] op_sel_hi:[1,1,1]
	global_load_dword v121, v[230:231], off
	v_lshl_add_u64 v[230:231], v[230:231], 0, s[60:61]
	ds_read_b128 v[198:201], v10 offset:1408
	ds_read_b128 v[202:205], v10 offset:1424
	ds_read_b128 v[206:209], v10 offset:1440
	ds_read_b128 v[210:213], v10 offset:1456
	ds_read_b128 v[214:217], v10 offset:1472
	ds_read_b128 v[218:221], v10 offset:1488
	ds_read_b128 v[222:225], v10 offset:1504
	ds_read_b128 v[226:229], v10 offset:1520
	s_waitcnt vmcnt(63) lgkmcnt(8)
	v_pk_fma_f32 v[16:17], v[122:123], v[166:167], v[16:17] op_sel_hi:[0,1,1]
	v_pk_fma_f32 v[18:19], v[122:123], v[168:169], v[18:19] op_sel_hi:[0,1,1]
	v_pk_fma_f32 v[20:21], v[122:123], v[170:171], v[20:21] op_sel_hi:[0,1,1]
	v_pk_fma_f32 v[22:23], v[122:123], v[172:173], v[22:23] op_sel_hi:[0,1,1]
	v_pk_fma_f32 v[24:25], v[122:123], v[174:175], v[24:25] op_sel_hi:[0,1,1]
	v_pk_fma_f32 v[26:27], v[122:123], v[176:177], v[26:27] op_sel_hi:[0,1,1]
	v_pk_fma_f32 v[28:29], v[122:123], v[178:179], v[28:29] op_sel_hi:[0,1,1]
	v_pk_fma_f32 v[14:15], v[122:123], v[180:181], v[14:15] op_sel_hi:[0,1,1]
	global_load_dword v122, v[230:231], off
	v_lshl_add_u64 v[230:231], v[230:231], 0, s[60:61]
	s_waitcnt vmcnt(63)
	v_pk_fma_f32 v[16:17], v[122:123], v[182:183], v[16:17] op_sel:[1,0,0] op_sel_hi:[1,1,1]
	v_pk_fma_f32 v[18:19], v[122:123], v[184:185], v[18:19] op_sel:[1,0,0] op_sel_hi:[1,1,1]
	v_pk_fma_f32 v[20:21], v[122:123], v[186:187], v[20:21] op_sel:[1,0,0] op_sel_hi:[1,1,1]
	v_pk_fma_f32 v[22:23], v[122:123], v[188:189], v[22:23] op_sel:[1,0,0] op_sel_hi:[1,1,1]
	v_pk_fma_f32 v[24:25], v[122:123], v[190:191], v[24:25] op_sel:[1,0,0] op_sel_hi:[1,1,1]
	v_pk_fma_f32 v[26:27], v[122:123], v[192:193], v[26:27] op_sel:[1,0,0] op_sel_hi:[1,1,1]
	v_pk_fma_f32 v[28:29], v[122:123], v[194:195], v[28:29] op_sel:[1,0,0] op_sel_hi:[1,1,1]
	v_pk_fma_f32 v[14:15], v[122:123], v[196:197], v[14:15] op_sel:[1,0,0] op_sel_hi:[1,1,1]
	global_load_dword v123, v[230:231], off
	v_lshl_add_u64 v[230:231], v[230:231], 0, s[60:61]
	ds_read_b128 v[166:169], v10 offset:1536
	ds_read_b128 v[170:173], v10 offset:1552
	ds_read_b128 v[174:177], v10 offset:1568
	ds_read_b128 v[178:181], v10 offset:1584
	ds_read_b128 v[182:185], v10 offset:1600
	ds_read_b128 v[186:189], v10 offset:1616
	ds_read_b128 v[190:193], v10 offset:1632
	ds_read_b128 v[194:197], v10 offset:1648
	s_waitcnt vmcnt(63) lgkmcnt(8)
; #define LAS __attribute__((address_space(3)))
; __device__ __forceinline__ void p0_mod(const Args& a, LAS unsigned char* lds, int bid, int G, int tid) {
;     ...
;         for (int k = wave * 128; k < wave * 128 + 128; ++k) {
;             const float wv = wp[(size_t)k * 6144];
; #pragma unroll
;             for (int r4 = 0; r4 < 4; ++r4) { const f32x4 s = *(const LAS f32x4*)(S + k * 16 + r4 * 4);
;                 acc[r4 * 4 + 0] += s.x * wv; acc[r4 * 4 + 1] += s.y * wv; acc[r4 * 4 + 2] += s.z * wv; acc[r4 * 4 + 3] += s.w * wv; }
;         }
	v_pk_fma_f32 v[16:17], v[124:125], v[198:199], v[16:17] op_sel_hi:[0,1,1]
	v_pk_fma_f32 v[18:19], v[124:125], v[200:201], v[18:19] op_sel_hi:[0,1,1]
	v_pk_fma_f32 v[20:21], v[124:125], v[202:203], v[20:21] op_sel_hi:[0,1,1]
	v_pk_fma_f32 v[22:23], v[124:125], v[204:205], v[22:23] op_sel_hi:[0,1,1]
	v_pk_fma_f32 v[24:25], v[124:125], v[206:207], v[24:25] op_sel_hi:[0,1,1]
	v_pk_fma_f32 v[26:27], v[124:125], v[208:209], v[26:27] op_sel_hi:[0,1,1]
	v_pk_fma_f32 v[28:29], v[124:125], v[210:211], v[28:29] op_sel_hi:[0,1,1]
	v_pk_fma_f32 v[14:15], v[124:125], v[212:213], v[14:15] op_sel_hi:[0,1,1]
	global_load_dword v124, v[230:231], off
	v_lshl_add_u64 v[230:231], v[230:231], 0, s[60:61]
	s_waitcnt vmcnt(63)
	v_pk_fma_f32 v[16:17], v[124:125], v[214:215], v[16:17] op_sel:[1,0,0] op_sel_hi:[1,1,1]
	v_pk_fma_f32 v[18:19], v[124:125], v[216:217], v[18:19] op_sel:[1,0,0] op_sel_hi:[1,1,1]
	v_pk_fma_f32 v[20:21], v[124:125], v[218:219], v[20:21] op_sel:[1,0,0] op_sel_hi:[1,1,1]
	v_pk_fma_f32 v[22:23], v[124:125], v[220:221], v[22:23] op_sel:[1,0,0] op_sel_hi:[1,1,1]
	v_pk_fma_f32 v[24:25], v[124:125], v[222:223], v[24:25] op_sel:[1,0,0] op_sel_hi:[1,1,1]
	v_pk_fma_f32 v[26:27], v[124:125], v[224:225], v[26:27] op_sel:[1,0,0] op_sel_hi:[1,1,1]
	v_pk_fma_f32 v[28:29], v[124:125], v[226:227], v[28:29] op_sel:[1,0,0] op_sel_hi:[1,1,1]
	v_pk_fma_f32 v[14:15], v[124:125], v[228:229], v[14:15] op_sel:[1,0,0] op_sel_hi:[1,1,1]
	global_load_dword v125, v[230:231], off
	v_lshl_add_u64 v[230:231], v[230:231], 0, s[60:61]
	ds_read_b128 v[198:201], v10 offset:1664
	ds_read_b128 v[202:205], v10 offset:1680
	ds_read_b128 v[206:209], v10 offset:1696
	ds_read_b128 v[210:213], v10 offset:1712
	ds_read_b128 v[214:217], v10 offset:1728
	ds_read_b128 v[218:221], v10 offset:1744
	ds_read_b128 v[222:225], v10 offset:1760
	ds_read_b128 v[226:229], v10 offset:1776
	s_waitcnt vmcnt(63) lgkmcnt(8)
	v_pk_fma_f32 v[16:17], v[126:127], v[166:167], v[16:17] op_sel_hi:[0,1,1]
	v_pk_fma_f32 v[18:19], v[126:127], v[168:169], v[18:19] op_sel_hi:[0,1,1]
	v_pk_fma_f32 v[20:21], v[126:127], v[170:171], v[20:21] op_sel_hi:[0,1,1]
	v_pk_fma_f32 v[22:23], v[126:127], v[172:173], v[22:23] op_sel_hi:[0,1,1]
	v_pk_fma_f32 v[24:25], v[126:127], v[174:175], v[24:25] op_sel_hi:[0,1,1]
	v_pk_fma_f32 v[26:27], v[126:127], v[176:177], v[26:27] op_sel_hi:[0,1,1]
	v_pk_fma_f32 v[28:29], v[126:127], v[178:179], v[28:29] op_sel_hi:[0,1,1]
	v_pk_fma_f32 v[14:15], v[126:127], v[180:181], v[14:15] op_sel_hi:[0,1,1]
	global_load_dword v126, v[230:231], off
	v_lshl_add_u64 v[230:231], v[230:231], 0, s[60:61]
	s_waitcnt vmcnt(63)
	v_pk_fma_f32 v[16:17], v[126:127], v[182:183], v[16:17] op_sel:[1,0,0] op_sel_hi:[1,1,1]
	v_pk_fma_f32 v[18:19], v[126:127], v[184:185], v[18:19] op_sel:[1,0,0] op_sel_hi:[1,1,1]
	v_pk_fma_f32 v[20:21], v[126:127], v[186:187], v[20:21] op_sel:[1,0,0] op_sel_hi:[1,1,1]
	v_pk_fma_f32 v[22:23], v[126:127], v[188:189], v[22:23] op_sel:[1,0,0] op_sel_hi:[1,1,1]
	v_pk_fma_f32 v[24:25], v[126:127], v[190:191], v[24:25] op_sel:[1,0,0] op_sel_hi:[1,1,1]
	v_pk_fma_f32 v[26:27], v[126:127], v[192:193], v[26:27] op_sel:[1,0,0] op_sel_hi:[1,1,1]
	v_pk_fma_f32 v[28:29], v[126:127], v[194:195], v[28:29] op_sel:[1,0,0] op_sel_hi:[1,1,1]
	v_pk_fma_f32 v[14:15], v[126:127], v[196:197], v[14:15] op_sel:[1,0,0] op_sel_hi:[1,1,1]
	global_load_dword v127, v[230:231], off
	v_lshl_add_u64 v[230:231], v[230:231], 0, s[60:61]
	ds_read_b128 v[166:169], v10 offset:1792
	ds_read_b128 v[170:173], v10 offset:1808
	ds_read_b128 v[174:177], v10 offset:1824
	ds_read_b128 v[178:181], v10 offset:1840
	ds_read_b128 v[182:185], v10 offset:1856
	ds_read_b128 v[186:189], v10 offset:1872
	ds_read_b128 v[190:193], v10 offset:1888
	ds_read_b128 v[194:197], v10 offset:1904
	s_waitcnt vmcnt(63) lgkmcnt(8)
	v_pk_fma_f32 v[16:17], v[128:129], v[198:199], v[16:17] op_sel_hi:[0,1,1]
	v_pk_fma_f32 v[18:19], v[128:129], v[200:201], v[18:19] op_sel_hi:[0,1,1]
	v_pk_fma_f32 v[20:21], v[128:129], v[202:203], v[20:21] op_sel_hi:[0,1,1]
	v_pk_fma_f32 v[22:23], v[128:129], v[204:205], v[22:23] op_sel_hi:[0,1,1]
	v_pk_fma_f32 v[24:25], v[128:129], v[206:207], v[24:25] op_sel_hi:[0,1,1]
	v_pk_fma_f32 v[26:27], v[128:129], v[208:209], v[26:27] op_sel_hi:[0,1,1]
	v_pk_fma_f32 v[28:29], v[128:129], v[210:211], v[28:29] op_sel_hi:[0,1,1]
	v_pk_fma_f32 v[14:15], v[128:129], v[212:213], v[14:15] op_sel_hi:[0,1,1]
	global_load_dword v128, v[230:231], off
	v_lshl_add_u64 v[230:231], v[230:231], 0, s[60:61]
	s_waitcnt vmcnt(63)
	v_pk_fma_f32 v[16:17], v[128:129], v[214:215], v[16:17] op_sel:[1,0,0] op_sel_hi:[1,1,1]
	v_pk_fma_f32 v[18:19], v[128:129], v[216:217], v[18:19] op_sel:[1,0,0] op_sel_hi:[1,1,1]
	v_pk_fma_f32 v[20:21], v[128:129], v[218:219], v[20:21] op_sel:[1,0,0] op_sel_hi:[1,1,1]
	v_pk_fma_f32 v[22:23], v[128:129], v[220:221], v[22:23] op_sel:[1,0,0] op_sel_hi:[1,1,1]
	v_pk_fma_f32 v[24:25], v[128:129], v[222:223], v[24:25] op_sel:[1,0,0] op_sel_hi:[1,1,1]
	v_pk_fma_f32 v[26:27], v[128:129], v[224:225], v[26:27] op_sel:[1,0,0] op_sel_hi:[1,1,1]
	v_pk_fma_f32 v[28:29], v[128:129], v[226:227], v[28:29] op_sel:[1,0,0] op_sel_hi:[1,1,1]
	v_pk_fma_f32 v[14:15], v[128:129], v[228:229], v[14:15] op_sel:[1,0,0] op_sel_hi:[1,1,1]
	global_load_dword v129, v[230:231], off
	v_lshl_add_u64 v[230:231], v[230:231], 0, s[60:61]
	ds_read_b128 v[198:201], v10 offset:1920
	ds_read_b128 v[202:205], v10 offset:1936
	ds_read_b128 v[206:209], v10 offset:1952
	ds_read_b128 v[210:213], v10 offset:1968
	ds_read_b128 v[214:217], v10 offset:1984
	ds_read_b128 v[218:221], v10 offset:2000
	ds_read_b128 v[222:225], v10 offset:2016
	ds_read_b128 v[226:229], v10 offset:2032
	s_waitcnt vmcnt(63) lgkmcnt(8)
; #define LAS __attribute__((address_space(3)))
; __device__ __forceinline__ void p0_mod(const Args& a, LAS unsigned char* lds, int bid, int G, int tid) {
;     ...
;         for (int k = wave * 128; k < wave * 128 + 128; ++k) {
;             const float wv = wp[(size_t)k * 6144];
; #pragma unroll
;             for (int r4 = 0; r4 < 4; ++r4) { const f32x4 s = *(const LAS f32x4*)(S + k * 16 + r4 * 4);
;                 acc[r4 * 4 + 0] += s.x * wv; acc[r4 * 4 + 1] += s.y * wv; acc[r4 * 4 + 2] += s.z * wv; acc[r4 * 4 + 3] += s.w * wv; }
;         }
	v_pk_fma_f32 v[16:17], v[130:131], v[166:167], v[16:17] op_sel_hi:[0,1,1]
	v_pk_fma_f32 v[18:19], v[130:131], v[168:169], v[18:19] op_sel_hi:[0,1,1]
	v_pk_fma_f32 v[20:21], v[130:131], v[170:171], v[20:21] op_sel_hi:[0,1,1]
	v_pk_fma_f32 v[22:23], v[130:131], v[172:173], v[22:23] op_sel_hi:[0,1,1]
	v_pk_fma_f32 v[24:25], v[130:131], v[174:175], v[24:25] op_sel_hi:[0,1,1]
	v_pk_fma_f32 v[26:27], v[130:131], v[176:177], v[26:27] op_sel_hi:[0,1,1]
	v_pk_fma_f32 v[28:29], v[130:131], v[178:179], v[28:29] op_sel_hi:[0,1,1]
	v_pk_fma_f32 v[14:15], v[130:131], v[180:181], v[14:15] op_sel_hi:[0,1,1]
	global_load_dword v130, v[230:231], off
	v_lshl_add_u64 v[230:231], v[230:231], 0, s[60:61]
	s_waitcnt vmcnt(63)
	v_pk_fma_f32 v[16:17], v[130:131], v[182:183], v[16:17] op_sel:[1,0,0] op_sel_hi:[1,1,1]
	v_pk_fma_f32 v[18:19], v[130:131], v[184:185], v[18:19] op_sel:[1,0,0] op_sel_hi:[1,1,1]
	v_pk_fma_f32 v[20:21], v[130:131], v[186:187], v[20:21] op_sel:[1,0,0] op_sel_hi:[1,1,1]
	v_pk_fma_f32 v[22:23], v[130:131], v[188:189], v[22:23] op_sel:[1,0,0] op_sel_hi:[1,1,1]
	v_pk_fma_f32 v[24:25], v[130:131], v[190:191], v[24:25] op_sel:[1,0,0] op_sel_hi:[1,1,1]
	v_pk_fma_f32 v[26:27], v[130:131], v[192:193], v[26:27] op_sel:[1,0,0] op_sel_hi:[1,1,1]
	v_pk_fma_f32 v[28:29], v[130:131], v[194:195], v[28:29] op_sel:[1,0,0] op_sel_hi:[1,1,1]
	v_pk_fma_f32 v[14:15], v[130:131], v[196:197], v[14:15] op_sel:[1,0,0] op_sel_hi:[1,1,1]
	global_load_dword v131, v[230:231], off
	v_lshl_add_u64 v[230:231], v[230:231], 0, s[60:61]
	ds_read_b128 v[166:169], v10 offset:2048
	ds_read_b128 v[170:173], v10 offset:2064
	ds_read_b128 v[174:177], v10 offset:2080
	ds_read_b128 v[178:181], v10 offset:2096
	ds_read_b128 v[182:185], v10 offset:2112
	ds_read_b128 v[186:189], v10 offset:2128
	ds_read_b128 v[190:193], v10 offset:2144
	ds_read_b128 v[194:197], v10 offset:2160
	s_waitcnt vmcnt(63) lgkmcnt(8)
	v_pk_fma_f32 v[16:17], v[132:133], v[198:199], v[16:17] op_sel_hi:[0,1,1]
	v_pk_fma_f32 v[18:19], v[132:133], v[200:201], v[18:19] op_sel_hi:[0,1,1]
	v_pk_fma_f32 v[20:21], v[132:133], v[202:203], v[20:21] op_sel_hi:[0,1,1]
	v_pk_fma_f32 v[22:23], v[132:133], v[204:205], v[22:23] op_sel_hi:[0,1,1]
	v_pk_fma_f32 v[24:25], v[132:133], v[206:207], v[24:25] op_sel_hi:[0,1,1]
	v_pk_fma_f32 v[26:27], v[132:133], v[208:209], v[26:27] op_sel_hi:[0,1,1]
	v_pk_fma_f32 v[28:29], v[132:133], v[210:211], v[28:29] op_sel_hi:[0,1,1]
	v_pk_fma_f32 v[14:15], v[132:133], v[212:213], v[14:15] op_sel_hi:[0,1,1]
	global_load_dword v132, v[230:231], off
	v_lshl_add_u64 v[230:231], v[230:231], 0, s[60:61]
	s_waitcnt vmcnt(63)
	v_pk_fma_f32 v[16:17], v[132:133], v[214:215], v[16:17] op_sel:[1,0,0] op_sel_hi:[1,1,1]
	v_pk_fma_f32 v[18:19], v[132:133], v[216:217], v[18:19] op_sel:[1,0,0] op_sel_hi:[1,1,1]
	v_pk_fma_f32 v[20:21], v[132:133], v[218:219], v[20:21] op_sel:[1,0,0] op_sel_hi:[1,1,1]
	v_pk_fma_f32 v[22:23], v[132:133], v[220:221], v[22:23] op_sel:[1,0,0] op_sel_hi:[1,1,1]
	v_pk_fma_f32 v[24:25], v[132:133], v[222:223], v[24:25] op_sel:[1,0,0] op_sel_hi:[1,1,1]
	v_pk_fma_f32 v[26:27], v[132:133], v[224:225], v[26:27] op_sel:[1,0,0] op_sel_hi:[1,1,1]
	v_pk_fma_f32 v[28:29], v[132:133], v[226:227], v[28:29] op_sel:[1,0,0] op_sel_hi:[1,1,1]
	v_pk_fma_f32 v[14:15], v[132:133], v[228:229], v[14:15] op_sel:[1,0,0] op_sel_hi:[1,1,1]
	global_load_dword v133, v[230:231], off
	v_lshl_add_u64 v[230:231], v[230:231], 0, s[60:61]
	ds_read_b128 v[198:201], v10 offset:2176
	ds_read_b128 v[202:205], v10 offset:2192
	ds_read_b128 v[206:209], v10 offset:2208
	ds_read_b128 v[210:213], v10 offset:2224
	ds_read_b128 v[214:217], v10 offset:2240
	ds_read_b128 v[218:221], v10 offset:2256
	ds_read_b128 v[222:225], v10 offset:2272
	ds_read_b128 v[226:229], v10 offset:2288
	s_waitcnt vmcnt(63) lgkmcnt(8)
	v_pk_fma_f32 v[16:17], v[134:135], v[166:167], v[16:17] op_sel_hi:[0,1,1]
	v_pk_fma_f32 v[18:19], v[134:135], v[168:169], v[18:19] op_sel_hi:[0,1,1]
	v_pk_fma_f32 v[20:21], v[134:135], v[170:171], v[20:21] op_sel_hi:[0,1,1]
	v_pk_fma_f32 v[22:23], v[134:135], v[172:173], v[22:23] op_sel_hi:[0,1,1]
	v_pk_fma_f32 v[24:25], v[134:135], v[174:175], v[24:25] op_sel_hi:[0,1,1]
	v_pk_fma_f32 v[26:27], v[134:135], v[176:177], v[26:27] op_sel_hi:[0,1,1]
	v_pk_fma_f32 v[28:29], v[134:135], v[178:179], v[28:29] op_sel_hi:[0,1,1]
	v_pk_fma_f32 v[14:15], v[134:135], v[180:181], v[14:15] op_sel_hi:[0,1,1]
	global_load_dword v134, v[230:231], off
	v_lshl_add_u64 v[230:231], v[230:231], 0, s[60:61]
	s_waitcnt vmcnt(63)
	v_pk_fma_f32 v[16:17], v[134:135], v[182:183], v[16:17] op_sel:[1,0,0] op_sel_hi:[1,1,1]
	v_pk_fma_f32 v[18:19], v[134:135], v[184:185], v[18:19] op_sel:[1,0,0] op_sel_hi:[1,1,1]
	v_pk_fma_f32 v[20:21], v[134:135], v[186:187], v[20:21] op_sel:[1,0,0] op_sel_hi:[1,1,1]
	v_pk_fma_f32 v[22:23], v[134:135], v[188:189], v[22:23] op_sel:[1,0,0] op_sel_hi:[1,1,1]
	v_pk_fma_f32 v[24:25], v[134:135], v[190:191], v[24:25] op_sel:[1,0,0] op_sel_hi:[1,1,1]
	v_pk_fma_f32 v[26:27], v[134:135], v[192:193], v[26:27] op_sel:[1,0,0] op_sel_hi:[1,1,1]
	v_pk_fma_f32 v[28:29], v[134:135], v[194:195], v[28:29] op_sel:[1,0,0] op_sel_hi:[1,1,1]
	v_pk_fma_f32 v[14:15], v[134:135], v[196:197], v[14:15] op_sel:[1,0,0] op_sel_hi:[1,1,1]
	global_load_dword v135, v[230:231], off
	v_lshl_add_u64 v[230:231], v[230:231], 0, s[60:61]
	ds_read_b128 v[166:169], v10 offset:2304
	ds_read_b128 v[170:173], v10 offset:2320
	ds_read_b128 v[174:177], v10 offset:2336
	ds_read_b128 v[178:181], v10 offset:2352
	ds_read_b128 v[182:185], v10 offset:2368
	ds_read_b128 v[186:189], v10 offset:2384
	ds_read_b128 v[190:193], v10 offset:2400
	ds_read_b128 v[194:197], v10 offset:2416
	s_waitcnt vmcnt(63) lgkmcnt(8)
; #define LAS __attribute__((address_space(3)))
; __device__ __forceinline__ void p0_mod(const Args& a, LAS unsigned char* lds, int bid, int G, int tid) {
;     ...
;         for (int k = wave * 128; k < wave * 128 + 128; ++k) {
;             const float wv = wp[(size_t)k * 6144];
; #pragma unroll
;             for (int r4 = 0; r4 < 4; ++r4) { const f32x4 s = *(const LAS f32x4*)(S + k * 16 + r4 * 4);
;                 acc[r4 * 4 + 0] += s.x * wv; acc[r4 * 4 + 1] += s.y * wv; acc[r4 * 4 + 2] += s.z * wv; acc[r4 * 4 + 3] += s.w * wv; }
;         }
	v_pk_fma_f32 v[16:17], v[136:137], v[198:199], v[16:17] op_sel_hi:[0,1,1]
	v_pk_fma_f32 v[18:19], v[136:137], v[200:201], v[18:19] op_sel_hi:[0,1,1]
	v_pk_fma_f32 v[20:21], v[136:137], v[202:203], v[20:21] op_sel_hi:[0,1,1]
	v_pk_fma_f32 v[22:23], v[136:137], v[204:205], v[22:23] op_sel_hi:[0,1,1]
	v_pk_fma_f32 v[24:25], v[136:137], v[206:207], v[24:25] op_sel_hi:[0,1,1]
	v_pk_fma_f32 v[26:27], v[136:137], v[208:209], v[26:27] op_sel_hi:[0,1,1]
	v_pk_fma_f32 v[28:29], v[136:137], v[210:211], v[28:29] op_sel_hi:[0,1,1]
	v_pk_fma_f32 v[14:15], v[136:137], v[212:213], v[14:15] op_sel_hi:[0,1,1]
	global_load_dword v136, v[230:231], off
	v_lshl_add_u64 v[230:231], v[230:231], 0, s[60:61]
	s_waitcnt vmcnt(63)
	v_pk_fma_f32 v[16:17], v[136:137], v[214:215], v[16:17] op_sel:[1,0,0] op_sel_hi:[1,1,1]
	v_pk_fma_f32 v[18:19], v[136:137], v[216:217], v[18:19] op_sel:[1,0,0] op_sel_hi:[1,1,1]
	v_pk_fma_f32 v[20:21], v[136:137], v[218:219], v[20:21] op_sel:[1,0,0] op_sel_hi:[1,1,1]
	v_pk_fma_f32 v[22:23], v[136:137], v[220:221], v[22:23] op_sel:[1,0,0] op_sel_hi:[1,1,1]
	v_pk_fma_f32 v[24:25], v[136:137], v[222:223], v[24:25] op_sel:[1,0,0] op_sel_hi:[1,1,1]
	v_pk_fma_f32 v[26:27], v[136:137], v[224:225], v[26:27] op_sel:[1,0,0] op_sel_hi:[1,1,1]
	v_pk_fma_f32 v[28:29], v[136:137], v[226:227], v[28:29] op_sel:[1,0,0] op_sel_hi:[1,1,1]
	v_pk_fma_f32 v[14:15], v[136:137], v[228:229], v[14:15] op_sel:[1,0,0] op_sel_hi:[1,1,1]
	global_load_dword v137, v[230:231], off
	v_lshl_add_u64 v[230:231], v[230:231], 0, s[60:61]
	ds_read_b128 v[198:201], v10 offset:2432
	ds_read_b128 v[202:205], v10 offset:2448
	ds_read_b128 v[206:209], v10 offset:2464
	ds_read_b128 v[210:213], v10 offset:2480
	ds_read_b128 v[214:217], v10 offset:2496
	ds_read_b128 v[218:221], v10 offset:2512
	ds_read_b128 v[222:225], v10 offset:2528
	ds_read_b128 v[226:229], v10 offset:2544
	s_waitcnt vmcnt(63) lgkmcnt(8)
	v_pk_fma_f32 v[16:17], v[138:139], v[166:167], v[16:17] op_sel_hi:[0,1,1]
	v_pk_fma_f32 v[18:19], v[138:139], v[168:169], v[18:19] op_sel_hi:[0,1,1]
	v_pk_fma_f32 v[20:21], v[138:139], v[170:171], v[20:21] op_sel_hi:[0,1,1]
	v_pk_fma_f32 v[22:23], v[138:139], v[172:173], v[22:23] op_sel_hi:[0,1,1]
	v_pk_fma_f32 v[24:25], v[138:139], v[174:175], v[24:25] op_sel_hi:[0,1,1]
	v_pk_fma_f32 v[26:27], v[138:139], v[176:177], v[26:27] op_sel_hi:[0,1,1]
	v_pk_fma_f32 v[28:29], v[138:139], v[178:179], v[28:29] op_sel_hi:[0,1,1]
	v_pk_fma_f32 v[14:15], v[138:139], v[180:181], v[14:15] op_sel_hi:[0,1,1]
	global_load_dword v138, v[230:231], off
	v_lshl_add_u64 v[230:231], v[230:231], 0, s[60:61]
	s_waitcnt vmcnt(63)
	v_pk_fma_f32 v[16:17], v[138:139], v[182:183], v[16:17] op_sel:[1,0,0] op_sel_hi:[1,1,1]
	v_pk_fma_f32 v[18:19], v[138:139], v[184:185], v[18:19] op_sel:[1,0,0] op_sel_hi:[1,1,1]
	v_pk_fma_f32 v[20:21], v[138:139], v[186:187], v[20:21] op_sel:[1,0,0] op_sel_hi:[1,1,1]
	v_pk_fma_f32 v[22:23], v[138:139], v[188:189], v[22:23] op_sel:[1,0,0] op_sel_hi:[1,1,1]
	v_pk_fma_f32 v[24:25], v[138:139], v[190:191], v[24:25] op_sel:[1,0,0] op_sel_hi:[1,1,1]
	v_pk_fma_f32 v[26:27], v[138:139], v[192:193], v[26:27] op_sel:[1,0,0] op_sel_hi:[1,1,1]
	v_pk_fma_f32 v[28:29], v[138:139], v[194:195], v[28:29] op_sel:[1,0,0] op_sel_hi:[1,1,1]
	v_pk_fma_f32 v[14:15], v[138:139], v[196:197], v[14:15] op_sel:[1,0,0] op_sel_hi:[1,1,1]
	global_load_dword v139, v[230:231], off
	v_lshl_add_u64 v[230:231], v[230:231], 0, s[60:61]
	ds_read_b128 v[166:169], v10 offset:2560
	ds_read_b128 v[170:173], v10 offset:2576
	ds_read_b128 v[174:177], v10 offset:2592
	ds_read_b128 v[178:181], v10 offset:2608
	ds_read_b128 v[182:185], v10 offset:2624
	ds_read_b128 v[186:189], v10 offset:2640
	ds_read_b128 v[190:193], v10 offset:2656
	ds_read_b128 v[194:197], v10 offset:2672
	s_waitcnt vmcnt(63) lgkmcnt(8)
	v_pk_fma_f32 v[16:17], v[140:141], v[198:199], v[16:17] op_sel_hi:[0,1,1]
	v_pk_fma_f32 v[18:19], v[140:141], v[200:201], v[18:19] op_sel_hi:[0,1,1]
	v_pk_fma_f32 v[20:21], v[140:141], v[202:203], v[20:21] op_sel_hi:[0,1,1]
	v_pk_fma_f32 v[22:23], v[140:141], v[204:205], v[22:23] op_sel_hi:[0,1,1]
	v_pk_fma_f32 v[24:25], v[140:141], v[206:207], v[24:25] op_sel_hi:[0,1,1]
	v_pk_fma_f32 v[26:27], v[140:141], v[208:209], v[26:27] op_sel_hi:[0,1,1]
	v_pk_fma_f32 v[28:29], v[140:141], v[210:211], v[28:29] op_sel_hi:[0,1,1]
	v_pk_fma_f32 v[14:15], v[140:141], v[212:213], v[14:15] op_sel_hi:[0,1,1]
	global_load_dword v140, v[230:231], off
	v_lshl_add_u64 v[230:231], v[230:231], 0, s[60:61]
	s_waitcnt vmcnt(63)
	v_pk_fma_f32 v[16:17], v[140:141], v[214:215], v[16:17] op_sel:[1,0,0] op_sel_hi:[1,1,1]
	v_pk_fma_f32 v[18:19], v[140:141], v[216:217], v[18:19] op_sel:[1,0,0] op_sel_hi:[1,1,1]
	v_pk_fma_f32 v[20:21], v[140:141], v[218:219], v[20:21] op_sel:[1,0,0] op_sel_hi:[1,1,1]
	v_pk_fma_f32 v[22:23], v[140:141], v[220:221], v[22:23] op_sel:[1,0,0] op_sel_hi:[1,1,1]
	v_pk_fma_f32 v[24:25], v[140:141], v[222:223], v[24:25] op_sel:[1,0,0] op_sel_hi:[1,1,1]
	v_pk_fma_f32 v[26:27], v[140:141], v[224:225], v[26:27] op_sel:[1,0,0] op_sel_hi:[1,1,1]
	v_pk_fma_f32 v[28:29], v[140:141], v[226:227], v[28:29] op_sel:[1,0,0] op_sel_hi:[1,1,1]
	v_pk_fma_f32 v[14:15], v[140:141], v[228:229], v[14:15] op_sel:[1,0,0] op_sel_hi:[1,1,1]
	global_load_dword v141, v[230:231], off
	v_lshl_add_u64 v[230:231], v[230:231], 0, s[60:61]
	ds_read_b128 v[198:201], v10 offset:2688
	ds_read_b128 v[202:205], v10 offset:2704
	ds_read_b128 v[206:209], v10 offset:2720
	ds_read_b128 v[210:213], v10 offset:2736
	ds_read_b128 v[214:217], v10 offset:2752
	ds_read_b128 v[218:221], v10 offset:2768
	ds_read_b128 v[222:225], v10 offset:2784
	ds_read_b128 v[226:229], v10 offset:2800
	s_waitcnt vmcnt(63) lgkmcnt(8)
; #define LAS __attribute__((address_space(3)))
; __device__ __forceinline__ void p0_mod(const Args& a, LAS unsigned char* lds, int bid, int G, int tid) {
;     ...
;         for (int k = wave * 128; k < wave * 128 + 128; ++k) {
;             const float wv = wp[(size_t)k * 6144];
; #pragma unroll
;             for (int r4 = 0; r4 < 4; ++r4) { const f32x4 s = *(const LAS f32x4*)(S + k * 16 + r4 * 4);
;                 acc[r4 * 4 + 0] += s.x * wv; acc[r4 * 4 + 1] += s.y * wv; acc[r4 * 4 + 2] += s.z * wv; acc[r4 * 4 + 3] += s.w * wv; }
;         }
	v_pk_fma_f32 v[16:17], v[142:143], v[166:167], v[16:17] op_sel_hi:[0,1,1]
	v_pk_fma_f32 v[18:19], v[142:143], v[168:169], v[18:19] op_sel_hi:[0,1,1]
	v_pk_fma_f32 v[20:21], v[142:143], v[170:171], v[20:21] op_sel_hi:[0,1,1]
	v_pk_fma_f32 v[22:23], v[142:143], v[172:173], v[22:23] op_sel_hi:[0,1,1]
	v_pk_fma_f32 v[24:25], v[142:143], v[174:175], v[24:25] op_sel_hi:[0,1,1]
	v_pk_fma_f32 v[26:27], v[142:143], v[176:177], v[26:27] op_sel_hi:[0,1,1]
	v_pk_fma_f32 v[28:29], v[142:143], v[178:179], v[28:29] op_sel_hi:[0,1,1]
	v_pk_fma_f32 v[14:15], v[142:143], v[180:181], v[14:15] op_sel_hi:[0,1,1]
	global_load_dword v142, v[230:231], off
	v_lshl_add_u64 v[230:231], v[230:231], 0, s[60:61]
	s_waitcnt vmcnt(63)
	v_pk_fma_f32 v[16:17], v[142:143], v[182:183], v[16:17] op_sel:[1,0,0] op_sel_hi:[1,1,1]
	v_pk_fma_f32 v[18:19], v[142:143], v[184:185], v[18:19] op_sel:[1,0,0] op_sel_hi:[1,1,1]
	v_pk_fma_f32 v[20:21], v[142:143], v[186:187], v[20:21] op_sel:[1,0,0] op_sel_hi:[1,1,1]
	v_pk_fma_f32 v[22:23], v[142:143], v[188:189], v[22:23] op_sel:[1,0,0] op_sel_hi:[1,1,1]
	v_pk_fma_f32 v[24:25], v[142:143], v[190:191], v[24:25] op_sel:[1,0,0] op_sel_hi:[1,1,1]
	v_pk_fma_f32 v[26:27], v[142:143], v[192:193], v[26:27] op_sel:[1,0,0] op_sel_hi:[1,1,1]
	v_pk_fma_f32 v[28:29], v[142:143], v[194:195], v[28:29] op_sel:[1,0,0] op_sel_hi:[1,1,1]
	v_pk_fma_f32 v[14:15], v[142:143], v[196:197], v[14:15] op_sel:[1,0,0] op_sel_hi:[1,1,1]
	global_load_dword v143, v[230:231], off
	v_lshl_add_u64 v[230:231], v[230:231], 0, s[60:61]
	ds_read_b128 v[166:169], v10 offset:2816
	ds_read_b128 v[170:173], v10 offset:2832
	ds_read_b128 v[174:177], v10 offset:2848
	ds_read_b128 v[178:181], v10 offset:2864
	ds_read_b128 v[182:185], v10 offset:2880
	ds_read_b128 v[186:189], v10 offset:2896
	ds_read_b128 v[190:193], v10 offset:2912
	ds_read_b128 v[194:197], v10 offset:2928
	s_waitcnt vmcnt(63) lgkmcnt(8)
	v_pk_fma_f32 v[16:17], v[144:145], v[198:199], v[16:17] op_sel_hi:[0,1,1]
	v_pk_fma_f32 v[18:19], v[144:145], v[200:201], v[18:19] op_sel_hi:[0,1,1]
	v_pk_fma_f32 v[20:21], v[144:145], v[202:203], v[20:21] op_sel_hi:[0,1,1]
	v_pk_fma_f32 v[22:23], v[144:145], v[204:205], v[22:23] op_sel_hi:[0,1,1]
	v_pk_fma_f32 v[24:25], v[144:145], v[206:207], v[24:25] op_sel_hi:[0,1,1]
	v_pk_fma_f32 v[26:27], v[144:145], v[208:209], v[26:27] op_sel_hi:[0,1,1]
	v_pk_fma_f32 v[28:29], v[144:145], v[210:211], v[28:29] op_sel_hi:[0,1,1]
	v_pk_fma_f32 v[14:15], v[144:145], v[212:213], v[14:15] op_sel_hi:[0,1,1]
	global_load_dword v144, v[230:231], off
	v_lshl_add_u64 v[230:231], v[230:231], 0, s[60:61]
	s_waitcnt vmcnt(63)
	v_pk_fma_f32 v[16:17], v[144:145], v[214:215], v[16:17] op_sel:[1,0,0] op_sel_hi:[1,1,1]
	v_pk_fma_f32 v[18:19], v[144:145], v[216:217], v[18:19] op_sel:[1,0,0] op_sel_hi:[1,1,1]
	v_pk_fma_f32 v[20:21], v[144:145], v[218:219], v[20:21] op_sel:[1,0,0] op_sel_hi:[1,1,1]
	v_pk_fma_f32 v[22:23], v[144:145], v[220:221], v[22:23] op_sel:[1,0,0] op_sel_hi:[1,1,1]
	v_pk_fma_f32 v[24:25], v[144:145], v[222:223], v[24:25] op_sel:[1,0,0] op_sel_hi:[1,1,1]
	v_pk_fma_f32 v[26:27], v[144:145], v[224:225], v[26:27] op_sel:[1,0,0] op_sel_hi:[1,1,1]
	v_pk_fma_f32 v[28:29], v[144:145], v[226:227], v[28:29] op_sel:[1,0,0] op_sel_hi:[1,1,1]
	v_pk_fma_f32 v[14:15], v[144:145], v[228:229], v[14:15] op_sel:[1,0,0] op_sel_hi:[1,1,1]
	global_load_dword v145, v[230:231], off
	v_lshl_add_u64 v[230:231], v[230:231], 0, s[60:61]
	ds_read_b128 v[198:201], v10 offset:2944
	ds_read_b128 v[202:205], v10 offset:2960
	ds_read_b128 v[206:209], v10 offset:2976
	ds_read_b128 v[210:213], v10 offset:2992
	ds_read_b128 v[214:217], v10 offset:3008
	ds_read_b128 v[218:221], v10 offset:3024
	ds_read_b128 v[222:225], v10 offset:3040
	ds_read_b128 v[226:229], v10 offset:3056
	s_waitcnt vmcnt(63) lgkmcnt(8)
	v_pk_fma_f32 v[16:17], v[146:147], v[166:167], v[16:17] op_sel_hi:[0,1,1]
	v_pk_fma_f32 v[18:19], v[146:147], v[168:169], v[18:19] op_sel_hi:[0,1,1]
	v_pk_fma_f32 v[20:21], v[146:147], v[170:171], v[20:21] op_sel_hi:[0,1,1]
	v_pk_fma_f32 v[22:23], v[146:147], v[172:173], v[22:23] op_sel_hi:[0,1,1]
	v_pk_fma_f32 v[24:25], v[146:147], v[174:175], v[24:25] op_sel_hi:[0,1,1]
	v_pk_fma_f32 v[26:27], v[146:147], v[176:177], v[26:27] op_sel_hi:[0,1,1]
	v_pk_fma_f32 v[28:29], v[146:147], v[178:179], v[28:29] op_sel_hi:[0,1,1]
	v_pk_fma_f32 v[14:15], v[146:147], v[180:181], v[14:15] op_sel_hi:[0,1,1]
	global_load_dword v146, v[230:231], off
	v_lshl_add_u64 v[230:231], v[230:231], 0, s[60:61]
	s_waitcnt vmcnt(63)
	v_pk_fma_f32 v[16:17], v[146:147], v[182:183], v[16:17] op_sel:[1,0,0] op_sel_hi:[1,1,1]
	v_pk_fma_f32 v[18:19], v[146:147], v[184:185], v[18:19] op_sel:[1,0,0] op_sel_hi:[1,1,1]
	v_pk_fma_f32 v[20:21], v[146:147], v[186:187], v[20:21] op_sel:[1,0,0] op_sel_hi:[1,1,1]
	v_pk_fma_f32 v[22:23], v[146:147], v[188:189], v[22:23] op_sel:[1,0,0] op_sel_hi:[1,1,1]
	v_pk_fma_f32 v[24:25], v[146:147], v[190:191], v[24:25] op_sel:[1,0,0] op_sel_hi:[1,1,1]
	v_pk_fma_f32 v[26:27], v[146:147], v[192:193], v[26:27] op_sel:[1,0,0] op_sel_hi:[1,1,1]
	v_pk_fma_f32 v[28:29], v[146:147], v[194:195], v[28:29] op_sel:[1,0,0] op_sel_hi:[1,1,1]
	v_pk_fma_f32 v[14:15], v[146:147], v[196:197], v[14:15] op_sel:[1,0,0] op_sel_hi:[1,1,1]
	global_load_dword v147, v[230:231], off
	v_lshl_add_u64 v[230:231], v[230:231], 0, s[60:61]
	ds_read_b128 v[166:169], v10 offset:3072
	ds_read_b128 v[170:173], v10 offset:3088
	ds_read_b128 v[174:177], v10 offset:3104
	ds_read_b128 v[178:181], v10 offset:3120
	ds_read_b128 v[182:185], v10 offset:3136
	ds_read_b128 v[186:189], v10 offset:3152
	ds_read_b128 v[190:193], v10 offset:3168
	ds_read_b128 v[194:197], v10 offset:3184
	s_waitcnt vmcnt(63) lgkmcnt(8)
; #define LAS __attribute__((address_space(3)))
; __device__ __forceinline__ void p0_mod(const Args& a, LAS unsigned char* lds, int bid, int G, int tid) {
;     ...
;         for (int k = wave * 128; k < wave * 128 + 128; ++k) {
;             const float wv = wp[(size_t)k * 6144];
; #pragma unroll
;             for (int r4 = 0; r4 < 4; ++r4) { const f32x4 s = *(const LAS f32x4*)(S + k * 16 + r4 * 4);
;                 acc[r4 * 4 + 0] += s.x * wv; acc[r4 * 4 + 1] += s.y * wv; acc[r4 * 4 + 2] += s.z * wv; acc[r4 * 4 + 3] += s.w * wv; }
;         }
	v_pk_fma_f32 v[16:17], v[148:149], v[198:199], v[16:17] op_sel_hi:[0,1,1]
	v_pk_fma_f32 v[18:19], v[148:149], v[200:201], v[18:19] op_sel_hi:[0,1,1]
	v_pk_fma_f32 v[20:21], v[148:149], v[202:203], v[20:21] op_sel_hi:[0,1,1]
	v_pk_fma_f32 v[22:23], v[148:149], v[204:205], v[22:23] op_sel_hi:[0,1,1]
	v_pk_fma_f32 v[24:25], v[148:149], v[206:207], v[24:25] op_sel_hi:[0,1,1]
	v_pk_fma_f32 v[26:27], v[148:149], v[208:209], v[26:27] op_sel_hi:[0,1,1]
	v_pk_fma_f32 v[28:29], v[148:149], v[210:211], v[28:29] op_sel_hi:[0,1,1]
	v_pk_fma_f32 v[14:15], v[148:149], v[212:213], v[14:15] op_sel_hi:[0,1,1]
	global_load_dword v148, v[230:231], off
	v_lshl_add_u64 v[230:231], v[230:231], 0, s[60:61]
	s_waitcnt vmcnt(63)
	v_pk_fma_f32 v[16:17], v[148:149], v[214:215], v[16:17] op_sel:[1,0,0] op_sel_hi:[1,1,1]
	v_pk_fma_f32 v[18:19], v[148:149], v[216:217], v[18:19] op_sel:[1,0,0] op_sel_hi:[1,1,1]
	v_pk_fma_f32 v[20:21], v[148:149], v[218:219], v[20:21] op_sel:[1,0,0] op_sel_hi:[1,1,1]
	v_pk_fma_f32 v[22:23], v[148:149], v[220:221], v[22:23] op_sel:[1,0,0] op_sel_hi:[1,1,1]
	v_pk_fma_f32 v[24:25], v[148:149], v[222:223], v[24:25] op_sel:[1,0,0] op_sel_hi:[1,1,1]
	v_pk_fma_f32 v[26:27], v[148:149], v[224:225], v[26:27] op_sel:[1,0,0] op_sel_hi:[1,1,1]
	v_pk_fma_f32 v[28:29], v[148:149], v[226:227], v[28:29] op_sel:[1,0,0] op_sel_hi:[1,1,1]
	v_pk_fma_f32 v[14:15], v[148:149], v[228:229], v[14:15] op_sel:[1,0,0] op_sel_hi:[1,1,1]
	global_load_dword v149, v[230:231], off
	v_lshl_add_u64 v[230:231], v[230:231], 0, s[60:61]
	ds_read_b128 v[198:201], v10 offset:3200
	ds_read_b128 v[202:205], v10 offset:3216
	ds_read_b128 v[206:209], v10 offset:3232
	ds_read_b128 v[210:213], v10 offset:3248
	ds_read_b128 v[214:217], v10 offset:3264
	ds_read_b128 v[218:221], v10 offset:3280
	ds_read_b128 v[222:225], v10 offset:3296
	ds_read_b128 v[226:229], v10 offset:3312
	s_waitcnt vmcnt(63) lgkmcnt(8)
	v_pk_fma_f32 v[16:17], v[150:151], v[166:167], v[16:17] op_sel_hi:[0,1,1]
	v_pk_fma_f32 v[18:19], v[150:151], v[168:169], v[18:19] op_sel_hi:[0,1,1]
	v_pk_fma_f32 v[20:21], v[150:151], v[170:171], v[20:21] op_sel_hi:[0,1,1]
	v_pk_fma_f32 v[22:23], v[150:151], v[172:173], v[22:23] op_sel_hi:[0,1,1]
	v_pk_fma_f32 v[24:25], v[150:151], v[174:175], v[24:25] op_sel_hi:[0,1,1]
	v_pk_fma_f32 v[26:27], v[150:151], v[176:177], v[26:27] op_sel_hi:[0,1,1]
	v_pk_fma_f32 v[28:29], v[150:151], v[178:179], v[28:29] op_sel_hi:[0,1,1]
	v_pk_fma_f32 v[14:15], v[150:151], v[180:181], v[14:15] op_sel_hi:[0,1,1]
	global_load_dword v150, v[230:231], off
	v_lshl_add_u64 v[230:231], v[230:231], 0, s[60:61]
	s_waitcnt vmcnt(63)
	v_pk_fma_f32 v[16:17], v[150:151], v[182:183], v[16:17] op_sel:[1,0,0] op_sel_hi:[1,1,1]
	v_pk_fma_f32 v[18:19], v[150:151], v[184:185], v[18:19] op_sel:[1,0,0] op_sel_hi:[1,1,1]
	v_pk_fma_f32 v[20:21], v[150:151], v[186:187], v[20:21] op_sel:[1,0,0] op_sel_hi:[1,1,1]
	v_pk_fma_f32 v[22:23], v[150:151], v[188:189], v[22:23] op_sel:[1,0,0] op_sel_hi:[1,1,1]
	v_pk_fma_f32 v[24:25], v[150:151], v[190:191], v[24:25] op_sel:[1,0,0] op_sel_hi:[1,1,1]
	v_pk_fma_f32 v[26:27], v[150:151], v[192:193], v[26:27] op_sel:[1,0,0] op_sel_hi:[1,1,1]
	v_pk_fma_f32 v[28:29], v[150:151], v[194:195], v[28:29] op_sel:[1,0,0] op_sel_hi:[1,1,1]
	v_pk_fma_f32 v[14:15], v[150:151], v[196:197], v[14:15] op_sel:[1,0,0] op_sel_hi:[1,1,1]
	global_load_dword v151, v[230:231], off
	v_lshl_add_u64 v[230:231], v[230:231], 0, s[60:61]
	ds_read_b128 v[166:169], v10 offset:3328
	ds_read_b128 v[170:173], v10 offset:3344
	ds_read_b128 v[174:177], v10 offset:3360
	ds_read_b128 v[178:181], v10 offset:3376
	ds_read_b128 v[182:185], v10 offset:3392
	ds_read_b128 v[186:189], v10 offset:3408
	ds_read_b128 v[190:193], v10 offset:3424
	ds_read_b128 v[194:197], v10 offset:3440
	s_waitcnt vmcnt(63) lgkmcnt(8)
	v_pk_fma_f32 v[16:17], v[152:153], v[198:199], v[16:17] op_sel_hi:[0,1,1]
	v_pk_fma_f32 v[18:19], v[152:153], v[200:201], v[18:19] op_sel_hi:[0,1,1]
	v_pk_fma_f32 v[20:21], v[152:153], v[202:203], v[20:21] op_sel_hi:[0,1,1]
	v_pk_fma_f32 v[22:23], v[152:153], v[204:205], v[22:23] op_sel_hi:[0,1,1]
	v_pk_fma_f32 v[24:25], v[152:153], v[206:207], v[24:25] op_sel_hi:[0,1,1]
	v_pk_fma_f32 v[26:27], v[152:153], v[208:209], v[26:27] op_sel_hi:[0,1,1]
	v_pk_fma_f32 v[28:29], v[152:153], v[210:211], v[28:29] op_sel_hi:[0,1,1]
	v_pk_fma_f32 v[14:15], v[152:153], v[212:213], v[14:15] op_sel_hi:[0,1,1]
	global_load_dword v152, v[230:231], off
	v_lshl_add_u64 v[230:231], v[230:231], 0, s[60:61]
	s_waitcnt vmcnt(63)
	v_pk_fma_f32 v[16:17], v[152:153], v[214:215], v[16:17] op_sel:[1,0,0] op_sel_hi:[1,1,1]
	v_pk_fma_f32 v[18:19], v[152:153], v[216:217], v[18:19] op_sel:[1,0,0] op_sel_hi:[1,1,1]
	v_pk_fma_f32 v[20:21], v[152:153], v[218:219], v[20:21] op_sel:[1,0,0] op_sel_hi:[1,1,1]
	v_pk_fma_f32 v[22:23], v[152:153], v[220:221], v[22:23] op_sel:[1,0,0] op_sel_hi:[1,1,1]
	v_pk_fma_f32 v[24:25], v[152:153], v[222:223], v[24:25] op_sel:[1,0,0] op_sel_hi:[1,1,1]
	v_pk_fma_f32 v[26:27], v[152:153], v[224:225], v[26:27] op_sel:[1,0,0] op_sel_hi:[1,1,1]
	v_pk_fma_f32 v[28:29], v[152:153], v[226:227], v[28:29] op_sel:[1,0,0] op_sel_hi:[1,1,1]
	v_pk_fma_f32 v[14:15], v[152:153], v[228:229], v[14:15] op_sel:[1,0,0] op_sel_hi:[1,1,1]
	global_load_dword v153, v[230:231], off
	v_lshl_add_u64 v[230:231], v[230:231], 0, s[60:61]
	ds_read_b128 v[198:201], v10 offset:3456
	ds_read_b128 v[202:205], v10 offset:3472
	ds_read_b128 v[206:209], v10 offset:3488
	ds_read_b128 v[210:213], v10 offset:3504
	ds_read_b128 v[214:217], v10 offset:3520
	ds_read_b128 v[218:221], v10 offset:3536
	ds_read_b128 v[222:225], v10 offset:3552
	ds_read_b128 v[226:229], v10 offset:3568
	s_waitcnt vmcnt(63) lgkmcnt(8)
; #define LAS __attribute__((address_space(3)))
; __device__ __forceinline__ void p0_mod(const Args& a, LAS unsigned char* lds, int bid, int G, int tid) {
;     ...
;         for (int k = wave * 128; k < wave * 128 + 128; ++k) {
;             const float wv = wp[(size_t)k * 6144];
; #pragma unroll
;             for (int r4 = 0; r4 < 4; ++r4) { const f32x4 s = *(const LAS f32x4*)(S + k * 16 + r4 * 4);
;                 acc[r4 * 4 + 0] += s.x * wv; acc[r4 * 4 + 1] += s.y * wv; acc[r4 * 4 + 2] += s.z * wv; acc[r4 * 4 + 3] += s.w * wv; }
;         }
	v_pk_fma_f32 v[16:17], v[154:155], v[166:167], v[16:17] op_sel_hi:[0,1,1]
	v_pk_fma_f32 v[18:19], v[154:155], v[168:169], v[18:19] op_sel_hi:[0,1,1]
	v_pk_fma_f32 v[20:21], v[154:155], v[170:171], v[20:21] op_sel_hi:[0,1,1]
	v_pk_fma_f32 v[22:23], v[154:155], v[172:173], v[22:23] op_sel_hi:[0,1,1]
	v_pk_fma_f32 v[24:25], v[154:155], v[174:175], v[24:25] op_sel_hi:[0,1,1]
	v_pk_fma_f32 v[26:27], v[154:155], v[176:177], v[26:27] op_sel_hi:[0,1,1]
	v_pk_fma_f32 v[28:29], v[154:155], v[178:179], v[28:29] op_sel_hi:[0,1,1]
	v_pk_fma_f32 v[14:15], v[154:155], v[180:181], v[14:15] op_sel_hi:[0,1,1]
	global_load_dword v154, v[230:231], off
	v_lshl_add_u64 v[230:231], v[230:231], 0, s[60:61]
	s_waitcnt vmcnt(63)
	v_pk_fma_f32 v[16:17], v[154:155], v[182:183], v[16:17] op_sel:[1,0,0] op_sel_hi:[1,1,1]
	v_pk_fma_f32 v[18:19], v[154:155], v[184:185], v[18:19] op_sel:[1,0,0] op_sel_hi:[1,1,1]
	v_pk_fma_f32 v[20:21], v[154:155], v[186:187], v[20:21] op_sel:[1,0,0] op_sel_hi:[1,1,1]
	v_pk_fma_f32 v[22:23], v[154:155], v[188:189], v[22:23] op_sel:[1,0,0] op_sel_hi:[1,1,1]
	v_pk_fma_f32 v[24:25], v[154:155], v[190:191], v[24:25] op_sel:[1,0,0] op_sel_hi:[1,1,1]
	v_pk_fma_f32 v[26:27], v[154:155], v[192:193], v[26:27] op_sel:[1,0,0] op_sel_hi:[1,1,1]
	v_pk_fma_f32 v[28:29], v[154:155], v[194:195], v[28:29] op_sel:[1,0,0] op_sel_hi:[1,1,1]
	v_pk_fma_f32 v[14:15], v[154:155], v[196:197], v[14:15] op_sel:[1,0,0] op_sel_hi:[1,1,1]
	global_load_dword v155, v[230:231], off
	v_lshl_add_u64 v[230:231], v[230:231], 0, s[60:61]
	ds_read_b128 v[166:169], v10 offset:3584
	ds_read_b128 v[170:173], v10 offset:3600
	ds_read_b128 v[174:177], v10 offset:3616
	ds_read_b128 v[178:181], v10 offset:3632
	ds_read_b128 v[182:185], v10 offset:3648
	ds_read_b128 v[186:189], v10 offset:3664
	ds_read_b128 v[190:193], v10 offset:3680
	ds_read_b128 v[194:197], v10 offset:3696
	s_waitcnt vmcnt(63) lgkmcnt(8)
	v_pk_fma_f32 v[16:17], v[156:157], v[198:199], v[16:17] op_sel_hi:[0,1,1]
	v_pk_fma_f32 v[18:19], v[156:157], v[200:201], v[18:19] op_sel_hi:[0,1,1]
	v_pk_fma_f32 v[20:21], v[156:157], v[202:203], v[20:21] op_sel_hi:[0,1,1]
	v_pk_fma_f32 v[22:23], v[156:157], v[204:205], v[22:23] op_sel_hi:[0,1,1]
	v_pk_fma_f32 v[24:25], v[156:157], v[206:207], v[24:25] op_sel_hi:[0,1,1]
	v_pk_fma_f32 v[26:27], v[156:157], v[208:209], v[26:27] op_sel_hi:[0,1,1]
	v_pk_fma_f32 v[28:29], v[156:157], v[210:211], v[28:29] op_sel_hi:[0,1,1]
	v_pk_fma_f32 v[14:15], v[156:157], v[212:213], v[14:15] op_sel_hi:[0,1,1]
	global_load_dword v156, v[230:231], off
	v_lshl_add_u64 v[230:231], v[230:231], 0, s[60:61]
	s_waitcnt vmcnt(63)
	v_pk_fma_f32 v[16:17], v[156:157], v[214:215], v[16:17] op_sel:[1,0,0] op_sel_hi:[1,1,1]
	v_pk_fma_f32 v[18:19], v[156:157], v[216:217], v[18:19] op_sel:[1,0,0] op_sel_hi:[1,1,1]
	v_pk_fma_f32 v[20:21], v[156:157], v[218:219], v[20:21] op_sel:[1,0,0] op_sel_hi:[1,1,1]
	v_pk_fma_f32 v[22:23], v[156:157], v[220:221], v[22:23] op_sel:[1,0,0] op_sel_hi:[1,1,1]
	v_pk_fma_f32 v[24:25], v[156:157], v[222:223], v[24:25] op_sel:[1,0,0] op_sel_hi:[1,1,1]
	v_pk_fma_f32 v[26:27], v[156:157], v[224:225], v[26:27] op_sel:[1,0,0] op_sel_hi:[1,1,1]
	v_pk_fma_f32 v[28:29], v[156:157], v[226:227], v[28:29] op_sel:[1,0,0] op_sel_hi:[1,1,1]
	v_pk_fma_f32 v[14:15], v[156:157], v[228:229], v[14:15] op_sel:[1,0,0] op_sel_hi:[1,1,1]
	global_load_dword v157, v[230:231], off
	v_lshl_add_u64 v[230:231], v[230:231], 0, s[60:61]
	ds_read_b128 v[198:201], v10 offset:3712
	ds_read_b128 v[202:205], v10 offset:3728
	ds_read_b128 v[206:209], v10 offset:3744
	ds_read_b128 v[210:213], v10 offset:3760
	ds_read_b128 v[214:217], v10 offset:3776
	ds_read_b128 v[218:221], v10 offset:3792
	ds_read_b128 v[222:225], v10 offset:3808
	ds_read_b128 v[226:229], v10 offset:3824
	s_waitcnt vmcnt(63) lgkmcnt(8)
	v_pk_fma_f32 v[16:17], v[158:159], v[166:167], v[16:17] op_sel_hi:[0,1,1]
	v_pk_fma_f32 v[18:19], v[158:159], v[168:169], v[18:19] op_sel_hi:[0,1,1]
	v_pk_fma_f32 v[20:21], v[158:159], v[170:171], v[20:21] op_sel_hi:[0,1,1]
	v_pk_fma_f32 v[22:23], v[158:159], v[172:173], v[22:23] op_sel_hi:[0,1,1]
	v_pk_fma_f32 v[24:25], v[158:159], v[174:175], v[24:25] op_sel_hi:[0,1,1]
	v_pk_fma_f32 v[26:27], v[158:159], v[176:177], v[26:27] op_sel_hi:[0,1,1]
	v_pk_fma_f32 v[28:29], v[158:159], v[178:179], v[28:29] op_sel_hi:[0,1,1]
	v_pk_fma_f32 v[14:15], v[158:159], v[180:181], v[14:15] op_sel_hi:[0,1,1]
	global_load_dword v158, v[230:231], off
	v_lshl_add_u64 v[230:231], v[230:231], 0, s[60:61]
	s_waitcnt vmcnt(63)
	v_pk_fma_f32 v[16:17], v[158:159], v[182:183], v[16:17] op_sel:[1,0,0] op_sel_hi:[1,1,1]
	v_pk_fma_f32 v[18:19], v[158:159], v[184:185], v[18:19] op_sel:[1,0,0] op_sel_hi:[1,1,1]
	v_pk_fma_f32 v[20:21], v[158:159], v[186:187], v[20:21] op_sel:[1,0,0] op_sel_hi:[1,1,1]
	v_pk_fma_f32 v[22:23], v[158:159], v[188:189], v[22:23] op_sel:[1,0,0] op_sel_hi:[1,1,1]
	v_pk_fma_f32 v[24:25], v[158:159], v[190:191], v[24:25] op_sel:[1,0,0] op_sel_hi:[1,1,1]
	v_pk_fma_f32 v[26:27], v[158:159], v[192:193], v[26:27] op_sel:[1,0,0] op_sel_hi:[1,1,1]
	v_pk_fma_f32 v[28:29], v[158:159], v[194:195], v[28:29] op_sel:[1,0,0] op_sel_hi:[1,1,1]
	v_pk_fma_f32 v[14:15], v[158:159], v[196:197], v[14:15] op_sel:[1,0,0] op_sel_hi:[1,1,1]
	global_load_dword v159, v[230:231], off
	v_lshl_add_u64 v[230:231], v[230:231], 0, s[60:61]
	ds_read_b128 v[166:169], v10 offset:3840
	ds_read_b128 v[170:173], v10 offset:3856
	ds_read_b128 v[174:177], v10 offset:3872
	ds_read_b128 v[178:181], v10 offset:3888
	ds_read_b128 v[182:185], v10 offset:3904
	ds_read_b128 v[186:189], v10 offset:3920
	ds_read_b128 v[190:193], v10 offset:3936
	ds_read_b128 v[194:197], v10 offset:3952
	s_waitcnt vmcnt(63) lgkmcnt(8)
; #define LAS __attribute__((address_space(3)))
; __device__ __forceinline__ void p0_mod(const Args& a, LAS unsigned char* lds, int bid, int G, int tid) {
;     ...
;         for (int k = wave * 128; k < wave * 128 + 128; ++k) {
;             const float wv = wp[(size_t)k * 6144];
; #pragma unroll
;             for (int r4 = 0; r4 < 4; ++r4) { const f32x4 s = *(const LAS f32x4*)(S + k * 16 + r4 * 4);
;                 acc[r4 * 4 + 0] += s.x * wv; acc[r4 * 4 + 1] += s.y * wv; acc[r4 * 4 + 2] += s.z * wv; acc[r4 * 4 + 3] += s.w * wv; }
;         }
	v_pk_fma_f32 v[16:17], v[160:161], v[198:199], v[16:17] op_sel_hi:[0,1,1]
	v_pk_fma_f32 v[18:19], v[160:161], v[200:201], v[18:19] op_sel_hi:[0,1,1]
	v_pk_fma_f32 v[20:21], v[160:161], v[202:203], v[20:21] op_sel_hi:[0,1,1]
	v_pk_fma_f32 v[22:23], v[160:161], v[204:205], v[22:23] op_sel_hi:[0,1,1]
	v_pk_fma_f32 v[24:25], v[160:161], v[206:207], v[24:25] op_sel_hi:[0,1,1]
	v_pk_fma_f32 v[26:27], v[160:161], v[208:209], v[26:27] op_sel_hi:[0,1,1]
	v_pk_fma_f32 v[28:29], v[160:161], v[210:211], v[28:29] op_sel_hi:[0,1,1]
	v_pk_fma_f32 v[14:15], v[160:161], v[212:213], v[14:15] op_sel_hi:[0,1,1]
	global_load_dword v160, v[230:231], off
	v_lshl_add_u64 v[230:231], v[230:231], 0, s[60:61]
	s_waitcnt vmcnt(63)
	v_pk_fma_f32 v[16:17], v[160:161], v[214:215], v[16:17] op_sel:[1,0,0] op_sel_hi:[1,1,1]
	v_pk_fma_f32 v[18:19], v[160:161], v[216:217], v[18:19] op_sel:[1,0,0] op_sel_hi:[1,1,1]
	v_pk_fma_f32 v[20:21], v[160:161], v[218:219], v[20:21] op_sel:[1,0,0] op_sel_hi:[1,1,1]
	v_pk_fma_f32 v[22:23], v[160:161], v[220:221], v[22:23] op_sel:[1,0,0] op_sel_hi:[1,1,1]
	v_pk_fma_f32 v[24:25], v[160:161], v[222:223], v[24:25] op_sel:[1,0,0] op_sel_hi:[1,1,1]
	v_pk_fma_f32 v[26:27], v[160:161], v[224:225], v[26:27] op_sel:[1,0,0] op_sel_hi:[1,1,1]
	v_pk_fma_f32 v[28:29], v[160:161], v[226:227], v[28:29] op_sel:[1,0,0] op_sel_hi:[1,1,1]
	v_pk_fma_f32 v[14:15], v[160:161], v[228:229], v[14:15] op_sel:[1,0,0] op_sel_hi:[1,1,1]
	global_load_dword v161, v[230:231], off
	v_lshl_add_u64 v[230:231], v[230:231], 0, s[60:61]
	ds_read_b128 v[198:201], v10 offset:3968
	ds_read_b128 v[202:205], v10 offset:3984
	ds_read_b128 v[206:209], v10 offset:4000
	ds_read_b128 v[210:213], v10 offset:4016
	ds_read_b128 v[214:217], v10 offset:4032
	ds_read_b128 v[218:221], v10 offset:4048
	ds_read_b128 v[222:225], v10 offset:4064
	ds_read_b128 v[226:229], v10 offset:4080
	s_waitcnt vmcnt(63) lgkmcnt(8)
	v_pk_fma_f32 v[16:17], v[162:163], v[166:167], v[16:17] op_sel_hi:[0,1,1]
	v_pk_fma_f32 v[18:19], v[162:163], v[168:169], v[18:19] op_sel_hi:[0,1,1]
	v_pk_fma_f32 v[20:21], v[162:163], v[170:171], v[20:21] op_sel_hi:[0,1,1]
	v_pk_fma_f32 v[22:23], v[162:163], v[172:173], v[22:23] op_sel_hi:[0,1,1]
	v_pk_fma_f32 v[24:25], v[162:163], v[174:175], v[24:25] op_sel_hi:[0,1,1]
	v_pk_fma_f32 v[26:27], v[162:163], v[176:177], v[26:27] op_sel_hi:[0,1,1]
	v_pk_fma_f32 v[28:29], v[162:163], v[178:179], v[28:29] op_sel_hi:[0,1,1]
	v_pk_fma_f32 v[14:15], v[162:163], v[180:181], v[14:15] op_sel_hi:[0,1,1]
	global_load_dword v162, v[230:231], off
	v_lshl_add_u64 v[230:231], v[230:231], 0, s[60:61]
	s_waitcnt vmcnt(63)
	v_pk_fma_f32 v[16:17], v[162:163], v[182:183], v[16:17] op_sel:[1,0,0] op_sel_hi:[1,1,1]
	v_pk_fma_f32 v[18:19], v[162:163], v[184:185], v[18:19] op_sel:[1,0,0] op_sel_hi:[1,1,1]
	v_pk_fma_f32 v[20:21], v[162:163], v[186:187], v[20:21] op_sel:[1,0,0] op_sel_hi:[1,1,1]
	v_pk_fma_f32 v[22:23], v[162:163], v[188:189], v[22:23] op_sel:[1,0,0] op_sel_hi:[1,1,1]
	v_pk_fma_f32 v[24:25], v[162:163], v[190:191], v[24:25] op_sel:[1,0,0] op_sel_hi:[1,1,1]
	v_pk_fma_f32 v[26:27], v[162:163], v[192:193], v[26:27] op_sel:[1,0,0] op_sel_hi:[1,1,1]
	v_pk_fma_f32 v[28:29], v[162:163], v[194:195], v[28:29] op_sel:[1,0,0] op_sel_hi:[1,1,1]
	v_pk_fma_f32 v[14:15], v[162:163], v[196:197], v[14:15] op_sel:[1,0,0] op_sel_hi:[1,1,1]
	global_load_dword v163, v[230:231], off
	v_lshl_add_u64 v[230:231], v[230:231], 0, s[60:61]
	ds_read_b128 v[166:169], v10 offset:4096
	ds_read_b128 v[170:173], v10 offset:4112
	ds_read_b128 v[174:177], v10 offset:4128
	ds_read_b128 v[178:181], v10 offset:4144
	ds_read_b128 v[182:185], v10 offset:4160
	ds_read_b128 v[186:189], v10 offset:4176
	ds_read_b128 v[190:193], v10 offset:4192
	ds_read_b128 v[194:197], v10 offset:4208
	s_waitcnt vmcnt(63) lgkmcnt(8)
	v_pk_fma_f32 v[16:17], v[164:165], v[198:199], v[16:17] op_sel_hi:[0,1,1]
	v_pk_fma_f32 v[18:19], v[164:165], v[200:201], v[18:19] op_sel_hi:[0,1,1]
	v_pk_fma_f32 v[20:21], v[164:165], v[202:203], v[20:21] op_sel_hi:[0,1,1]
	v_pk_fma_f32 v[22:23], v[164:165], v[204:205], v[22:23] op_sel_hi:[0,1,1]
	v_pk_fma_f32 v[24:25], v[164:165], v[206:207], v[24:25] op_sel_hi:[0,1,1]
	v_pk_fma_f32 v[26:27], v[164:165], v[208:209], v[26:27] op_sel_hi:[0,1,1]
	v_pk_fma_f32 v[28:29], v[164:165], v[210:211], v[28:29] op_sel_hi:[0,1,1]
	v_pk_fma_f32 v[14:15], v[164:165], v[212:213], v[14:15] op_sel_hi:[0,1,1]
	global_load_dword v164, v[230:231], off
	v_lshl_add_u64 v[230:231], v[230:231], 0, s[60:61]
	s_waitcnt vmcnt(63)
	v_pk_fma_f32 v[16:17], v[164:165], v[214:215], v[16:17] op_sel:[1,0,0] op_sel_hi:[1,1,1]
	v_pk_fma_f32 v[18:19], v[164:165], v[216:217], v[18:19] op_sel:[1,0,0] op_sel_hi:[1,1,1]
	v_pk_fma_f32 v[20:21], v[164:165], v[218:219], v[20:21] op_sel:[1,0,0] op_sel_hi:[1,1,1]
	v_pk_fma_f32 v[22:23], v[164:165], v[220:221], v[22:23] op_sel:[1,0,0] op_sel_hi:[1,1,1]
	v_pk_fma_f32 v[24:25], v[164:165], v[222:223], v[24:25] op_sel:[1,0,0] op_sel_hi:[1,1,1]
	v_pk_fma_f32 v[26:27], v[164:165], v[224:225], v[26:27] op_sel:[1,0,0] op_sel_hi:[1,1,1]
	v_pk_fma_f32 v[28:29], v[164:165], v[226:227], v[28:29] op_sel:[1,0,0] op_sel_hi:[1,1,1]
	v_pk_fma_f32 v[14:15], v[164:165], v[228:229], v[14:15] op_sel:[1,0,0] op_sel_hi:[1,1,1]
	global_load_dword v165, v[230:231], off
	ds_read_b128 v[198:201], v10 offset:4224
	ds_read_b128 v[202:205], v10 offset:4240
	ds_read_b128 v[206:209], v10 offset:4256
	ds_read_b128 v[210:213], v10 offset:4272
	ds_read_b128 v[214:217], v10 offset:4288
	ds_read_b128 v[218:221], v10 offset:4304
	ds_read_b128 v[222:225], v10 offset:4320
	ds_read_b128 v[226:229], v10 offset:4336
	s_waitcnt vmcnt(63) lgkmcnt(8)
; #define LAS __attribute__((address_space(3)))
; __device__ __forceinline__ void p0_mod(const Args& a, LAS unsigned char* lds, int bid, int G, int tid) {
;     ...
;         for (int k = wave * 128; k < wave * 128 + 128; ++k) {
;             const float wv = wp[(size_t)k * 6144];
; #pragma unroll
;             for (int r4 = 0; r4 < 4; ++r4) { const f32x4 s = *(const LAS f32x4*)(S + k * 16 + r4 * 4);
;                 acc[r4 * 4 + 0] += s.x * wv; acc[r4 * 4 + 1] += s.y * wv; acc[r4 * 4 + 2] += s.z * wv; acc[r4 * 4 + 3] += s.w * wv; }
;         }
	v_pk_fma_f32 v[16:17], v[102:103], v[166:167], v[16:17] op_sel_hi:[0,1,1]
	v_pk_fma_f32 v[18:19], v[102:103], v[168:169], v[18:19] op_sel_hi:[0,1,1]
	v_pk_fma_f32 v[20:21], v[102:103], v[170:171], v[20:21] op_sel_hi:[0,1,1]
	v_pk_fma_f32 v[22:23], v[102:103], v[172:173], v[22:23] op_sel_hi:[0,1,1]
	v_pk_fma_f32 v[24:25], v[102:103], v[174:175], v[24:25] op_sel_hi:[0,1,1]
	v_pk_fma_f32 v[26:27], v[102:103], v[176:177], v[26:27] op_sel_hi:[0,1,1]
	v_pk_fma_f32 v[28:29], v[102:103], v[178:179], v[28:29] op_sel_hi:[0,1,1]
	v_pk_fma_f32 v[14:15], v[102:103], v[180:181], v[14:15] op_sel_hi:[0,1,1]
	s_waitcnt vmcnt(62)
	v_pk_fma_f32 v[16:17], v[102:103], v[182:183], v[16:17] op_sel:[1,0,0] op_sel_hi:[1,1,1]
	v_pk_fma_f32 v[18:19], v[102:103], v[184:185], v[18:19] op_sel:[1,0,0] op_sel_hi:[1,1,1]
	v_pk_fma_f32 v[20:21], v[102:103], v[186:187], v[20:21] op_sel:[1,0,0] op_sel_hi:[1,1,1]
	v_pk_fma_f32 v[22:23], v[102:103], v[188:189], v[22:23] op_sel:[1,0,0] op_sel_hi:[1,1,1]
	v_pk_fma_f32 v[24:25], v[102:103], v[190:191], v[24:25] op_sel:[1,0,0] op_sel_hi:[1,1,1]
	v_pk_fma_f32 v[26:27], v[102:103], v[192:193], v[26:27] op_sel:[1,0,0] op_sel_hi:[1,1,1]
	v_pk_fma_f32 v[28:29], v[102:103], v[194:195], v[28:29] op_sel:[1,0,0] op_sel_hi:[1,1,1]
	v_pk_fma_f32 v[14:15], v[102:103], v[196:197], v[14:15] op_sel:[1,0,0] op_sel_hi:[1,1,1]
	ds_read_b128 v[166:169], v10 offset:4352
	ds_read_b128 v[170:173], v10 offset:4368
	ds_read_b128 v[174:177], v10 offset:4384
	ds_read_b128 v[178:181], v10 offset:4400
	ds_read_b128 v[182:185], v10 offset:4416
	ds_read_b128 v[186:189], v10 offset:4432
	ds_read_b128 v[190:193], v10 offset:4448
	ds_read_b128 v[194:197], v10 offset:4464
	s_waitcnt vmcnt(61) lgkmcnt(8)
	v_pk_fma_f32 v[16:17], v[104:105], v[198:199], v[16:17] op_sel_hi:[0,1,1]
	v_pk_fma_f32 v[18:19], v[104:105], v[200:201], v[18:19] op_sel_hi:[0,1,1]
	v_pk_fma_f32 v[20:21], v[104:105], v[202:203], v[20:21] op_sel_hi:[0,1,1]
	v_pk_fma_f32 v[22:23], v[104:105], v[204:205], v[22:23] op_sel_hi:[0,1,1]
	v_pk_fma_f32 v[24:25], v[104:105], v[206:207], v[24:25] op_sel_hi:[0,1,1]
	v_pk_fma_f32 v[26:27], v[104:105], v[208:209], v[26:27] op_sel_hi:[0,1,1]
	v_pk_fma_f32 v[28:29], v[104:105], v[210:211], v[28:29] op_sel_hi:[0,1,1]
	v_pk_fma_f32 v[14:15], v[104:105], v[212:213], v[14:15] op_sel_hi:[0,1,1]
	s_waitcnt vmcnt(60)
	v_pk_fma_f32 v[16:17], v[104:105], v[214:215], v[16:17] op_sel:[1,0,0] op_sel_hi:[1,1,1]
	v_pk_fma_f32 v[18:19], v[104:105], v[216:217], v[18:19] op_sel:[1,0,0] op_sel_hi:[1,1,1]
	v_pk_fma_f32 v[20:21], v[104:105], v[218:219], v[20:21] op_sel:[1,0,0] op_sel_hi:[1,1,1]
	v_pk_fma_f32 v[22:23], v[104:105], v[220:221], v[22:23] op_sel:[1,0,0] op_sel_hi:[1,1,1]
	v_pk_fma_f32 v[24:25], v[104:105], v[222:223], v[24:25] op_sel:[1,0,0] op_sel_hi:[1,1,1]
	v_pk_fma_f32 v[26:27], v[104:105], v[224:225], v[26:27] op_sel:[1,0,0] op_sel_hi:[1,1,1]
	v_pk_fma_f32 v[28:29], v[104:105], v[226:227], v[28:29] op_sel:[1,0,0] op_sel_hi:[1,1,1]
	v_pk_fma_f32 v[14:15], v[104:105], v[228:229], v[14:15] op_sel:[1,0,0] op_sel_hi:[1,1,1]
	ds_read_b128 v[198:201], v10 offset:4480
	ds_read_b128 v[202:205], v10 offset:4496
	ds_read_b128 v[206:209], v10 offset:4512
	ds_read_b128 v[210:213], v10 offset:4528
	ds_read_b128 v[214:217], v10 offset:4544
	ds_read_b128 v[218:221], v10 offset:4560
	ds_read_b128 v[222:225], v10 offset:4576
	ds_read_b128 v[226:229], v10 offset:4592
	s_waitcnt vmcnt(59) lgkmcnt(8)
	v_pk_fma_f32 v[16:17], v[106:107], v[166:167], v[16:17] op_sel_hi:[0,1,1]
	v_pk_fma_f32 v[18:19], v[106:107], v[168:169], v[18:19] op_sel_hi:[0,1,1]
	v_pk_fma_f32 v[20:21], v[106:107], v[170:171], v[20:21] op_sel_hi:[0,1,1]
	v_pk_fma_f32 v[22:23], v[106:107], v[172:173], v[22:23] op_sel_hi:[0,1,1]
	v_pk_fma_f32 v[24:25], v[106:107], v[174:175], v[24:25] op_sel_hi:[0,1,1]
	v_pk_fma_f32 v[26:27], v[106:107], v[176:177], v[26:27] op_sel_hi:[0,1,1]
	v_pk_fma_f32 v[28:29], v[106:107], v[178:179], v[28:29] op_sel_hi:[0,1,1]
	v_pk_fma_f32 v[14:15], v[106:107], v[180:181], v[14:15] op_sel_hi:[0,1,1]
	s_waitcnt vmcnt(58)
	v_pk_fma_f32 v[16:17], v[106:107], v[182:183], v[16:17] op_sel:[1,0,0] op_sel_hi:[1,1,1]
	v_pk_fma_f32 v[18:19], v[106:107], v[184:185], v[18:19] op_sel:[1,0,0] op_sel_hi:[1,1,1]
	v_pk_fma_f32 v[20:21], v[106:107], v[186:187], v[20:21] op_sel:[1,0,0] op_sel_hi:[1,1,1]
	v_pk_fma_f32 v[22:23], v[106:107], v[188:189], v[22:23] op_sel:[1,0,0] op_sel_hi:[1,1,1]
	v_pk_fma_f32 v[24:25], v[106:107], v[190:191], v[24:25] op_sel:[1,0,0] op_sel_hi:[1,1,1]
	v_pk_fma_f32 v[26:27], v[106:107], v[192:193], v[26:27] op_sel:[1,0,0] op_sel_hi:[1,1,1]
	v_pk_fma_f32 v[28:29], v[106:107], v[194:195], v[28:29] op_sel:[1,0,0] op_sel_hi:[1,1,1]
	v_pk_fma_f32 v[14:15], v[106:107], v[196:197], v[14:15] op_sel:[1,0,0] op_sel_hi:[1,1,1]
	ds_read_b128 v[166:169], v10 offset:4608
	ds_read_b128 v[170:173], v10 offset:4624
	ds_read_b128 v[174:177], v10 offset:4640
	ds_read_b128 v[178:181], v10 offset:4656
	ds_read_b128 v[182:185], v10 offset:4672
	ds_read_b128 v[186:189], v10 offset:4688
	ds_read_b128 v[190:193], v10 offset:4704
	ds_read_b128 v[194:197], v10 offset:4720
	s_waitcnt vmcnt(57) lgkmcnt(8)
	v_pk_fma_f32 v[16:17], v[108:109], v[198:199], v[16:17] op_sel_hi:[0,1,1]
	v_pk_fma_f32 v[18:19], v[108:109], v[200:201], v[18:19] op_sel_hi:[0,1,1]
	v_pk_fma_f32 v[20:21], v[108:109], v[202:203], v[20:21] op_sel_hi:[0,1,1]
	v_pk_fma_f32 v[22:23], v[108:109], v[204:205], v[22:23] op_sel_hi:[0,1,1]
	v_pk_fma_f32 v[24:25], v[108:109], v[206:207], v[24:25] op_sel_hi:[0,1,1]
	v_pk_fma_f32 v[26:27], v[108:109], v[208:209], v[26:27] op_sel_hi:[0,1,1]
	v_pk_fma_f32 v[28:29], v[108:109], v[210:211], v[28:29] op_sel_hi:[0,1,1]
	v_pk_fma_f32 v[14:15], v[108:109], v[212:213], v[14:15] op_sel_hi:[0,1,1]
	s_waitcnt vmcnt(56)
; #define LAS __attribute__((address_space(3)))
; __device__ __forceinline__ void p0_mod(const Args& a, LAS unsigned char* lds, int bid, int G, int tid) {
;     ...
;         for (int k = wave * 128; k < wave * 128 + 128; ++k) {
;             const float wv = wp[(size_t)k * 6144];
; #pragma unroll
;             for (int r4 = 0; r4 < 4; ++r4) { const f32x4 s = *(const LAS f32x4*)(S + k * 16 + r4 * 4);
;                 acc[r4 * 4 + 0] += s.x * wv; acc[r4 * 4 + 1] += s.y * wv; acc[r4 * 4 + 2] += s.z * wv; acc[r4 * 4 + 3] += s.w * wv; }
;         }
	v_pk_fma_f32 v[16:17], v[108:109], v[214:215], v[16:17] op_sel:[1,0,0] op_sel_hi:[1,1,1]
	v_pk_fma_f32 v[18:19], v[108:109], v[216:217], v[18:19] op_sel:[1,0,0] op_sel_hi:[1,1,1]
	v_pk_fma_f32 v[20:21], v[108:109], v[218:219], v[20:21] op_sel:[1,0,0] op_sel_hi:[1,1,1]
	v_pk_fma_f32 v[22:23], v[108:109], v[220:221], v[22:23] op_sel:[1,0,0] op_sel_hi:[1,1,1]
	v_pk_fma_f32 v[24:25], v[108:109], v[222:223], v[24:25] op_sel:[1,0,0] op_sel_hi:[1,1,1]
	v_pk_fma_f32 v[26:27], v[108:109], v[224:225], v[26:27] op_sel:[1,0,0] op_sel_hi:[1,1,1]
	v_pk_fma_f32 v[28:29], v[108:109], v[226:227], v[28:29] op_sel:[1,0,0] op_sel_hi:[1,1,1]
	v_pk_fma_f32 v[14:15], v[108:109], v[228:229], v[14:15] op_sel:[1,0,0] op_sel_hi:[1,1,1]
	ds_read_b128 v[198:201], v10 offset:4736
	ds_read_b128 v[202:205], v10 offset:4752
	ds_read_b128 v[206:209], v10 offset:4768
	ds_read_b128 v[210:213], v10 offset:4784
	ds_read_b128 v[214:217], v10 offset:4800
	ds_read_b128 v[218:221], v10 offset:4816
	ds_read_b128 v[222:225], v10 offset:4832
	ds_read_b128 v[226:229], v10 offset:4848
	s_waitcnt vmcnt(55) lgkmcnt(8)
	v_pk_fma_f32 v[16:17], v[110:111], v[166:167], v[16:17] op_sel_hi:[0,1,1]
	v_pk_fma_f32 v[18:19], v[110:111], v[168:169], v[18:19] op_sel_hi:[0,1,1]
	v_pk_fma_f32 v[20:21], v[110:111], v[170:171], v[20:21] op_sel_hi:[0,1,1]
	v_pk_fma_f32 v[22:23], v[110:111], v[172:173], v[22:23] op_sel_hi:[0,1,1]
	v_pk_fma_f32 v[24:25], v[110:111], v[174:175], v[24:25] op_sel_hi:[0,1,1]
	v_pk_fma_f32 v[26:27], v[110:111], v[176:177], v[26:27] op_sel_hi:[0,1,1]
	v_pk_fma_f32 v[28:29], v[110:111], v[178:179], v[28:29] op_sel_hi:[0,1,1]
	v_pk_fma_f32 v[14:15], v[110:111], v[180:181], v[14:15] op_sel_hi:[0,1,1]
	s_waitcnt vmcnt(54)
	v_pk_fma_f32 v[16:17], v[110:111], v[182:183], v[16:17] op_sel:[1,0,0] op_sel_hi:[1,1,1]
	v_pk_fma_f32 v[18:19], v[110:111], v[184:185], v[18:19] op_sel:[1,0,0] op_sel_hi:[1,1,1]
	v_pk_fma_f32 v[20:21], v[110:111], v[186:187], v[20:21] op_sel:[1,0,0] op_sel_hi:[1,1,1]
	v_pk_fma_f32 v[22:23], v[110:111], v[188:189], v[22:23] op_sel:[1,0,0] op_sel_hi:[1,1,1]
	v_pk_fma_f32 v[24:25], v[110:111], v[190:191], v[24:25] op_sel:[1,0,0] op_sel_hi:[1,1,1]
	v_pk_fma_f32 v[26:27], v[110:111], v[192:193], v[26:27] op_sel:[1,0,0] op_sel_hi:[1,1,1]
	v_pk_fma_f32 v[28:29], v[110:111], v[194:195], v[28:29] op_sel:[1,0,0] op_sel_hi:[1,1,1]
	v_pk_fma_f32 v[14:15], v[110:111], v[196:197], v[14:15] op_sel:[1,0,0] op_sel_hi:[1,1,1]
	ds_read_b128 v[166:169], v10 offset:4864
	ds_read_b128 v[170:173], v10 offset:4880
	ds_read_b128 v[174:177], v10 offset:4896
	ds_read_b128 v[178:181], v10 offset:4912
	ds_read_b128 v[182:185], v10 offset:4928
	ds_read_b128 v[186:189], v10 offset:4944
	ds_read_b128 v[190:193], v10 offset:4960
	ds_read_b128 v[194:197], v10 offset:4976
	s_waitcnt vmcnt(53) lgkmcnt(8)
	v_pk_fma_f32 v[16:17], v[112:113], v[198:199], v[16:17] op_sel_hi:[0,1,1]
	v_pk_fma_f32 v[18:19], v[112:113], v[200:201], v[18:19] op_sel_hi:[0,1,1]
	v_pk_fma_f32 v[20:21], v[112:113], v[202:203], v[20:21] op_sel_hi:[0,1,1]
	v_pk_fma_f32 v[22:23], v[112:113], v[204:205], v[22:23] op_sel_hi:[0,1,1]
	v_pk_fma_f32 v[24:25], v[112:113], v[206:207], v[24:25] op_sel_hi:[0,1,1]
	v_pk_fma_f32 v[26:27], v[112:113], v[208:209], v[26:27] op_sel_hi:[0,1,1]
	v_pk_fma_f32 v[28:29], v[112:113], v[210:211], v[28:29] op_sel_hi:[0,1,1]
	v_pk_fma_f32 v[14:15], v[112:113], v[212:213], v[14:15] op_sel_hi:[0,1,1]
	s_waitcnt vmcnt(52)
	v_pk_fma_f32 v[16:17], v[112:113], v[214:215], v[16:17] op_sel:[1,0,0] op_sel_hi:[1,1,1]
	v_pk_fma_f32 v[18:19], v[112:113], v[216:217], v[18:19] op_sel:[1,0,0] op_sel_hi:[1,1,1]
	v_pk_fma_f32 v[20:21], v[112:113], v[218:219], v[20:21] op_sel:[1,0,0] op_sel_hi:[1,1,1]
	v_pk_fma_f32 v[22:23], v[112:113], v[220:221], v[22:23] op_sel:[1,0,0] op_sel_hi:[1,1,1]
	v_pk_fma_f32 v[24:25], v[112:113], v[222:223], v[24:25] op_sel:[1,0,0] op_sel_hi:[1,1,1]
	v_pk_fma_f32 v[26:27], v[112:113], v[224:225], v[26:27] op_sel:[1,0,0] op_sel_hi:[1,1,1]
	v_pk_fma_f32 v[28:29], v[112:113], v[226:227], v[28:29] op_sel:[1,0,0] op_sel_hi:[1,1,1]
	v_pk_fma_f32 v[14:15], v[112:113], v[228:229], v[14:15] op_sel:[1,0,0] op_sel_hi:[1,1,1]
	ds_read_b128 v[198:201], v10 offset:4992
	ds_read_b128 v[202:205], v10 offset:5008
	ds_read_b128 v[206:209], v10 offset:5024
	ds_read_b128 v[210:213], v10 offset:5040
	ds_read_b128 v[214:217], v10 offset:5056
	ds_read_b128 v[218:221], v10 offset:5072
	ds_read_b128 v[222:225], v10 offset:5088
	ds_read_b128 v[226:229], v10 offset:5104
	s_waitcnt vmcnt(51) lgkmcnt(8)
	v_pk_fma_f32 v[16:17], v[114:115], v[166:167], v[16:17] op_sel_hi:[0,1,1]
	v_pk_fma_f32 v[18:19], v[114:115], v[168:169], v[18:19] op_sel_hi:[0,1,1]
	v_pk_fma_f32 v[20:21], v[114:115], v[170:171], v[20:21] op_sel_hi:[0,1,1]
	v_pk_fma_f32 v[22:23], v[114:115], v[172:173], v[22:23] op_sel_hi:[0,1,1]
	v_pk_fma_f32 v[24:25], v[114:115], v[174:175], v[24:25] op_sel_hi:[0,1,1]
	v_pk_fma_f32 v[26:27], v[114:115], v[176:177], v[26:27] op_sel_hi:[0,1,1]
	v_pk_fma_f32 v[28:29], v[114:115], v[178:179], v[28:29] op_sel_hi:[0,1,1]
	v_pk_fma_f32 v[14:15], v[114:115], v[180:181], v[14:15] op_sel_hi:[0,1,1]
	s_waitcnt vmcnt(50)
; #define LAS __attribute__((address_space(3)))
; __device__ __forceinline__ void p0_mod(const Args& a, LAS unsigned char* lds, int bid, int G, int tid) {
;     ...
;         for (int k = wave * 128; k < wave * 128 + 128; ++k) {
;             const float wv = wp[(size_t)k * 6144];
; #pragma unroll
;             for (int r4 = 0; r4 < 4; ++r4) { const f32x4 s = *(const LAS f32x4*)(S + k * 16 + r4 * 4);
;                 acc[r4 * 4 + 0] += s.x * wv; acc[r4 * 4 + 1] += s.y * wv; acc[r4 * 4 + 2] += s.z * wv; acc[r4 * 4 + 3] += s.w * wv; }
;         }
	v_pk_fma_f32 v[16:17], v[114:115], v[182:183], v[16:17] op_sel:[1,0,0] op_sel_hi:[1,1,1]
	v_pk_fma_f32 v[18:19], v[114:115], v[184:185], v[18:19] op_sel:[1,0,0] op_sel_hi:[1,1,1]
	v_pk_fma_f32 v[20:21], v[114:115], v[186:187], v[20:21] op_sel:[1,0,0] op_sel_hi:[1,1,1]
	v_pk_fma_f32 v[22:23], v[114:115], v[188:189], v[22:23] op_sel:[1,0,0] op_sel_hi:[1,1,1]
	v_pk_fma_f32 v[24:25], v[114:115], v[190:191], v[24:25] op_sel:[1,0,0] op_sel_hi:[1,1,1]
	v_pk_fma_f32 v[26:27], v[114:115], v[192:193], v[26:27] op_sel:[1,0,0] op_sel_hi:[1,1,1]
	v_pk_fma_f32 v[28:29], v[114:115], v[194:195], v[28:29] op_sel:[1,0,0] op_sel_hi:[1,1,1]
	v_pk_fma_f32 v[14:15], v[114:115], v[196:197], v[14:15] op_sel:[1,0,0] op_sel_hi:[1,1,1]
	ds_read_b128 v[166:169], v10 offset:5120
	ds_read_b128 v[170:173], v10 offset:5136
	ds_read_b128 v[174:177], v10 offset:5152
	ds_read_b128 v[178:181], v10 offset:5168
	ds_read_b128 v[182:185], v10 offset:5184
	ds_read_b128 v[186:189], v10 offset:5200
	ds_read_b128 v[190:193], v10 offset:5216
	ds_read_b128 v[194:197], v10 offset:5232
	s_waitcnt vmcnt(49) lgkmcnt(8)
	v_pk_fma_f32 v[16:17], v[116:117], v[198:199], v[16:17] op_sel_hi:[0,1,1]
	v_pk_fma_f32 v[18:19], v[116:117], v[200:201], v[18:19] op_sel_hi:[0,1,1]
	v_pk_fma_f32 v[20:21], v[116:117], v[202:203], v[20:21] op_sel_hi:[0,1,1]
	v_pk_fma_f32 v[22:23], v[116:117], v[204:205], v[22:23] op_sel_hi:[0,1,1]
	v_pk_fma_f32 v[24:25], v[116:117], v[206:207], v[24:25] op_sel_hi:[0,1,1]
	v_pk_fma_f32 v[26:27], v[116:117], v[208:209], v[26:27] op_sel_hi:[0,1,1]
	v_pk_fma_f32 v[28:29], v[116:117], v[210:211], v[28:29] op_sel_hi:[0,1,1]
	v_pk_fma_f32 v[14:15], v[116:117], v[212:213], v[14:15] op_sel_hi:[0,1,1]
	s_waitcnt vmcnt(48)
	v_pk_fma_f32 v[16:17], v[116:117], v[214:215], v[16:17] op_sel:[1,0,0] op_sel_hi:[1,1,1]
	v_pk_fma_f32 v[18:19], v[116:117], v[216:217], v[18:19] op_sel:[1,0,0] op_sel_hi:[1,1,1]
	v_pk_fma_f32 v[20:21], v[116:117], v[218:219], v[20:21] op_sel:[1,0,0] op_sel_hi:[1,1,1]
	v_pk_fma_f32 v[22:23], v[116:117], v[220:221], v[22:23] op_sel:[1,0,0] op_sel_hi:[1,1,1]
	v_pk_fma_f32 v[24:25], v[116:117], v[222:223], v[24:25] op_sel:[1,0,0] op_sel_hi:[1,1,1]
	v_pk_fma_f32 v[26:27], v[116:117], v[224:225], v[26:27] op_sel:[1,0,0] op_sel_hi:[1,1,1]
	v_pk_fma_f32 v[28:29], v[116:117], v[226:227], v[28:29] op_sel:[1,0,0] op_sel_hi:[1,1,1]
	v_pk_fma_f32 v[14:15], v[116:117], v[228:229], v[14:15] op_sel:[1,0,0] op_sel_hi:[1,1,1]
	ds_read_b128 v[198:201], v10 offset:5248
	ds_read_b128 v[202:205], v10 offset:5264
	ds_read_b128 v[206:209], v10 offset:5280
	ds_read_b128 v[210:213], v10 offset:5296
	ds_read_b128 v[214:217], v10 offset:5312
	ds_read_b128 v[218:221], v10 offset:5328
	ds_read_b128 v[222:225], v10 offset:5344
	ds_read_b128 v[226:229], v10 offset:5360
	s_waitcnt vmcnt(47) lgkmcnt(8)
	v_pk_fma_f32 v[16:17], v[118:119], v[166:167], v[16:17] op_sel_hi:[0,1,1]
	v_pk_fma_f32 v[18:19], v[118:119], v[168:169], v[18:19] op_sel_hi:[0,1,1]
	v_pk_fma_f32 v[20:21], v[118:119], v[170:171], v[20:21] op_sel_hi:[0,1,1]
	v_pk_fma_f32 v[22:23], v[118:119], v[172:173], v[22:23] op_sel_hi:[0,1,1]
	v_pk_fma_f32 v[24:25], v[118:119], v[174:175], v[24:25] op_sel_hi:[0,1,1]
	v_pk_fma_f32 v[26:27], v[118:119], v[176:177], v[26:27] op_sel_hi:[0,1,1]
	v_pk_fma_f32 v[28:29], v[118:119], v[178:179], v[28:29] op_sel_hi:[0,1,1]
	v_pk_fma_f32 v[14:15], v[118:119], v[180:181], v[14:15] op_sel_hi:[0,1,1]
	s_waitcnt vmcnt(46)
	v_pk_fma_f32 v[16:17], v[118:119], v[182:183], v[16:17] op_sel:[1,0,0] op_sel_hi:[1,1,1]
	v_pk_fma_f32 v[18:19], v[118:119], v[184:185], v[18:19] op_sel:[1,0,0] op_sel_hi:[1,1,1]
	v_pk_fma_f32 v[20:21], v[118:119], v[186:187], v[20:21] op_sel:[1,0,0] op_sel_hi:[1,1,1]
	v_pk_fma_f32 v[22:23], v[118:119], v[188:189], v[22:23] op_sel:[1,0,0] op_sel_hi:[1,1,1]
	v_pk_fma_f32 v[24:25], v[118:119], v[190:191], v[24:25] op_sel:[1,0,0] op_sel_hi:[1,1,1]
	v_pk_fma_f32 v[26:27], v[118:119], v[192:193], v[26:27] op_sel:[1,0,0] op_sel_hi:[1,1,1]
	v_pk_fma_f32 v[28:29], v[118:119], v[194:195], v[28:29] op_sel:[1,0,0] op_sel_hi:[1,1,1]
	v_pk_fma_f32 v[14:15], v[118:119], v[196:197], v[14:15] op_sel:[1,0,0] op_sel_hi:[1,1,1]
	ds_read_b128 v[166:169], v10 offset:5376
	ds_read_b128 v[170:173], v10 offset:5392
	ds_read_b128 v[174:177], v10 offset:5408
	ds_read_b128 v[178:181], v10 offset:5424
	ds_read_b128 v[182:185], v10 offset:5440
	ds_read_b128 v[186:189], v10 offset:5456
	ds_read_b128 v[190:193], v10 offset:5472
	ds_read_b128 v[194:197], v10 offset:5488
	s_waitcnt vmcnt(45) lgkmcnt(8)
	v_pk_fma_f32 v[16:17], v[120:121], v[198:199], v[16:17] op_sel_hi:[0,1,1]
	v_pk_fma_f32 v[18:19], v[120:121], v[200:201], v[18:19] op_sel_hi:[0,1,1]
	v_pk_fma_f32 v[20:21], v[120:121], v[202:203], v[20:21] op_sel_hi:[0,1,1]
	v_pk_fma_f32 v[22:23], v[120:121], v[204:205], v[22:23] op_sel_hi:[0,1,1]
	v_pk_fma_f32 v[24:25], v[120:121], v[206:207], v[24:25] op_sel_hi:[0,1,1]
	v_pk_fma_f32 v[26:27], v[120:121], v[208:209], v[26:27] op_sel_hi:[0,1,1]
	v_pk_fma_f32 v[28:29], v[120:121], v[210:211], v[28:29] op_sel_hi:[0,1,1]
	v_pk_fma_f32 v[14:15], v[120:121], v[212:213], v[14:15] op_sel_hi:[0,1,1]
	s_waitcnt vmcnt(44)
; #define LAS __attribute__((address_space(3)))
; __device__ __forceinline__ void p0_mod(const Args& a, LAS unsigned char* lds, int bid, int G, int tid) {
;     ...
;         for (int k = wave * 128; k < wave * 128 + 128; ++k) {
;             const float wv = wp[(size_t)k * 6144];
; #pragma unroll
;             for (int r4 = 0; r4 < 4; ++r4) { const f32x4 s = *(const LAS f32x4*)(S + k * 16 + r4 * 4);
;                 acc[r4 * 4 + 0] += s.x * wv; acc[r4 * 4 + 1] += s.y * wv; acc[r4 * 4 + 2] += s.z * wv; acc[r4 * 4 + 3] += s.w * wv; }
;         }
	v_pk_fma_f32 v[16:17], v[120:121], v[214:215], v[16:17] op_sel:[1,0,0] op_sel_hi:[1,1,1]
	v_pk_fma_f32 v[18:19], v[120:121], v[216:217], v[18:19] op_sel:[1,0,0] op_sel_hi:[1,1,1]
	v_pk_fma_f32 v[20:21], v[120:121], v[218:219], v[20:21] op_sel:[1,0,0] op_sel_hi:[1,1,1]
	v_pk_fma_f32 v[22:23], v[120:121], v[220:221], v[22:23] op_sel:[1,0,0] op_sel_hi:[1,1,1]
	v_pk_fma_f32 v[24:25], v[120:121], v[222:223], v[24:25] op_sel:[1,0,0] op_sel_hi:[1,1,1]
	v_pk_fma_f32 v[26:27], v[120:121], v[224:225], v[26:27] op_sel:[1,0,0] op_sel_hi:[1,1,1]
	v_pk_fma_f32 v[28:29], v[120:121], v[226:227], v[28:29] op_sel:[1,0,0] op_sel_hi:[1,1,1]
	v_pk_fma_f32 v[14:15], v[120:121], v[228:229], v[14:15] op_sel:[1,0,0] op_sel_hi:[1,1,1]
	ds_read_b128 v[198:201], v10 offset:5504
	ds_read_b128 v[202:205], v10 offset:5520
	ds_read_b128 v[206:209], v10 offset:5536
	ds_read_b128 v[210:213], v10 offset:5552
	ds_read_b128 v[214:217], v10 offset:5568
	ds_read_b128 v[218:221], v10 offset:5584
	ds_read_b128 v[222:225], v10 offset:5600
	ds_read_b128 v[226:229], v10 offset:5616
	s_waitcnt vmcnt(43) lgkmcnt(8)
	v_pk_fma_f32 v[16:17], v[122:123], v[166:167], v[16:17] op_sel_hi:[0,1,1]
	v_pk_fma_f32 v[18:19], v[122:123], v[168:169], v[18:19] op_sel_hi:[0,1,1]
	v_pk_fma_f32 v[20:21], v[122:123], v[170:171], v[20:21] op_sel_hi:[0,1,1]
	v_pk_fma_f32 v[22:23], v[122:123], v[172:173], v[22:23] op_sel_hi:[0,1,1]
	v_pk_fma_f32 v[24:25], v[122:123], v[174:175], v[24:25] op_sel_hi:[0,1,1]
	v_pk_fma_f32 v[26:27], v[122:123], v[176:177], v[26:27] op_sel_hi:[0,1,1]
	v_pk_fma_f32 v[28:29], v[122:123], v[178:179], v[28:29] op_sel_hi:[0,1,1]
	v_pk_fma_f32 v[14:15], v[122:123], v[180:181], v[14:15] op_sel_hi:[0,1,1]
	s_waitcnt vmcnt(42)
	v_pk_fma_f32 v[16:17], v[122:123], v[182:183], v[16:17] op_sel:[1,0,0] op_sel_hi:[1,1,1]
	v_pk_fma_f32 v[18:19], v[122:123], v[184:185], v[18:19] op_sel:[1,0,0] op_sel_hi:[1,1,1]
	v_pk_fma_f32 v[20:21], v[122:123], v[186:187], v[20:21] op_sel:[1,0,0] op_sel_hi:[1,1,1]
	v_pk_fma_f32 v[22:23], v[122:123], v[188:189], v[22:23] op_sel:[1,0,0] op_sel_hi:[1,1,1]
	v_pk_fma_f32 v[24:25], v[122:123], v[190:191], v[24:25] op_sel:[1,0,0] op_sel_hi:[1,1,1]
	v_pk_fma_f32 v[26:27], v[122:123], v[192:193], v[26:27] op_sel:[1,0,0] op_sel_hi:[1,1,1]
	v_pk_fma_f32 v[28:29], v[122:123], v[194:195], v[28:29] op_sel:[1,0,0] op_sel_hi:[1,1,1]
	v_pk_fma_f32 v[14:15], v[122:123], v[196:197], v[14:15] op_sel:[1,0,0] op_sel_hi:[1,1,1]
	ds_read_b128 v[166:169], v10 offset:5632
	ds_read_b128 v[170:173], v10 offset:5648
	ds_read_b128 v[174:177], v10 offset:5664
	ds_read_b128 v[178:181], v10 offset:5680
	ds_read_b128 v[182:185], v10 offset:5696
	ds_read_b128 v[186:189], v10 offset:5712
	ds_read_b128 v[190:193], v10 offset:5728
	ds_read_b128 v[194:197], v10 offset:5744
	s_waitcnt vmcnt(41) lgkmcnt(8)
	v_pk_fma_f32 v[16:17], v[124:125], v[198:199], v[16:17] op_sel_hi:[0,1,1]
	v_pk_fma_f32 v[18:19], v[124:125], v[200:201], v[18:19] op_sel_hi:[0,1,1]
	v_pk_fma_f32 v[20:21], v[124:125], v[202:203], v[20:21] op_sel_hi:[0,1,1]
	v_pk_fma_f32 v[22:23], v[124:125], v[204:205], v[22:23] op_sel_hi:[0,1,1]
	v_pk_fma_f32 v[24:25], v[124:125], v[206:207], v[24:25] op_sel_hi:[0,1,1]
	v_pk_fma_f32 v[26:27], v[124:125], v[208:209], v[26:27] op_sel_hi:[0,1,1]
	v_pk_fma_f32 v[28:29], v[124:125], v[210:211], v[28:29] op_sel_hi:[0,1,1]
	v_pk_fma_f32 v[14:15], v[124:125], v[212:213], v[14:15] op_sel_hi:[0,1,1]
	s_waitcnt vmcnt(40)
	v_pk_fma_f32 v[16:17], v[124:125], v[214:215], v[16:17] op_sel:[1,0,0] op_sel_hi:[1,1,1]
	v_pk_fma_f32 v[18:19], v[124:125], v[216:217], v[18:19] op_sel:[1,0,0] op_sel_hi:[1,1,1]
	v_pk_fma_f32 v[20:21], v[124:125], v[218:219], v[20:21] op_sel:[1,0,0] op_sel_hi:[1,1,1]
	v_pk_fma_f32 v[22:23], v[124:125], v[220:221], v[22:23] op_sel:[1,0,0] op_sel_hi:[1,1,1]
	v_pk_fma_f32 v[24:25], v[124:125], v[222:223], v[24:25] op_sel:[1,0,0] op_sel_hi:[1,1,1]
	v_pk_fma_f32 v[26:27], v[124:125], v[224:225], v[26:27] op_sel:[1,0,0] op_sel_hi:[1,1,1]
	v_pk_fma_f32 v[28:29], v[124:125], v[226:227], v[28:29] op_sel:[1,0,0] op_sel_hi:[1,1,1]
	v_pk_fma_f32 v[14:15], v[124:125], v[228:229], v[14:15] op_sel:[1,0,0] op_sel_hi:[1,1,1]
	ds_read_b128 v[198:201], v10 offset:5760
	ds_read_b128 v[202:205], v10 offset:5776
	ds_read_b128 v[206:209], v10 offset:5792
	ds_read_b128 v[210:213], v10 offset:5808
	ds_read_b128 v[214:217], v10 offset:5824
	ds_read_b128 v[218:221], v10 offset:5840
	ds_read_b128 v[222:225], v10 offset:5856
	ds_read_b128 v[226:229], v10 offset:5872
	s_waitcnt vmcnt(39) lgkmcnt(8)
	v_pk_fma_f32 v[16:17], v[126:127], v[166:167], v[16:17] op_sel_hi:[0,1,1]
	v_pk_fma_f32 v[18:19], v[126:127], v[168:169], v[18:19] op_sel_hi:[0,1,1]
	v_pk_fma_f32 v[20:21], v[126:127], v[170:171], v[20:21] op_sel_hi:[0,1,1]
	v_pk_fma_f32 v[22:23], v[126:127], v[172:173], v[22:23] op_sel_hi:[0,1,1]
	v_pk_fma_f32 v[24:25], v[126:127], v[174:175], v[24:25] op_sel_hi:[0,1,1]
	v_pk_fma_f32 v[26:27], v[126:127], v[176:177], v[26:27] op_sel_hi:[0,1,1]
	v_pk_fma_f32 v[28:29], v[126:127], v[178:179], v[28:29] op_sel_hi:[0,1,1]
	v_pk_fma_f32 v[14:15], v[126:127], v[180:181], v[14:15] op_sel_hi:[0,1,1]
	s_waitcnt vmcnt(38)
; #define LAS __attribute__((address_space(3)))
; __device__ __forceinline__ void p0_mod(const Args& a, LAS unsigned char* lds, int bid, int G, int tid) {
;     ...
;         for (int k = wave * 128; k < wave * 128 + 128; ++k) {
;             const float wv = wp[(size_t)k * 6144];
; #pragma unroll
;             for (int r4 = 0; r4 < 4; ++r4) { const f32x4 s = *(const LAS f32x4*)(S + k * 16 + r4 * 4);
;                 acc[r4 * 4 + 0] += s.x * wv; acc[r4 * 4 + 1] += s.y * wv; acc[r4 * 4 + 2] += s.z * wv; acc[r4 * 4 + 3] += s.w * wv; }
;         }
	v_pk_fma_f32 v[16:17], v[126:127], v[182:183], v[16:17] op_sel:[1,0,0] op_sel_hi:[1,1,1]
	v_pk_fma_f32 v[18:19], v[126:127], v[184:185], v[18:19] op_sel:[1,0,0] op_sel_hi:[1,1,1]
	v_pk_fma_f32 v[20:21], v[126:127], v[186:187], v[20:21] op_sel:[1,0,0] op_sel_hi:[1,1,1]
	v_pk_fma_f32 v[22:23], v[126:127], v[188:189], v[22:23] op_sel:[1,0,0] op_sel_hi:[1,1,1]
	v_pk_fma_f32 v[24:25], v[126:127], v[190:191], v[24:25] op_sel:[1,0,0] op_sel_hi:[1,1,1]
	v_pk_fma_f32 v[26:27], v[126:127], v[192:193], v[26:27] op_sel:[1,0,0] op_sel_hi:[1,1,1]
	v_pk_fma_f32 v[28:29], v[126:127], v[194:195], v[28:29] op_sel:[1,0,0] op_sel_hi:[1,1,1]
	v_pk_fma_f32 v[14:15], v[126:127], v[196:197], v[14:15] op_sel:[1,0,0] op_sel_hi:[1,1,1]
	ds_read_b128 v[166:169], v10 offset:5888
	ds_read_b128 v[170:173], v10 offset:5904
	ds_read_b128 v[174:177], v10 offset:5920
	ds_read_b128 v[178:181], v10 offset:5936
	ds_read_b128 v[182:185], v10 offset:5952
	ds_read_b128 v[186:189], v10 offset:5968
	ds_read_b128 v[190:193], v10 offset:5984
	ds_read_b128 v[194:197], v10 offset:6000
	s_waitcnt vmcnt(37) lgkmcnt(8)
	v_pk_fma_f32 v[16:17], v[128:129], v[198:199], v[16:17] op_sel_hi:[0,1,1]
	v_pk_fma_f32 v[18:19], v[128:129], v[200:201], v[18:19] op_sel_hi:[0,1,1]
	v_pk_fma_f32 v[20:21], v[128:129], v[202:203], v[20:21] op_sel_hi:[0,1,1]
	v_pk_fma_f32 v[22:23], v[128:129], v[204:205], v[22:23] op_sel_hi:[0,1,1]
	v_pk_fma_f32 v[24:25], v[128:129], v[206:207], v[24:25] op_sel_hi:[0,1,1]
	v_pk_fma_f32 v[26:27], v[128:129], v[208:209], v[26:27] op_sel_hi:[0,1,1]
	v_pk_fma_f32 v[28:29], v[128:129], v[210:211], v[28:29] op_sel_hi:[0,1,1]
	v_pk_fma_f32 v[14:15], v[128:129], v[212:213], v[14:15] op_sel_hi:[0,1,1]
	s_waitcnt vmcnt(36)
	v_pk_fma_f32 v[16:17], v[128:129], v[214:215], v[16:17] op_sel:[1,0,0] op_sel_hi:[1,1,1]
	v_pk_fma_f32 v[18:19], v[128:129], v[216:217], v[18:19] op_sel:[1,0,0] op_sel_hi:[1,1,1]
	v_pk_fma_f32 v[20:21], v[128:129], v[218:219], v[20:21] op_sel:[1,0,0] op_sel_hi:[1,1,1]
	v_pk_fma_f32 v[22:23], v[128:129], v[220:221], v[22:23] op_sel:[1,0,0] op_sel_hi:[1,1,1]
	v_pk_fma_f32 v[24:25], v[128:129], v[222:223], v[24:25] op_sel:[1,0,0] op_sel_hi:[1,1,1]
	v_pk_fma_f32 v[26:27], v[128:129], v[224:225], v[26:27] op_sel:[1,0,0] op_sel_hi:[1,1,1]
	v_pk_fma_f32 v[28:29], v[128:129], v[226:227], v[28:29] op_sel:[1,0,0] op_sel_hi:[1,1,1]
	v_pk_fma_f32 v[14:15], v[128:129], v[228:229], v[14:15] op_sel:[1,0,0] op_sel_hi:[1,1,1]
	ds_read_b128 v[198:201], v10 offset:6016
	ds_read_b128 v[202:205], v10 offset:6032
	ds_read_b128 v[206:209], v10 offset:6048
	ds_read_b128 v[210:213], v10 offset:6064
	ds_read_b128 v[214:217], v10 offset:6080
	ds_read_b128 v[218:221], v10 offset:6096
	ds_read_b128 v[222:225], v10 offset:6112
	ds_read_b128 v[226:229], v10 offset:6128
	s_waitcnt vmcnt(35) lgkmcnt(8)
	v_pk_fma_f32 v[16:17], v[130:131], v[166:167], v[16:17] op_sel_hi:[0,1,1]
	v_pk_fma_f32 v[18:19], v[130:131], v[168:169], v[18:19] op_sel_hi:[0,1,1]
	v_pk_fma_f32 v[20:21], v[130:131], v[170:171], v[20:21] op_sel_hi:[0,1,1]
	v_pk_fma_f32 v[22:23], v[130:131], v[172:173], v[22:23] op_sel_hi:[0,1,1]
	v_pk_fma_f32 v[24:25], v[130:131], v[174:175], v[24:25] op_sel_hi:[0,1,1]
	v_pk_fma_f32 v[26:27], v[130:131], v[176:177], v[26:27] op_sel_hi:[0,1,1]
	v_pk_fma_f32 v[28:29], v[130:131], v[178:179], v[28:29] op_sel_hi:[0,1,1]
	v_pk_fma_f32 v[14:15], v[130:131], v[180:181], v[14:15] op_sel_hi:[0,1,1]
	s_waitcnt vmcnt(34)
	v_pk_fma_f32 v[16:17], v[130:131], v[182:183], v[16:17] op_sel:[1,0,0] op_sel_hi:[1,1,1]
	v_pk_fma_f32 v[18:19], v[130:131], v[184:185], v[18:19] op_sel:[1,0,0] op_sel_hi:[1,1,1]
	v_pk_fma_f32 v[20:21], v[130:131], v[186:187], v[20:21] op_sel:[1,0,0] op_sel_hi:[1,1,1]
	v_pk_fma_f32 v[22:23], v[130:131], v[188:189], v[22:23] op_sel:[1,0,0] op_sel_hi:[1,1,1]
	v_pk_fma_f32 v[24:25], v[130:131], v[190:191], v[24:25] op_sel:[1,0,0] op_sel_hi:[1,1,1]
	v_pk_fma_f32 v[26:27], v[130:131], v[192:193], v[26:27] op_sel:[1,0,0] op_sel_hi:[1,1,1]
	v_pk_fma_f32 v[28:29], v[130:131], v[194:195], v[28:29] op_sel:[1,0,0] op_sel_hi:[1,1,1]
	v_pk_fma_f32 v[14:15], v[130:131], v[196:197], v[14:15] op_sel:[1,0,0] op_sel_hi:[1,1,1]
	ds_read_b128 v[166:169], v10 offset:6144
	ds_read_b128 v[170:173], v10 offset:6160
	ds_read_b128 v[174:177], v10 offset:6176
	ds_read_b128 v[178:181], v10 offset:6192
	ds_read_b128 v[182:185], v10 offset:6208
	ds_read_b128 v[186:189], v10 offset:6224
	ds_read_b128 v[190:193], v10 offset:6240
	ds_read_b128 v[194:197], v10 offset:6256
	s_waitcnt vmcnt(33) lgkmcnt(8)
	v_pk_fma_f32 v[16:17], v[132:133], v[198:199], v[16:17] op_sel_hi:[0,1,1]
	v_pk_fma_f32 v[18:19], v[132:133], v[200:201], v[18:19] op_sel_hi:[0,1,1]
	v_pk_fma_f32 v[20:21], v[132:133], v[202:203], v[20:21] op_sel_hi:[0,1,1]
	v_pk_fma_f32 v[22:23], v[132:133], v[204:205], v[22:23] op_sel_hi:[0,1,1]
	v_pk_fma_f32 v[24:25], v[132:133], v[206:207], v[24:25] op_sel_hi:[0,1,1]
	v_pk_fma_f32 v[26:27], v[132:133], v[208:209], v[26:27] op_sel_hi:[0,1,1]
	v_pk_fma_f32 v[28:29], v[132:133], v[210:211], v[28:29] op_sel_hi:[0,1,1]
	v_pk_fma_f32 v[14:15], v[132:133], v[212:213], v[14:15] op_sel_hi:[0,1,1]
	s_waitcnt vmcnt(32)
; #define LAS __attribute__((address_space(3)))
; __device__ __forceinline__ void p0_mod(const Args& a, LAS unsigned char* lds, int bid, int G, int tid) {
;     ...
;         for (int k = wave * 128; k < wave * 128 + 128; ++k) {
;             const float wv = wp[(size_t)k * 6144];
; #pragma unroll
;             for (int r4 = 0; r4 < 4; ++r4) { const f32x4 s = *(const LAS f32x4*)(S + k * 16 + r4 * 4);
;                 acc[r4 * 4 + 0] += s.x * wv; acc[r4 * 4 + 1] += s.y * wv; acc[r4 * 4 + 2] += s.z * wv; acc[r4 * 4 + 3] += s.w * wv; }
;         }
	v_pk_fma_f32 v[16:17], v[132:133], v[214:215], v[16:17] op_sel:[1,0,0] op_sel_hi:[1,1,1]
	v_pk_fma_f32 v[18:19], v[132:133], v[216:217], v[18:19] op_sel:[1,0,0] op_sel_hi:[1,1,1]
	v_pk_fma_f32 v[20:21], v[132:133], v[218:219], v[20:21] op_sel:[1,0,0] op_sel_hi:[1,1,1]
	v_pk_fma_f32 v[22:23], v[132:133], v[220:221], v[22:23] op_sel:[1,0,0] op_sel_hi:[1,1,1]
	v_pk_fma_f32 v[24:25], v[132:133], v[222:223], v[24:25] op_sel:[1,0,0] op_sel_hi:[1,1,1]
	v_pk_fma_f32 v[26:27], v[132:133], v[224:225], v[26:27] op_sel:[1,0,0] op_sel_hi:[1,1,1]
	v_pk_fma_f32 v[28:29], v[132:133], v[226:227], v[28:29] op_sel:[1,0,0] op_sel_hi:[1,1,1]
	v_pk_fma_f32 v[14:15], v[132:133], v[228:229], v[14:15] op_sel:[1,0,0] op_sel_hi:[1,1,1]
	ds_read_b128 v[198:201], v10 offset:6272
	ds_read_b128 v[202:205], v10 offset:6288
	ds_read_b128 v[206:209], v10 offset:6304
	ds_read_b128 v[210:213], v10 offset:6320
	ds_read_b128 v[214:217], v10 offset:6336
	ds_read_b128 v[218:221], v10 offset:6352
	ds_read_b128 v[222:225], v10 offset:6368
	ds_read_b128 v[226:229], v10 offset:6384
	s_waitcnt vmcnt(31) lgkmcnt(8)
	v_pk_fma_f32 v[16:17], v[134:135], v[166:167], v[16:17] op_sel_hi:[0,1,1]
	v_pk_fma_f32 v[18:19], v[134:135], v[168:169], v[18:19] op_sel_hi:[0,1,1]
	v_pk_fma_f32 v[20:21], v[134:135], v[170:171], v[20:21] op_sel_hi:[0,1,1]
	v_pk_fma_f32 v[22:23], v[134:135], v[172:173], v[22:23] op_sel_hi:[0,1,1]
	v_pk_fma_f32 v[24:25], v[134:135], v[174:175], v[24:25] op_sel_hi:[0,1,1]
	v_pk_fma_f32 v[26:27], v[134:135], v[176:177], v[26:27] op_sel_hi:[0,1,1]
	v_pk_fma_f32 v[28:29], v[134:135], v[178:179], v[28:29] op_sel_hi:[0,1,1]
	v_pk_fma_f32 v[14:15], v[134:135], v[180:181], v[14:15] op_sel_hi:[0,1,1]
	s_waitcnt vmcnt(30)
	v_pk_fma_f32 v[16:17], v[134:135], v[182:183], v[16:17] op_sel:[1,0,0] op_sel_hi:[1,1,1]
	v_pk_fma_f32 v[18:19], v[134:135], v[184:185], v[18:19] op_sel:[1,0,0] op_sel_hi:[1,1,1]
	v_pk_fma_f32 v[20:21], v[134:135], v[186:187], v[20:21] op_sel:[1,0,0] op_sel_hi:[1,1,1]
	v_pk_fma_f32 v[22:23], v[134:135], v[188:189], v[22:23] op_sel:[1,0,0] op_sel_hi:[1,1,1]
	v_pk_fma_f32 v[24:25], v[134:135], v[190:191], v[24:25] op_sel:[1,0,0] op_sel_hi:[1,1,1]
	v_pk_fma_f32 v[26:27], v[134:135], v[192:193], v[26:27] op_sel:[1,0,0] op_sel_hi:[1,1,1]
	v_pk_fma_f32 v[28:29], v[134:135], v[194:195], v[28:29] op_sel:[1,0,0] op_sel_hi:[1,1,1]
	v_pk_fma_f32 v[14:15], v[134:135], v[196:197], v[14:15] op_sel:[1,0,0] op_sel_hi:[1,1,1]
	ds_read_b128 v[166:169], v10 offset:6400
	ds_read_b128 v[170:173], v10 offset:6416
	ds_read_b128 v[174:177], v10 offset:6432
	ds_read_b128 v[178:181], v10 offset:6448
	ds_read_b128 v[182:185], v10 offset:6464
	ds_read_b128 v[186:189], v10 offset:6480
	ds_read_b128 v[190:193], v10 offset:6496
	ds_read_b128 v[194:197], v10 offset:6512
	s_waitcnt vmcnt(29) lgkmcnt(8)
	v_pk_fma_f32 v[16:17], v[136:137], v[198:199], v[16:17] op_sel_hi:[0,1,1]
	v_pk_fma_f32 v[18:19], v[136:137], v[200:201], v[18:19] op_sel_hi:[0,1,1]
	v_pk_fma_f32 v[20:21], v[136:137], v[202:203], v[20:21] op_sel_hi:[0,1,1]
	v_pk_fma_f32 v[22:23], v[136:137], v[204:205], v[22:23] op_sel_hi:[0,1,1]
	v_pk_fma_f32 v[24:25], v[136:137], v[206:207], v[24:25] op_sel_hi:[0,1,1]
	v_pk_fma_f32 v[26:27], v[136:137], v[208:209], v[26:27] op_sel_hi:[0,1,1]
	v_pk_fma_f32 v[28:29], v[136:137], v[210:211], v[28:29] op_sel_hi:[0,1,1]
	v_pk_fma_f32 v[14:15], v[136:137], v[212:213], v[14:15] op_sel_hi:[0,1,1]
	s_waitcnt vmcnt(28)
	v_pk_fma_f32 v[16:17], v[136:137], v[214:215], v[16:17] op_sel:[1,0,0] op_sel_hi:[1,1,1]
	v_pk_fma_f32 v[18:19], v[136:137], v[216:217], v[18:19] op_sel:[1,0,0] op_sel_hi:[1,1,1]
	v_pk_fma_f32 v[20:21], v[136:137], v[218:219], v[20:21] op_sel:[1,0,0] op_sel_hi:[1,1,1]
	v_pk_fma_f32 v[22:23], v[136:137], v[220:221], v[22:23] op_sel:[1,0,0] op_sel_hi:[1,1,1]
	v_pk_fma_f32 v[24:25], v[136:137], v[222:223], v[24:25] op_sel:[1,0,0] op_sel_hi:[1,1,1]
	v_pk_fma_f32 v[26:27], v[136:137], v[224:225], v[26:27] op_sel:[1,0,0] op_sel_hi:[1,1,1]
	v_pk_fma_f32 v[28:29], v[136:137], v[226:227], v[28:29] op_sel:[1,0,0] op_sel_hi:[1,1,1]
	v_pk_fma_f32 v[14:15], v[136:137], v[228:229], v[14:15] op_sel:[1,0,0] op_sel_hi:[1,1,1]
	ds_read_b128 v[198:201], v10 offset:6528
	ds_read_b128 v[202:205], v10 offset:6544
	ds_read_b128 v[206:209], v10 offset:6560
	ds_read_b128 v[210:213], v10 offset:6576
	ds_read_b128 v[214:217], v10 offset:6592
	ds_read_b128 v[218:221], v10 offset:6608
	ds_read_b128 v[222:225], v10 offset:6624
	ds_read_b128 v[226:229], v10 offset:6640
	s_waitcnt vmcnt(27) lgkmcnt(8)
	v_pk_fma_f32 v[16:17], v[138:139], v[166:167], v[16:17] op_sel_hi:[0,1,1]
	v_pk_fma_f32 v[18:19], v[138:139], v[168:169], v[18:19] op_sel_hi:[0,1,1]
	v_pk_fma_f32 v[20:21], v[138:139], v[170:171], v[20:21] op_sel_hi:[0,1,1]
	v_pk_fma_f32 v[22:23], v[138:139], v[172:173], v[22:23] op_sel_hi:[0,1,1]
	v_pk_fma_f32 v[24:25], v[138:139], v[174:175], v[24:25] op_sel_hi:[0,1,1]
	v_pk_fma_f32 v[26:27], v[138:139], v[176:177], v[26:27] op_sel_hi:[0,1,1]
	v_pk_fma_f32 v[28:29], v[138:139], v[178:179], v[28:29] op_sel_hi:[0,1,1]
	v_pk_fma_f32 v[14:15], v[138:139], v[180:181], v[14:15] op_sel_hi:[0,1,1]
	s_waitcnt vmcnt(26)
; #define LAS __attribute__((address_space(3)))
; __device__ __forceinline__ void p0_mod(const Args& a, LAS unsigned char* lds, int bid, int G, int tid) {
;     ...
;         for (int k = wave * 128; k < wave * 128 + 128; ++k) {
;             const float wv = wp[(size_t)k * 6144];
; #pragma unroll
;             for (int r4 = 0; r4 < 4; ++r4) { const f32x4 s = *(const LAS f32x4*)(S + k * 16 + r4 * 4);
;                 acc[r4 * 4 + 0] += s.x * wv; acc[r4 * 4 + 1] += s.y * wv; acc[r4 * 4 + 2] += s.z * wv; acc[r4 * 4 + 3] += s.w * wv; }
;         }
	v_pk_fma_f32 v[16:17], v[138:139], v[182:183], v[16:17] op_sel:[1,0,0] op_sel_hi:[1,1,1]
	v_pk_fma_f32 v[18:19], v[138:139], v[184:185], v[18:19] op_sel:[1,0,0] op_sel_hi:[1,1,1]
	v_pk_fma_f32 v[20:21], v[138:139], v[186:187], v[20:21] op_sel:[1,0,0] op_sel_hi:[1,1,1]
	v_pk_fma_f32 v[22:23], v[138:139], v[188:189], v[22:23] op_sel:[1,0,0] op_sel_hi:[1,1,1]
	v_pk_fma_f32 v[24:25], v[138:139], v[190:191], v[24:25] op_sel:[1,0,0] op_sel_hi:[1,1,1]
	v_pk_fma_f32 v[26:27], v[138:139], v[192:193], v[26:27] op_sel:[1,0,0] op_sel_hi:[1,1,1]
	v_pk_fma_f32 v[28:29], v[138:139], v[194:195], v[28:29] op_sel:[1,0,0] op_sel_hi:[1,1,1]
	v_pk_fma_f32 v[14:15], v[138:139], v[196:197], v[14:15] op_sel:[1,0,0] op_sel_hi:[1,1,1]
	ds_read_b128 v[166:169], v10 offset:6656
	ds_read_b128 v[170:173], v10 offset:6672
	ds_read_b128 v[174:177], v10 offset:6688
	ds_read_b128 v[178:181], v10 offset:6704
	ds_read_b128 v[182:185], v10 offset:6720
	ds_read_b128 v[186:189], v10 offset:6736
	ds_read_b128 v[190:193], v10 offset:6752
	ds_read_b128 v[194:197], v10 offset:6768
	s_waitcnt vmcnt(25) lgkmcnt(8)
	v_pk_fma_f32 v[16:17], v[140:141], v[198:199], v[16:17] op_sel_hi:[0,1,1]
	v_pk_fma_f32 v[18:19], v[140:141], v[200:201], v[18:19] op_sel_hi:[0,1,1]
	v_pk_fma_f32 v[20:21], v[140:141], v[202:203], v[20:21] op_sel_hi:[0,1,1]
	v_pk_fma_f32 v[22:23], v[140:141], v[204:205], v[22:23] op_sel_hi:[0,1,1]
	v_pk_fma_f32 v[24:25], v[140:141], v[206:207], v[24:25] op_sel_hi:[0,1,1]
	v_pk_fma_f32 v[26:27], v[140:141], v[208:209], v[26:27] op_sel_hi:[0,1,1]
	v_pk_fma_f32 v[28:29], v[140:141], v[210:211], v[28:29] op_sel_hi:[0,1,1]
	v_pk_fma_f32 v[14:15], v[140:141], v[212:213], v[14:15] op_sel_hi:[0,1,1]
	s_waitcnt vmcnt(24)
	v_pk_fma_f32 v[16:17], v[140:141], v[214:215], v[16:17] op_sel:[1,0,0] op_sel_hi:[1,1,1]
	v_pk_fma_f32 v[18:19], v[140:141], v[216:217], v[18:19] op_sel:[1,0,0] op_sel_hi:[1,1,1]
	v_pk_fma_f32 v[20:21], v[140:141], v[218:219], v[20:21] op_sel:[1,0,0] op_sel_hi:[1,1,1]
	v_pk_fma_f32 v[22:23], v[140:141], v[220:221], v[22:23] op_sel:[1,0,0] op_sel_hi:[1,1,1]
	v_pk_fma_f32 v[24:25], v[140:141], v[222:223], v[24:25] op_sel:[1,0,0] op_sel_hi:[1,1,1]
	v_pk_fma_f32 v[26:27], v[140:141], v[224:225], v[26:27] op_sel:[1,0,0] op_sel_hi:[1,1,1]
	v_pk_fma_f32 v[28:29], v[140:141], v[226:227], v[28:29] op_sel:[1,0,0] op_sel_hi:[1,1,1]
	v_pk_fma_f32 v[14:15], v[140:141], v[228:229], v[14:15] op_sel:[1,0,0] op_sel_hi:[1,1,1]
	ds_read_b128 v[198:201], v10 offset:6784
	ds_read_b128 v[202:205], v10 offset:6800
	ds_read_b128 v[206:209], v10 offset:6816
	ds_read_b128 v[210:213], v10 offset:6832
	ds_read_b128 v[214:217], v10 offset:6848
	ds_read_b128 v[218:221], v10 offset:6864
	ds_read_b128 v[222:225], v10 offset:6880
	ds_read_b128 v[226:229], v10 offset:6896
	s_waitcnt vmcnt(23) lgkmcnt(8)
	v_pk_fma_f32 v[16:17], v[142:143], v[166:167], v[16:17] op_sel_hi:[0,1,1]
	v_pk_fma_f32 v[18:19], v[142:143], v[168:169], v[18:19] op_sel_hi:[0,1,1]
	v_pk_fma_f32 v[20:21], v[142:143], v[170:171], v[20:21] op_sel_hi:[0,1,1]
	v_pk_fma_f32 v[22:23], v[142:143], v[172:173], v[22:23] op_sel_hi:[0,1,1]
	v_pk_fma_f32 v[24:25], v[142:143], v[174:175], v[24:25] op_sel_hi:[0,1,1]
	v_pk_fma_f32 v[26:27], v[142:143], v[176:177], v[26:27] op_sel_hi:[0,1,1]
	v_pk_fma_f32 v[28:29], v[142:143], v[178:179], v[28:29] op_sel_hi:[0,1,1]
	v_pk_fma_f32 v[14:15], v[142:143], v[180:181], v[14:15] op_sel_hi:[0,1,1]
	s_waitcnt vmcnt(22)
	v_pk_fma_f32 v[16:17], v[142:143], v[182:183], v[16:17] op_sel:[1,0,0] op_sel_hi:[1,1,1]
	v_pk_fma_f32 v[18:19], v[142:143], v[184:185], v[18:19] op_sel:[1,0,0] op_sel_hi:[1,1,1]
	v_pk_fma_f32 v[20:21], v[142:143], v[186:187], v[20:21] op_sel:[1,0,0] op_sel_hi:[1,1,1]
	v_pk_fma_f32 v[22:23], v[142:143], v[188:189], v[22:23] op_sel:[1,0,0] op_sel_hi:[1,1,1]
	v_pk_fma_f32 v[24:25], v[142:143], v[190:191], v[24:25] op_sel:[1,0,0] op_sel_hi:[1,1,1]
	v_pk_fma_f32 v[26:27], v[142:143], v[192:193], v[26:27] op_sel:[1,0,0] op_sel_hi:[1,1,1]
	v_pk_fma_f32 v[28:29], v[142:143], v[194:195], v[28:29] op_sel:[1,0,0] op_sel_hi:[1,1,1]
	v_pk_fma_f32 v[14:15], v[142:143], v[196:197], v[14:15] op_sel:[1,0,0] op_sel_hi:[1,1,1]
	ds_read_b128 v[166:169], v10 offset:6912
	ds_read_b128 v[170:173], v10 offset:6928
	ds_read_b128 v[174:177], v10 offset:6944
	ds_read_b128 v[178:181], v10 offset:6960
	ds_read_b128 v[182:185], v10 offset:6976
	ds_read_b128 v[186:189], v10 offset:6992
	ds_read_b128 v[190:193], v10 offset:7008
	ds_read_b128 v[194:197], v10 offset:7024
	s_waitcnt vmcnt(21) lgkmcnt(8)
	v_pk_fma_f32 v[16:17], v[144:145], v[198:199], v[16:17] op_sel_hi:[0,1,1]
	v_pk_fma_f32 v[18:19], v[144:145], v[200:201], v[18:19] op_sel_hi:[0,1,1]
	v_pk_fma_f32 v[20:21], v[144:145], v[202:203], v[20:21] op_sel_hi:[0,1,1]
	v_pk_fma_f32 v[22:23], v[144:145], v[204:205], v[22:23] op_sel_hi:[0,1,1]
	v_pk_fma_f32 v[24:25], v[144:145], v[206:207], v[24:25] op_sel_hi:[0,1,1]
	v_pk_fma_f32 v[26:27], v[144:145], v[208:209], v[26:27] op_sel_hi:[0,1,1]
	v_pk_fma_f32 v[28:29], v[144:145], v[210:211], v[28:29] op_sel_hi:[0,1,1]
	v_pk_fma_f32 v[14:15], v[144:145], v[212:213], v[14:15] op_sel_hi:[0,1,1]
	s_waitcnt vmcnt(20)
; #define LAS __attribute__((address_space(3)))
; __device__ __forceinline__ void p0_mod(const Args& a, LAS unsigned char* lds, int bid, int G, int tid) {
;     ...
;         for (int k = wave * 128; k < wave * 128 + 128; ++k) {
;             const float wv = wp[(size_t)k * 6144];
; #pragma unroll
;             for (int r4 = 0; r4 < 4; ++r4) { const f32x4 s = *(const LAS f32x4*)(S + k * 16 + r4 * 4);
;                 acc[r4 * 4 + 0] += s.x * wv; acc[r4 * 4 + 1] += s.y * wv; acc[r4 * 4 + 2] += s.z * wv; acc[r4 * 4 + 3] += s.w * wv; }
;         }
	v_pk_fma_f32 v[16:17], v[144:145], v[214:215], v[16:17] op_sel:[1,0,0] op_sel_hi:[1,1,1]
	v_pk_fma_f32 v[18:19], v[144:145], v[216:217], v[18:19] op_sel:[1,0,0] op_sel_hi:[1,1,1]
	v_pk_fma_f32 v[20:21], v[144:145], v[218:219], v[20:21] op_sel:[1,0,0] op_sel_hi:[1,1,1]
	v_pk_fma_f32 v[22:23], v[144:145], v[220:221], v[22:23] op_sel:[1,0,0] op_sel_hi:[1,1,1]
	v_pk_fma_f32 v[24:25], v[144:145], v[222:223], v[24:25] op_sel:[1,0,0] op_sel_hi:[1,1,1]
	v_pk_fma_f32 v[26:27], v[144:145], v[224:225], v[26:27] op_sel:[1,0,0] op_sel_hi:[1,1,1]
	v_pk_fma_f32 v[28:29], v[144:145], v[226:227], v[28:29] op_sel:[1,0,0] op_sel_hi:[1,1,1]
	v_pk_fma_f32 v[14:15], v[144:145], v[228:229], v[14:15] op_sel:[1,0,0] op_sel_hi:[1,1,1]
	ds_read_b128 v[198:201], v10 offset:7040
	ds_read_b128 v[202:205], v10 offset:7056
	ds_read_b128 v[206:209], v10 offset:7072
	ds_read_b128 v[210:213], v10 offset:7088
	ds_read_b128 v[214:217], v10 offset:7104
	ds_read_b128 v[218:221], v10 offset:7120
	ds_read_b128 v[222:225], v10 offset:7136
	ds_read_b128 v[226:229], v10 offset:7152
	s_waitcnt vmcnt(19) lgkmcnt(8)
	v_pk_fma_f32 v[16:17], v[146:147], v[166:167], v[16:17] op_sel_hi:[0,1,1]
	v_pk_fma_f32 v[18:19], v[146:147], v[168:169], v[18:19] op_sel_hi:[0,1,1]
	v_pk_fma_f32 v[20:21], v[146:147], v[170:171], v[20:21] op_sel_hi:[0,1,1]
	v_pk_fma_f32 v[22:23], v[146:147], v[172:173], v[22:23] op_sel_hi:[0,1,1]
	v_pk_fma_f32 v[24:25], v[146:147], v[174:175], v[24:25] op_sel_hi:[0,1,1]
	v_pk_fma_f32 v[26:27], v[146:147], v[176:177], v[26:27] op_sel_hi:[0,1,1]
	v_pk_fma_f32 v[28:29], v[146:147], v[178:179], v[28:29] op_sel_hi:[0,1,1]
	v_pk_fma_f32 v[14:15], v[146:147], v[180:181], v[14:15] op_sel_hi:[0,1,1]
	s_waitcnt vmcnt(18)
	v_pk_fma_f32 v[16:17], v[146:147], v[182:183], v[16:17] op_sel:[1,0,0] op_sel_hi:[1,1,1]
	v_pk_fma_f32 v[18:19], v[146:147], v[184:185], v[18:19] op_sel:[1,0,0] op_sel_hi:[1,1,1]
	v_pk_fma_f32 v[20:21], v[146:147], v[186:187], v[20:21] op_sel:[1,0,0] op_sel_hi:[1,1,1]
	v_pk_fma_f32 v[22:23], v[146:147], v[188:189], v[22:23] op_sel:[1,0,0] op_sel_hi:[1,1,1]
	v_pk_fma_f32 v[24:25], v[146:147], v[190:191], v[24:25] op_sel:[1,0,0] op_sel_hi:[1,1,1]
	v_pk_fma_f32 v[26:27], v[146:147], v[192:193], v[26:27] op_sel:[1,0,0] op_sel_hi:[1,1,1]
	v_pk_fma_f32 v[28:29], v[146:147], v[194:195], v[28:29] op_sel:[1,0,0] op_sel_hi:[1,1,1]
	v_pk_fma_f32 v[14:15], v[146:147], v[196:197], v[14:15] op_sel:[1,0,0] op_sel_hi:[1,1,1]
	ds_read_b128 v[166:169], v10 offset:7168
	ds_read_b128 v[170:173], v10 offset:7184
	ds_read_b128 v[174:177], v10 offset:7200
	ds_read_b128 v[178:181], v10 offset:7216
	ds_read_b128 v[182:185], v10 offset:7232
	ds_read_b128 v[186:189], v10 offset:7248
	ds_read_b128 v[190:193], v10 offset:7264
	ds_read_b128 v[194:197], v10 offset:7280
	s_waitcnt vmcnt(17) lgkmcnt(8)
	v_pk_fma_f32 v[16:17], v[148:149], v[198:199], v[16:17] op_sel_hi:[0,1,1]
	v_pk_fma_f32 v[18:19], v[148:149], v[200:201], v[18:19] op_sel_hi:[0,1,1]
	v_pk_fma_f32 v[20:21], v[148:149], v[202:203], v[20:21] op_sel_hi:[0,1,1]
	v_pk_fma_f32 v[22:23], v[148:149], v[204:205], v[22:23] op_sel_hi:[0,1,1]
	v_pk_fma_f32 v[24:25], v[148:149], v[206:207], v[24:25] op_sel_hi:[0,1,1]
	v_pk_fma_f32 v[26:27], v[148:149], v[208:209], v[26:27] op_sel_hi:[0,1,1]
	v_pk_fma_f32 v[28:29], v[148:149], v[210:211], v[28:29] op_sel_hi:[0,1,1]
	v_pk_fma_f32 v[14:15], v[148:149], v[212:213], v[14:15] op_sel_hi:[0,1,1]
	s_waitcnt vmcnt(16)
	v_pk_fma_f32 v[16:17], v[148:149], v[214:215], v[16:17] op_sel:[1,0,0] op_sel_hi:[1,1,1]
	v_pk_fma_f32 v[18:19], v[148:149], v[216:217], v[18:19] op_sel:[1,0,0] op_sel_hi:[1,1,1]
	v_pk_fma_f32 v[20:21], v[148:149], v[218:219], v[20:21] op_sel:[1,0,0] op_sel_hi:[1,1,1]
	v_pk_fma_f32 v[22:23], v[148:149], v[220:221], v[22:23] op_sel:[1,0,0] op_sel_hi:[1,1,1]
	v_pk_fma_f32 v[24:25], v[148:149], v[222:223], v[24:25] op_sel:[1,0,0] op_sel_hi:[1,1,1]
	v_pk_fma_f32 v[26:27], v[148:149], v[224:225], v[26:27] op_sel:[1,0,0] op_sel_hi:[1,1,1]
	v_pk_fma_f32 v[28:29], v[148:149], v[226:227], v[28:29] op_sel:[1,0,0] op_sel_hi:[1,1,1]
	v_pk_fma_f32 v[14:15], v[148:149], v[228:229], v[14:15] op_sel:[1,0,0] op_sel_hi:[1,1,1]
	ds_read_b128 v[198:201], v10 offset:7296
	ds_read_b128 v[202:205], v10 offset:7312
	ds_read_b128 v[206:209], v10 offset:7328
	ds_read_b128 v[210:213], v10 offset:7344
	ds_read_b128 v[214:217], v10 offset:7360
	ds_read_b128 v[218:221], v10 offset:7376
	ds_read_b128 v[222:225], v10 offset:7392
	ds_read_b128 v[226:229], v10 offset:7408
	s_waitcnt vmcnt(15) lgkmcnt(8)
	v_pk_fma_f32 v[16:17], v[150:151], v[166:167], v[16:17] op_sel_hi:[0,1,1]
	v_pk_fma_f32 v[18:19], v[150:151], v[168:169], v[18:19] op_sel_hi:[0,1,1]
	v_pk_fma_f32 v[20:21], v[150:151], v[170:171], v[20:21] op_sel_hi:[0,1,1]
	v_pk_fma_f32 v[22:23], v[150:151], v[172:173], v[22:23] op_sel_hi:[0,1,1]
	v_pk_fma_f32 v[24:25], v[150:151], v[174:175], v[24:25] op_sel_hi:[0,1,1]
	v_pk_fma_f32 v[26:27], v[150:151], v[176:177], v[26:27] op_sel_hi:[0,1,1]
	v_pk_fma_f32 v[28:29], v[150:151], v[178:179], v[28:29] op_sel_hi:[0,1,1]
	v_pk_fma_f32 v[14:15], v[150:151], v[180:181], v[14:15] op_sel_hi:[0,1,1]
	s_waitcnt vmcnt(14)
; #define LAS __attribute__((address_space(3)))
; __device__ __forceinline__ void p0_mod(const Args& a, LAS unsigned char* lds, int bid, int G, int tid) {
;     ...
;         for (int k = wave * 128; k < wave * 128 + 128; ++k) {
;             const float wv = wp[(size_t)k * 6144];
; #pragma unroll
;             for (int r4 = 0; r4 < 4; ++r4) { const f32x4 s = *(const LAS f32x4*)(S + k * 16 + r4 * 4);
;                 acc[r4 * 4 + 0] += s.x * wv; acc[r4 * 4 + 1] += s.y * wv; acc[r4 * 4 + 2] += s.z * wv; acc[r4 * 4 + 3] += s.w * wv; }
;         }
	v_pk_fma_f32 v[16:17], v[150:151], v[182:183], v[16:17] op_sel:[1,0,0] op_sel_hi:[1,1,1]
	v_pk_fma_f32 v[18:19], v[150:151], v[184:185], v[18:19] op_sel:[1,0,0] op_sel_hi:[1,1,1]
	v_pk_fma_f32 v[20:21], v[150:151], v[186:187], v[20:21] op_sel:[1,0,0] op_sel_hi:[1,1,1]
	v_pk_fma_f32 v[22:23], v[150:151], v[188:189], v[22:23] op_sel:[1,0,0] op_sel_hi:[1,1,1]
	v_pk_fma_f32 v[24:25], v[150:151], v[190:191], v[24:25] op_sel:[1,0,0] op_sel_hi:[1,1,1]
	v_pk_fma_f32 v[26:27], v[150:151], v[192:193], v[26:27] op_sel:[1,0,0] op_sel_hi:[1,1,1]
	v_pk_fma_f32 v[28:29], v[150:151], v[194:195], v[28:29] op_sel:[1,0,0] op_sel_hi:[1,1,1]
	v_pk_fma_f32 v[14:15], v[150:151], v[196:197], v[14:15] op_sel:[1,0,0] op_sel_hi:[1,1,1]
	ds_read_b128 v[166:169], v10 offset:7424
	ds_read_b128 v[170:173], v10 offset:7440
	ds_read_b128 v[174:177], v10 offset:7456
	ds_read_b128 v[178:181], v10 offset:7472
	ds_read_b128 v[182:185], v10 offset:7488
	ds_read_b128 v[186:189], v10 offset:7504
	ds_read_b128 v[190:193], v10 offset:7520
	ds_read_b128 v[194:197], v10 offset:7536
	s_waitcnt vmcnt(13) lgkmcnt(8)
	v_pk_fma_f32 v[16:17], v[152:153], v[198:199], v[16:17] op_sel_hi:[0,1,1]
	v_pk_fma_f32 v[18:19], v[152:153], v[200:201], v[18:19] op_sel_hi:[0,1,1]
	v_pk_fma_f32 v[20:21], v[152:153], v[202:203], v[20:21] op_sel_hi:[0,1,1]
	v_pk_fma_f32 v[22:23], v[152:153], v[204:205], v[22:23] op_sel_hi:[0,1,1]
	v_pk_fma_f32 v[24:25], v[152:153], v[206:207], v[24:25] op_sel_hi:[0,1,1]
	v_pk_fma_f32 v[26:27], v[152:153], v[208:209], v[26:27] op_sel_hi:[0,1,1]
	v_pk_fma_f32 v[28:29], v[152:153], v[210:211], v[28:29] op_sel_hi:[0,1,1]
	v_pk_fma_f32 v[14:15], v[152:153], v[212:213], v[14:15] op_sel_hi:[0,1,1]
	s_waitcnt vmcnt(12)
	v_pk_fma_f32 v[16:17], v[152:153], v[214:215], v[16:17] op_sel:[1,0,0] op_sel_hi:[1,1,1]
	v_pk_fma_f32 v[18:19], v[152:153], v[216:217], v[18:19] op_sel:[1,0,0] op_sel_hi:[1,1,1]
	v_pk_fma_f32 v[20:21], v[152:153], v[218:219], v[20:21] op_sel:[1,0,0] op_sel_hi:[1,1,1]
	v_pk_fma_f32 v[22:23], v[152:153], v[220:221], v[22:23] op_sel:[1,0,0] op_sel_hi:[1,1,1]
	v_pk_fma_f32 v[24:25], v[152:153], v[222:223], v[24:25] op_sel:[1,0,0] op_sel_hi:[1,1,1]
	v_pk_fma_f32 v[26:27], v[152:153], v[224:225], v[26:27] op_sel:[1,0,0] op_sel_hi:[1,1,1]
	v_pk_fma_f32 v[28:29], v[152:153], v[226:227], v[28:29] op_sel:[1,0,0] op_sel_hi:[1,1,1]
	v_pk_fma_f32 v[14:15], v[152:153], v[228:229], v[14:15] op_sel:[1,0,0] op_sel_hi:[1,1,1]
	ds_read_b128 v[198:201], v10 offset:7552
	ds_read_b128 v[202:205], v10 offset:7568
	ds_read_b128 v[206:209], v10 offset:7584
	ds_read_b128 v[210:213], v10 offset:7600
	ds_read_b128 v[214:217], v10 offset:7616
	ds_read_b128 v[218:221], v10 offset:7632
	ds_read_b128 v[222:225], v10 offset:7648
	ds_read_b128 v[226:229], v10 offset:7664
	s_waitcnt vmcnt(11) lgkmcnt(8)
	v_pk_fma_f32 v[16:17], v[154:155], v[166:167], v[16:17] op_sel_hi:[0,1,1]
	v_pk_fma_f32 v[18:19], v[154:155], v[168:169], v[18:19] op_sel_hi:[0,1,1]
	v_pk_fma_f32 v[20:21], v[154:155], v[170:171], v[20:21] op_sel_hi:[0,1,1]
	v_pk_fma_f32 v[22:23], v[154:155], v[172:173], v[22:23] op_sel_hi:[0,1,1]
	v_pk_fma_f32 v[24:25], v[154:155], v[174:175], v[24:25] op_sel_hi:[0,1,1]
	v_pk_fma_f32 v[26:27], v[154:155], v[176:177], v[26:27] op_sel_hi:[0,1,1]
	v_pk_fma_f32 v[28:29], v[154:155], v[178:179], v[28:29] op_sel_hi:[0,1,1]
	v_pk_fma_f32 v[14:15], v[154:155], v[180:181], v[14:15] op_sel_hi:[0,1,1]
	s_waitcnt vmcnt(10)
	v_pk_fma_f32 v[16:17], v[154:155], v[182:183], v[16:17] op_sel:[1,0,0] op_sel_hi:[1,1,1]
	v_pk_fma_f32 v[18:19], v[154:155], v[184:185], v[18:19] op_sel:[1,0,0] op_sel_hi:[1,1,1]
	v_pk_fma_f32 v[20:21], v[154:155], v[186:187], v[20:21] op_sel:[1,0,0] op_sel_hi:[1,1,1]
	v_pk_fma_f32 v[22:23], v[154:155], v[188:189], v[22:23] op_sel:[1,0,0] op_sel_hi:[1,1,1]
	v_pk_fma_f32 v[24:25], v[154:155], v[190:191], v[24:25] op_sel:[1,0,0] op_sel_hi:[1,1,1]
	v_pk_fma_f32 v[26:27], v[154:155], v[192:193], v[26:27] op_sel:[1,0,0] op_sel_hi:[1,1,1]
	v_pk_fma_f32 v[28:29], v[154:155], v[194:195], v[28:29] op_sel:[1,0,0] op_sel_hi:[1,1,1]
	v_pk_fma_f32 v[14:15], v[154:155], v[196:197], v[14:15] op_sel:[1,0,0] op_sel_hi:[1,1,1]
	ds_read_b128 v[166:169], v10 offset:7680
	ds_read_b128 v[170:173], v10 offset:7696
	ds_read_b128 v[174:177], v10 offset:7712
	ds_read_b128 v[178:181], v10 offset:7728
	ds_read_b128 v[182:185], v10 offset:7744
	ds_read_b128 v[186:189], v10 offset:7760
	ds_read_b128 v[190:193], v10 offset:7776
	ds_read_b128 v[194:197], v10 offset:7792
	s_waitcnt vmcnt(9) lgkmcnt(8)
	v_pk_fma_f32 v[16:17], v[156:157], v[198:199], v[16:17] op_sel_hi:[0,1,1]
	v_pk_fma_f32 v[18:19], v[156:157], v[200:201], v[18:19] op_sel_hi:[0,1,1]
	v_pk_fma_f32 v[20:21], v[156:157], v[202:203], v[20:21] op_sel_hi:[0,1,1]
	v_pk_fma_f32 v[22:23], v[156:157], v[204:205], v[22:23] op_sel_hi:[0,1,1]
	v_pk_fma_f32 v[24:25], v[156:157], v[206:207], v[24:25] op_sel_hi:[0,1,1]
	v_pk_fma_f32 v[26:27], v[156:157], v[208:209], v[26:27] op_sel_hi:[0,1,1]
	v_pk_fma_f32 v[28:29], v[156:157], v[210:211], v[28:29] op_sel_hi:[0,1,1]
	v_pk_fma_f32 v[14:15], v[156:157], v[212:213], v[14:15] op_sel_hi:[0,1,1]
	s_waitcnt vmcnt(8)
; #define LAS __attribute__((address_space(3)))
; __device__ __forceinline__ void p0_mod(const Args& a, LAS unsigned char* lds, int bid, int G, int tid) {
;     ...
;         for (int k = wave * 128; k < wave * 128 + 128; ++k) {
;             const float wv = wp[(size_t)k * 6144];
; #pragma unroll
;             for (int r4 = 0; r4 < 4; ++r4) { const f32x4 s = *(const LAS f32x4*)(S + k * 16 + r4 * 4);
;                 acc[r4 * 4 + 0] += s.x * wv; acc[r4 * 4 + 1] += s.y * wv; acc[r4 * 4 + 2] += s.z * wv; acc[r4 * 4 + 3] += s.w * wv; }
;         }
	v_pk_fma_f32 v[16:17], v[156:157], v[214:215], v[16:17] op_sel:[1,0,0] op_sel_hi:[1,1,1]
	v_pk_fma_f32 v[18:19], v[156:157], v[216:217], v[18:19] op_sel:[1,0,0] op_sel_hi:[1,1,1]
	v_pk_fma_f32 v[20:21], v[156:157], v[218:219], v[20:21] op_sel:[1,0,0] op_sel_hi:[1,1,1]
	v_pk_fma_f32 v[22:23], v[156:157], v[220:221], v[22:23] op_sel:[1,0,0] op_sel_hi:[1,1,1]
	v_pk_fma_f32 v[24:25], v[156:157], v[222:223], v[24:25] op_sel:[1,0,0] op_sel_hi:[1,1,1]
	v_pk_fma_f32 v[26:27], v[156:157], v[224:225], v[26:27] op_sel:[1,0,0] op_sel_hi:[1,1,1]
	v_pk_fma_f32 v[28:29], v[156:157], v[226:227], v[28:29] op_sel:[1,0,0] op_sel_hi:[1,1,1]
	v_pk_fma_f32 v[14:15], v[156:157], v[228:229], v[14:15] op_sel:[1,0,0] op_sel_hi:[1,1,1]
	ds_read_b128 v[198:201], v10 offset:7808
	ds_read_b128 v[202:205], v10 offset:7824
	ds_read_b128 v[206:209], v10 offset:7840
	ds_read_b128 v[210:213], v10 offset:7856
	ds_read_b128 v[214:217], v10 offset:7872
	ds_read_b128 v[218:221], v10 offset:7888
	ds_read_b128 v[222:225], v10 offset:7904
	ds_read_b128 v[226:229], v10 offset:7920
	s_waitcnt vmcnt(7) lgkmcnt(8)
	v_pk_fma_f32 v[16:17], v[158:159], v[166:167], v[16:17] op_sel_hi:[0,1,1]
	v_pk_fma_f32 v[18:19], v[158:159], v[168:169], v[18:19] op_sel_hi:[0,1,1]
	v_pk_fma_f32 v[20:21], v[158:159], v[170:171], v[20:21] op_sel_hi:[0,1,1]
	v_pk_fma_f32 v[22:23], v[158:159], v[172:173], v[22:23] op_sel_hi:[0,1,1]
	v_pk_fma_f32 v[24:25], v[158:159], v[174:175], v[24:25] op_sel_hi:[0,1,1]
	v_pk_fma_f32 v[26:27], v[158:159], v[176:177], v[26:27] op_sel_hi:[0,1,1]
	v_pk_fma_f32 v[28:29], v[158:159], v[178:179], v[28:29] op_sel_hi:[0,1,1]
	v_pk_fma_f32 v[14:15], v[158:159], v[180:181], v[14:15] op_sel_hi:[0,1,1]
	s_waitcnt vmcnt(6)
	v_pk_fma_f32 v[16:17], v[158:159], v[182:183], v[16:17] op_sel:[1,0,0] op_sel_hi:[1,1,1]
	v_pk_fma_f32 v[18:19], v[158:159], v[184:185], v[18:19] op_sel:[1,0,0] op_sel_hi:[1,1,1]
	v_pk_fma_f32 v[20:21], v[158:159], v[186:187], v[20:21] op_sel:[1,0,0] op_sel_hi:[1,1,1]
	v_pk_fma_f32 v[22:23], v[158:159], v[188:189], v[22:23] op_sel:[1,0,0] op_sel_hi:[1,1,1]
	v_pk_fma_f32 v[24:25], v[158:159], v[190:191], v[24:25] op_sel:[1,0,0] op_sel_hi:[1,1,1]
	v_pk_fma_f32 v[26:27], v[158:159], v[192:193], v[26:27] op_sel:[1,0,0] op_sel_hi:[1,1,1]
	v_pk_fma_f32 v[28:29], v[158:159], v[194:195], v[28:29] op_sel:[1,0,0] op_sel_hi:[1,1,1]
	v_pk_fma_f32 v[14:15], v[158:159], v[196:197], v[14:15] op_sel:[1,0,0] op_sel_hi:[1,1,1]
	ds_read_b128 v[166:169], v10 offset:7936
	ds_read_b128 v[170:173], v10 offset:7952
	ds_read_b128 v[174:177], v10 offset:7968
	ds_read_b128 v[178:181], v10 offset:7984
	ds_read_b128 v[182:185], v10 offset:8000
	ds_read_b128 v[186:189], v10 offset:8016
	ds_read_b128 v[190:193], v10 offset:8032
	ds_read_b128 v[194:197], v10 offset:8048
	s_waitcnt vmcnt(5) lgkmcnt(8)
	v_pk_fma_f32 v[16:17], v[160:161], v[198:199], v[16:17] op_sel_hi:[0,1,1]
	v_pk_fma_f32 v[18:19], v[160:161], v[200:201], v[18:19] op_sel_hi:[0,1,1]
	v_pk_fma_f32 v[20:21], v[160:161], v[202:203], v[20:21] op_sel_hi:[0,1,1]
	v_pk_fma_f32 v[22:23], v[160:161], v[204:205], v[22:23] op_sel_hi:[0,1,1]
	v_pk_fma_f32 v[24:25], v[160:161], v[206:207], v[24:25] op_sel_hi:[0,1,1]
	v_pk_fma_f32 v[26:27], v[160:161], v[208:209], v[26:27] op_sel_hi:[0,1,1]
	v_pk_fma_f32 v[28:29], v[160:161], v[210:211], v[28:29] op_sel_hi:[0,1,1]
	v_pk_fma_f32 v[14:15], v[160:161], v[212:213], v[14:15] op_sel_hi:[0,1,1]
	s_waitcnt vmcnt(4)
; #define LAS __attribute__((address_space(3)))
; __device__ __forceinline__ void p0_mod(const Args& a, LAS unsigned char* lds, int bid, int G, int tid) {
;     ...
;         for (int k = wave * 128; k < wave * 128 + 128; ++k) {
;             const float wv = wp[(size_t)k * 6144];
; #pragma unroll
;             for (int r4 = 0; r4 < 4; ++r4) { const f32x4 s = *(const LAS f32x4*)(S + k * 16 + r4 * 4);
;                 acc[r4 * 4 + 0] += s.x * wv; acc[r4 * 4 + 1] += s.y * wv; acc[r4 * 4 + 2] += s.z * wv; acc[r4 * 4 + 3] += s.w * wv; }
;         }
; #pragma unroll
;         for (int r = 0; r < 16; ++r) P[(wave * 16 + r) * 64 + lane] = acc[r];
;         __syncthreads();
;         for (int o = tid; o < 1024; o += 512) { const int r = o >> 6, col = o & 63; float s = a.in[I_ADAB][cb * 64 + col];
	v_pk_fma_f32 v[16:17], v[160:161], v[214:215], v[16:17] op_sel:[1,0,0] op_sel_hi:[1,1,1]
	v_pk_fma_f32 v[18:19], v[160:161], v[216:217], v[18:19] op_sel:[1,0,0] op_sel_hi:[1,1,1]
	v_pk_fma_f32 v[20:21], v[160:161], v[218:219], v[20:21] op_sel:[1,0,0] op_sel_hi:[1,1,1]
	v_pk_fma_f32 v[22:23], v[160:161], v[220:221], v[22:23] op_sel:[1,0,0] op_sel_hi:[1,1,1]
	v_pk_fma_f32 v[24:25], v[160:161], v[222:223], v[24:25] op_sel:[1,0,0] op_sel_hi:[1,1,1]
	v_pk_fma_f32 v[26:27], v[160:161], v[224:225], v[26:27] op_sel:[1,0,0] op_sel_hi:[1,1,1]
	v_pk_fma_f32 v[28:29], v[160:161], v[226:227], v[28:29] op_sel:[1,0,0] op_sel_hi:[1,1,1]
	v_pk_fma_f32 v[14:15], v[160:161], v[228:229], v[14:15] op_sel:[1,0,0] op_sel_hi:[1,1,1]
	ds_read_b128 v[198:201], v10 offset:8064
	ds_read_b128 v[202:205], v10 offset:8080
	ds_read_b128 v[206:209], v10 offset:8096
	ds_read_b128 v[210:213], v10 offset:8112
	ds_read_b128 v[214:217], v10 offset:8128
	ds_read_b128 v[218:221], v10 offset:8144
	ds_read_b128 v[222:225], v10 offset:8160
	ds_read_b128 v[226:229], v10 offset:8176
	s_waitcnt vmcnt(3) lgkmcnt(8)
	v_pk_fma_f32 v[16:17], v[162:163], v[166:167], v[16:17] op_sel_hi:[0,1,1]
	v_pk_fma_f32 v[18:19], v[162:163], v[168:169], v[18:19] op_sel_hi:[0,1,1]
	v_pk_fma_f32 v[20:21], v[162:163], v[170:171], v[20:21] op_sel_hi:[0,1,1]
	v_pk_fma_f32 v[22:23], v[162:163], v[172:173], v[22:23] op_sel_hi:[0,1,1]
	v_pk_fma_f32 v[24:25], v[162:163], v[174:175], v[24:25] op_sel_hi:[0,1,1]
	v_pk_fma_f32 v[26:27], v[162:163], v[176:177], v[26:27] op_sel_hi:[0,1,1]
	v_pk_fma_f32 v[28:29], v[162:163], v[178:179], v[28:29] op_sel_hi:[0,1,1]
	v_pk_fma_f32 v[14:15], v[162:163], v[180:181], v[14:15] op_sel_hi:[0,1,1]
	s_waitcnt vmcnt(2)
	v_pk_fma_f32 v[16:17], v[162:163], v[182:183], v[16:17] op_sel:[1,0,0] op_sel_hi:[1,1,1]
	v_pk_fma_f32 v[18:19], v[162:163], v[184:185], v[18:19] op_sel:[1,0,0] op_sel_hi:[1,1,1]
	v_pk_fma_f32 v[20:21], v[162:163], v[186:187], v[20:21] op_sel:[1,0,0] op_sel_hi:[1,1,1]
	v_pk_fma_f32 v[22:23], v[162:163], v[188:189], v[22:23] op_sel:[1,0,0] op_sel_hi:[1,1,1]
	v_pk_fma_f32 v[24:25], v[162:163], v[190:191], v[24:25] op_sel:[1,0,0] op_sel_hi:[1,1,1]
	v_pk_fma_f32 v[26:27], v[162:163], v[192:193], v[26:27] op_sel:[1,0,0] op_sel_hi:[1,1,1]
	v_pk_fma_f32 v[28:29], v[162:163], v[194:195], v[28:29] op_sel:[1,0,0] op_sel_hi:[1,1,1]
	v_pk_fma_f32 v[14:15], v[162:163], v[196:197], v[14:15] op_sel:[1,0,0] op_sel_hi:[1,1,1]
	s_waitcnt vmcnt(1) lgkmcnt(0)
	v_pk_fma_f32 v[16:17], v[164:165], v[198:199], v[16:17] op_sel_hi:[0,1,1]
	v_pk_fma_f32 v[18:19], v[164:165], v[200:201], v[18:19] op_sel_hi:[0,1,1]
	v_pk_fma_f32 v[20:21], v[164:165], v[202:203], v[20:21] op_sel_hi:[0,1,1]
	v_pk_fma_f32 v[22:23], v[164:165], v[204:205], v[22:23] op_sel_hi:[0,1,1]
	v_pk_fma_f32 v[24:25], v[164:165], v[206:207], v[24:25] op_sel_hi:[0,1,1]
	v_pk_fma_f32 v[26:27], v[164:165], v[208:209], v[26:27] op_sel_hi:[0,1,1]
	v_pk_fma_f32 v[28:29], v[164:165], v[210:211], v[28:29] op_sel_hi:[0,1,1]
	v_pk_fma_f32 v[14:15], v[164:165], v[212:213], v[14:15] op_sel_hi:[0,1,1]
	s_waitcnt vmcnt(0)
	v_pk_fma_f32 v[16:17], v[164:165], v[214:215], v[16:17] op_sel:[1,0,0] op_sel_hi:[1,1,1]
	v_pk_fma_f32 v[18:19], v[164:165], v[216:217], v[18:19] op_sel:[1,0,0] op_sel_hi:[1,1,1]
	v_pk_fma_f32 v[20:21], v[164:165], v[218:219], v[20:21] op_sel:[1,0,0] op_sel_hi:[1,1,1]
	v_pk_fma_f32 v[22:23], v[164:165], v[220:221], v[22:23] op_sel:[1,0,0] op_sel_hi:[1,1,1]
	v_pk_fma_f32 v[24:25], v[164:165], v[222:223], v[24:25] op_sel:[1,0,0] op_sel_hi:[1,1,1]
	v_pk_fma_f32 v[26:27], v[164:165], v[224:225], v[26:27] op_sel:[1,0,0] op_sel_hi:[1,1,1]
	v_pk_fma_f32 v[28:29], v[164:165], v[226:227], v[28:29] op_sel:[1,0,0] op_sel_hi:[1,1,1]
	v_pk_fma_f32 v[14:15], v[164:165], v[228:229], v[14:15] op_sel:[1,0,0] op_sel_hi:[1,1,1]
	ds_write2st64_b32 v5, v16, v17 offset1:1
	ds_write2st64_b32 v5, v18, v19 offset0:2 offset1:3
	ds_write2st64_b32 v5, v20, v21 offset0:4 offset1:5
	ds_write2st64_b32 v5, v22, v23 offset0:6 offset1:7
	ds_write2st64_b32 v5, v24, v25 offset0:8 offset1:9
	ds_write2st64_b32 v5, v26, v27 offset0:10 offset1:11
	ds_write2st64_b32 v5, v28, v29 offset0:12 offset1:13
	ds_write2st64_b32 v5, v14, v15 offset0:14 offset1:15
	s_waitcnt lgkmcnt(0)
	s_barrier
	s_and_saveexec_b64 s[22:23], s[8:9]
	s_cbranch_execz .LBB0_8
	v_lshl_or_b32 v12, s58, 6, v39
	v_ashrrev_i32_e32 v13, 31, v12
	v_lshl_add_u64 v[14:15], v[12:13], 2, s[42:43]
	s_mov_b64 s[34:35], 0
	v_mov_b32_e32 v10, v4
